# in-projection GEMM: last two K-steps in the same pipelined fragment-ring form as the loop (replaces compiler tail)
# speedup vs baseline: 1.0087x; 1.0087x over previous
; template <bool AT>
; DI void gemm_main(f32x16 (&acc)[2][4], const u16* __restrict__ R, int ldr, const u16* __restrict__ Cm, int ldc,
;                   const u16* __restrict__ RT, int ldrt, int K, char* smem, int tid) {
;     ...
;     if (kt + 1 < nk) {
;       const int ks1 = kt + 1;
;       u16* Rs = S0 + (ks1 & 1) * STG;
;       u16* Cs = Rs + 256 * 72;
; #pragma unroll
;       for (int i = 0; i < 4; ++i) {
;         const int cid = tid + NT * i;
;         const int row = cid >> 3, kc = cid & 7;
;         if (AT && ks1 < 8) {
;           const int kr = cid >> 5, tc = cid & 31;
;           *(u32x4*)(Rs + kr * 264 + tc * 8) = rr[i];
;         } else {
;           *(u32x4*)(Rs + row * 72 + kc * 8) = rr[i];
;         }
;         *(u32x4*)(Cs + row * 72 + kc * 8) = cr[i];
;       }
;     }
;     if (kt + 2 < nk) {
;       const int kn = kt + 2;
; #pragma unroll
;       for (int i = 0; i < 4; ++i) {
;         const int cid = tid + NT * i;
;         const int row = cid >> 3, kc = cid & 7;
;         if (AT && kn < 8) {
;           const int kr = cid >> 5, tc = cid & 31;
;           rr[i] = *(const u32x4*)(RT + (size_t)(kn * 64 + kr) * ldrt + tc * 8);
;         } else {
;           rr[i] = *(const u32x4*)(R + (size_t)row * ldr + kn * 64 + kc * 8);
;         }
;         cr[i] = *(const u32x4*)(Cm + (size_t)row * ldc + kn * 64 + kc * 8);
;       }
;     }
;     __builtin_amdgcn_sched_barrier(0x38F);
;     if (kt >= 0) {
;       const u16* Rs = S0 + (kt & 1) * STG;
;       const u16* Cs = Rs + 256 * 72;
;       const u16* RTs = Rs;
; #pragma unroll
;       for (int ks = 0; ks < 4; ++ks) {
;         bf16x8 rf[2];
; #pragma unroll
;         for (int rb = 0; rb < 2; ++rb) {
;           if (AT && kt < 8) {
;             const u16* src = RTs + (16 * ks + 8 * g) * 264 + 64 * wr + 32 * rb + li;
;             bf16x8 t;
; #pragma unroll
;             for (int j = 0; j < 8; ++j) t[j] = (short)src[j * 264];
;             rf[rb] = t;
;           } else {
;             rf[rb] = *(const bf16x8*)(Rs + (64 * wr + 32 * rb + li) * 72 + 16 * ks + 8 * g);
;           }
;         }
; #pragma unroll
;         for (int cb = 0; cb < 4; ++cb) {
;           const bf16x8 cfv = *(const bf16x8*)(Cs + (128 * wc + 32 * cb + li) * 72 + 16 * ks + 8 * g);
; #pragma unroll
;           for (int rb = 0; rb < 2; ++rb) acc[rb][cb] = MFMA(rf[rb], cfv, acc[rb][cb]);
;         }
;       }
;     }
.Lgt_loop:
	ds_read_b128 v[192:195], v187 offset:0
	ds_read_b128 v[220:223], v187 offset:4608
	ds_read_b128 v[232:235], v190 offset:36864
	ds_read_b128 v[236:239], v190 offset:41472
	ds_read_b128 v[240:243], v190 offset:46080
	ds_read_b128 v[244:247], v190 offset:50688
	ds_read_b128 v[224:227], v187 offset:32
	ds_read_b128 v[228:231], v187 offset:4640
	s_waitcnt lgkmcnt(5)
	v_mfma_f32_32x32x16_bf16 v[112:127], v[192:195], v[232:235], v[112:127]
	v_mfma_f32_32x32x16_bf16 v[48:63], v[220:223], v[232:235], v[48:63]
	ds_read_b128 v[232:235], v190 offset:36896
	s_waitcnt vmcnt(0)
	ds_write_b128 v191, v[144:147]
	s_waitcnt lgkmcnt(6)
	v_mfma_f32_32x32x16_bf16 v[96:111], v[192:195], v[236:239], v[96:111]
	v_mfma_f32_32x32x16_bf16 v[32:47], v[220:223], v[236:239], v[32:47]
	ds_read_b128 v[236:239], v190 offset:41504
	ds_write_b128 v191, v[152:155] offset:36864
	s_waitcnt lgkmcnt(7)
	v_mfma_f32_32x32x16_bf16 v[80:95], v[192:195], v[240:243], v[80:95]
	v_mfma_f32_32x32x16_bf16 v[16:31], v[220:223], v[240:243], v[16:31]
	ds_read_b128 v[240:243], v190 offset:46112
	ds_write_b128 v196, v[136:139]
	s_waitcnt lgkmcnt(8)
	v_mfma_f32_32x32x16_bf16 v[64:79], v[192:195], v[244:247], v[64:79]
	v_mfma_f32_32x32x16_bf16 v[0:15], v[220:223], v[244:247], v[0:15]
	ds_read_b128 v[244:247], v190 offset:50720
	ds_write_b128 v196, v[148:151] offset:36864
	ds_read_b128 v[192:195], v187 offset:64
	ds_read_b128 v[220:223], v187 offset:4672
	s_waitcnt lgkmcnt(9)
	v_mfma_f32_32x32x16_bf16 v[112:127], v[224:227], v[232:235], v[112:127]
	v_mfma_f32_32x32x16_bf16 v[48:63], v[228:231], v[232:235], v[48:63]
	ds_read_b128 v[232:235], v190 offset:36928
	ds_write_b128 v197, v[132:135]
	s_waitcnt lgkmcnt(9)
	v_mfma_f32_32x32x16_bf16 v[96:111], v[224:227], v[236:239], v[96:111]
	v_mfma_f32_32x32x16_bf16 v[32:47], v[228:231], v[236:239], v[32:47]
	ds_read_b128 v[236:239], v190 offset:41536
	ds_write_b128 v197, v[140:143] offset:36864
	s_waitcnt lgkmcnt(9)
	v_mfma_f32_32x32x16_bf16 v[80:95], v[224:227], v[240:243], v[80:95]
	v_mfma_f32_32x32x16_bf16 v[16:31], v[228:231], v[240:243], v[16:31]
	ds_read_b128 v[240:243], v190 offset:46144
	ds_write_b128 v249, v[128:131]
	s_waitcnt lgkmcnt(9)
	v_mfma_f32_32x32x16_bf16 v[64:79], v[224:227], v[244:247], v[64:79]
	v_mfma_f32_32x32x16_bf16 v[0:15], v[228:231], v[244:247], v[0:15]
	ds_read_b128 v[244:247], v190 offset:50752
	ds_write_b128 v249, v[156:159] offset:36864
	ds_read_b128 v[224:227], v187 offset:96
	ds_read_b128 v[228:231], v187 offset:4704
	s_waitcnt lgkmcnt(9)
	v_mfma_f32_32x32x16_bf16 v[112:127], v[192:195], v[232:235], v[112:127]
	v_mfma_f32_32x32x16_bf16 v[48:63], v[220:223], v[232:235], v[48:63]
	ds_read_b128 v[232:235], v190 offset:36960
	v_subrev_u32_e32 v191, 0x12000, v191
	global_load_dwordx4 v[144:147], v[174:175], off
	v_lshl_add_u64 v[174:175], v[174:175], 0, s[58:59]
	s_waitcnt lgkmcnt(8)
	v_mfma_f32_32x32x16_bf16 v[96:111], v[192:195], v[236:239], v[96:111]
	v_mfma_f32_32x32x16_bf16 v[32:47], v[220:223], v[236:239], v[32:47]
	ds_read_b128 v[236:239], v190 offset:41568
	v_subrev_u32_e32 v196, 0x12000, v196
	global_load_dwordx4 v[152:155], v[166:167], off
	v_lshl_add_u64 v[166:167], v[166:167], 0, s[58:59]
	s_waitcnt lgkmcnt(7)
	v_mfma_f32_32x32x16_bf16 v[80:95], v[192:195], v[240:243], v[80:95]
	v_mfma_f32_32x32x16_bf16 v[16:31], v[220:223], v[240:243], v[16:31]
	ds_read_b128 v[240:243], v190 offset:46176
	v_subrev_u32_e32 v197, 0x12000, v197
	global_load_dwordx4 v[136:139], v[172:173], off
	v_lshl_add_u64 v[172:173], v[172:173], 0, s[58:59]
	s_waitcnt lgkmcnt(6)
	v_mfma_f32_32x32x16_bf16 v[64:79], v[192:195], v[244:247], v[64:79]
	v_mfma_f32_32x32x16_bf16 v[0:15], v[220:223], v[244:247], v[0:15]
	ds_read_b128 v[244:247], v190 offset:50784
	v_subrev_u32_e32 v249, 0x12000, v249
	global_load_dwordx4 v[148:151], v[164:165], off
	v_lshl_add_u64 v[164:165], v[164:165], 0, s[58:59]
	v_add_u32_e32 v187, 0x12000, v187
	v_add_u32_e32 v190, 0x12000, v190
	s_waitcnt lgkmcnt(3)
	v_mfma_f32_32x32x16_bf16 v[112:127], v[224:227], v[232:235], v[112:127]
	v_mfma_f32_32x32x16_bf16 v[48:63], v[228:231], v[232:235], v[48:63]
	global_load_dwordx4 v[132:135], v[170:171], off
	v_lshl_add_u64 v[170:171], v[170:171], 0, s[58:59]
	s_waitcnt lgkmcnt(2)
	v_mfma_f32_32x32x16_bf16 v[96:111], v[224:227], v[236:239], v[96:111]
	v_mfma_f32_32x32x16_bf16 v[32:47], v[228:231], v[236:239], v[32:47]
	global_load_dwordx4 v[140:143], v[162:163], off
	v_lshl_add_u64 v[162:163], v[162:163], 0, s[58:59]
	s_waitcnt lgkmcnt(1)
	v_mfma_f32_32x32x16_bf16 v[80:95], v[224:227], v[240:243], v[80:95]
	v_mfma_f32_32x32x16_bf16 v[16:31], v[228:231], v[240:243], v[16:31]
	global_load_dwordx4 v[128:131], v[168:169], off
	v_lshl_add_u64 v[168:169], v[168:169], 0, s[58:59]
	s_waitcnt lgkmcnt(0)
	v_mfma_f32_32x32x16_bf16 v[64:79], v[224:227], v[244:247], v[64:79]
	v_mfma_f32_32x32x16_bf16 v[0:15], v[228:231], v[244:247], v[0:15]
	global_load_dwordx4 v[156:159], v[160:161], off
	v_lshl_add_u64 v[160:161], v[160:161], 0, s[58:59]
	s_waitcnt lgkmcnt(0)
	s_barrier
; template <bool AT>
; DI void gemm_main(f32x16 (&acc)[2][4], const u16* __restrict__ R, int ldr, const u16* __restrict__ Cm, int ldc,
;                   const u16* __restrict__ RT, int ldrt, int K, char* smem, int tid) {
;     ...
;     if (kt + 1 < nk) {
;       const int ks1 = kt + 1;
;       u16* Rs = S0 + (ks1 & 1) * STG;
;       u16* Cs = Rs + 256 * 72;
; #pragma unroll
;       for (int i = 0; i < 4; ++i) {
;         const int cid = tid + NT * i;
;         const int row = cid >> 3, kc = cid & 7;
;         if (AT && ks1 < 8) {
;           const int kr = cid >> 5, tc = cid & 31;
;           *(u32x4*)(Rs + kr * 264 + tc * 8) = rr[i];
;         } else {
;           *(u32x4*)(Rs + row * 72 + kc * 8) = rr[i];
;         }
;         *(u32x4*)(Cs + row * 72 + kc * 8) = cr[i];
;       }
;     }
;     if (kt + 2 < nk) {
;       const int kn = kt + 2;
; #pragma unroll
;       for (int i = 0; i < 4; ++i) {
;         const int cid = tid + NT * i;
;         const int row = cid >> 3, kc = cid & 7;
;         if (AT && kn < 8) {
;           const int kr = cid >> 5, tc = cid & 31;
;           rr[i] = *(const u32x4*)(RT + (size_t)(kn * 64 + kr) * ldrt + tc * 8);
;         } else {
;           rr[i] = *(const u32x4*)(R + (size_t)row * ldr + kn * 64 + kc * 8);
;         }
;         cr[i] = *(const u32x4*)(Cm + (size_t)row * ldc + kn * 64 + kc * 8);
;       }
;     }
;     __builtin_amdgcn_sched_barrier(0x38F);
;     if (kt >= 0) {
;       const u16* Rs = S0 + (kt & 1) * STG;
;       const u16* Cs = Rs + 256 * 72;
;       const u16* RTs = Rs;
; #pragma unroll
;       for (int ks = 0; ks < 4; ++ks) {
;         bf16x8 rf[2];
; #pragma unroll
;         for (int rb = 0; rb < 2; ++rb) {
;           if (AT && kt < 8) {
;             const u16* src = RTs + (16 * ks + 8 * g) * 264 + 64 * wr + 32 * rb + li;
;             bf16x8 t;
; #pragma unroll
;             for (int j = 0; j < 8; ++j) t[j] = (short)src[j * 264];
;             rf[rb] = t;
;           } else {
;             rf[rb] = *(const bf16x8*)(Rs + (64 * wr + 32 * rb + li) * 72 + 16 * ks + 8 * g);
;           }
;         }
; #pragma unroll
;         for (int cb = 0; cb < 4; ++cb) {
;           const bf16x8 cfv = *(const bf16x8*)(Cs + (128 * wc + 32 * cb + li) * 72 + 16 * ks + 8 * g);
; #pragma unroll
;           for (int rb = 0; rb < 2; ++rb) acc[rb][cb] = MFMA(rf[rb], cfv, acc[rb][cb]);
;         }
;       }
;     }
	ds_read_b128 v[192:195], v187 offset:0
	ds_read_b128 v[220:223], v187 offset:4608
	ds_read_b128 v[232:235], v190 offset:36864
	ds_read_b128 v[236:239], v190 offset:41472
	ds_read_b128 v[240:243], v190 offset:46080
	ds_read_b128 v[244:247], v190 offset:50688
	ds_read_b128 v[224:227], v187 offset:32
	ds_read_b128 v[228:231], v187 offset:4640
	s_waitcnt lgkmcnt(5)
	v_mfma_f32_32x32x16_bf16 v[112:127], v[192:195], v[232:235], v[112:127]
	v_mfma_f32_32x32x16_bf16 v[48:63], v[220:223], v[232:235], v[48:63]
	ds_read_b128 v[232:235], v190 offset:36896
	s_waitcnt vmcnt(0)
	ds_write_b128 v191, v[144:147]
	s_waitcnt lgkmcnt(6)
	v_mfma_f32_32x32x16_bf16 v[96:111], v[192:195], v[236:239], v[96:111]
	v_mfma_f32_32x32x16_bf16 v[32:47], v[220:223], v[236:239], v[32:47]
	ds_read_b128 v[236:239], v190 offset:41504
	ds_write_b128 v191, v[152:155] offset:36864
	s_waitcnt lgkmcnt(7)
	v_mfma_f32_32x32x16_bf16 v[80:95], v[192:195], v[240:243], v[80:95]
	v_mfma_f32_32x32x16_bf16 v[16:31], v[220:223], v[240:243], v[16:31]
	ds_read_b128 v[240:243], v190 offset:46112
	ds_write_b128 v196, v[136:139]
	s_waitcnt lgkmcnt(8)
	v_mfma_f32_32x32x16_bf16 v[64:79], v[192:195], v[244:247], v[64:79]
	v_mfma_f32_32x32x16_bf16 v[0:15], v[220:223], v[244:247], v[0:15]
	ds_read_b128 v[244:247], v190 offset:50720
	ds_write_b128 v196, v[148:151] offset:36864
	ds_read_b128 v[192:195], v187 offset:64
	ds_read_b128 v[220:223], v187 offset:4672
	s_waitcnt lgkmcnt(9)
	v_mfma_f32_32x32x16_bf16 v[112:127], v[224:227], v[232:235], v[112:127]
	v_mfma_f32_32x32x16_bf16 v[48:63], v[228:231], v[232:235], v[48:63]
	ds_read_b128 v[232:235], v190 offset:36928
	ds_write_b128 v197, v[132:135]
	s_waitcnt lgkmcnt(9)
	v_mfma_f32_32x32x16_bf16 v[96:111], v[224:227], v[236:239], v[96:111]
	v_mfma_f32_32x32x16_bf16 v[32:47], v[228:231], v[236:239], v[32:47]
	ds_read_b128 v[236:239], v190 offset:41536
	ds_write_b128 v197, v[140:143] offset:36864
	s_waitcnt lgkmcnt(9)
	v_mfma_f32_32x32x16_bf16 v[80:95], v[224:227], v[240:243], v[80:95]
	v_mfma_f32_32x32x16_bf16 v[16:31], v[228:231], v[240:243], v[16:31]
	ds_read_b128 v[240:243], v190 offset:46144
	ds_write_b128 v249, v[128:131]
	s_waitcnt lgkmcnt(9)
	v_mfma_f32_32x32x16_bf16 v[64:79], v[224:227], v[244:247], v[64:79]
	v_mfma_f32_32x32x16_bf16 v[0:15], v[228:231], v[244:247], v[0:15]
	ds_read_b128 v[244:247], v190 offset:50752
	ds_write_b128 v249, v[156:159] offset:36864
	ds_read_b128 v[224:227], v187 offset:96
	ds_read_b128 v[228:231], v187 offset:4704
	s_waitcnt lgkmcnt(9)
	v_mfma_f32_32x32x16_bf16 v[112:127], v[192:195], v[232:235], v[112:127]
	v_mfma_f32_32x32x16_bf16 v[48:63], v[220:223], v[232:235], v[48:63]
	ds_read_b128 v[232:235], v190 offset:36960
	v_add_u32_e32 v191, 0x12000, v191
	global_load_dwordx4 v[144:147], v[174:175], off
	v_lshl_add_u64 v[174:175], v[174:175], 0, s[58:59]
	s_waitcnt lgkmcnt(8)
	v_mfma_f32_32x32x16_bf16 v[96:111], v[192:195], v[236:239], v[96:111]
	v_mfma_f32_32x32x16_bf16 v[32:47], v[220:223], v[236:239], v[32:47]
	ds_read_b128 v[236:239], v190 offset:41568
	v_add_u32_e32 v196, 0x12000, v196
	global_load_dwordx4 v[152:155], v[166:167], off
	v_lshl_add_u64 v[166:167], v[166:167], 0, s[58:59]
	s_waitcnt lgkmcnt(7)
	v_mfma_f32_32x32x16_bf16 v[80:95], v[192:195], v[240:243], v[80:95]
	v_mfma_f32_32x32x16_bf16 v[16:31], v[220:223], v[240:243], v[16:31]
	ds_read_b128 v[240:243], v190 offset:46176
	v_add_u32_e32 v197, 0x12000, v197
	global_load_dwordx4 v[136:139], v[172:173], off
	v_lshl_add_u64 v[172:173], v[172:173], 0, s[58:59]
	s_waitcnt lgkmcnt(6)
	v_mfma_f32_32x32x16_bf16 v[64:79], v[192:195], v[244:247], v[64:79]
	v_mfma_f32_32x32x16_bf16 v[0:15], v[220:223], v[244:247], v[0:15]
	ds_read_b128 v[244:247], v190 offset:50784
	v_add_u32_e32 v249, 0x12000, v249
	global_load_dwordx4 v[148:151], v[164:165], off
	v_lshl_add_u64 v[164:165], v[164:165], 0, s[58:59]
	v_subrev_u32_e32 v187, 0x12000, v187
	v_subrev_u32_e32 v190, 0x12000, v190
	s_waitcnt lgkmcnt(3)
	v_mfma_f32_32x32x16_bf16 v[112:127], v[224:227], v[232:235], v[112:127]
	v_mfma_f32_32x32x16_bf16 v[48:63], v[228:231], v[232:235], v[48:63]
	global_load_dwordx4 v[132:135], v[170:171], off
	v_lshl_add_u64 v[170:171], v[170:171], 0, s[58:59]
	s_waitcnt lgkmcnt(2)
	v_mfma_f32_32x32x16_bf16 v[96:111], v[224:227], v[236:239], v[96:111]
	v_mfma_f32_32x32x16_bf16 v[32:47], v[228:231], v[236:239], v[32:47]
	global_load_dwordx4 v[140:143], v[162:163], off
	v_lshl_add_u64 v[162:163], v[162:163], 0, s[58:59]
	s_waitcnt lgkmcnt(1)
	v_mfma_f32_32x32x16_bf16 v[80:95], v[224:227], v[240:243], v[80:95]
	v_mfma_f32_32x32x16_bf16 v[16:31], v[228:231], v[240:243], v[16:31]
	global_load_dwordx4 v[128:131], v[168:169], off
	v_lshl_add_u64 v[168:169], v[168:169], 0, s[58:59]
	s_waitcnt lgkmcnt(0)
	v_mfma_f32_32x32x16_bf16 v[64:79], v[224:227], v[244:247], v[64:79]
	v_mfma_f32_32x32x16_bf16 v[0:15], v[228:231], v[244:247], v[0:15]
	global_load_dwordx4 v[156:159], v[160:161], off
	v_lshl_add_u64 v[160:161], v[160:161], 0, s[58:59]
	s_waitcnt lgkmcnt(0)
	s_barrier
	s_add_i32 s78, s78, -1
	s_cmp_lg_u32 s78, 0
	s_cbranch_scc1 .Lgt_loop
; template <bool AT>
; DI void gemm_main(f32x16 (&acc)[2][4], const u16* __restrict__ R, int ldr, const u16* __restrict__ Cm, int ldc,
;                   const u16* __restrict__ RT, int ldrt, int K, char* smem, int tid) {
;     ...
;       u16* Rs = S0 + (ks1 & 1) * STG;
;       u16* Cs = Rs + 256 * 72;
; #pragma unroll
;       for (int i = 0; i < 4; ++i) {
;         const int cid = tid + NT * i;
;         const int row = cid >> 3, kc = cid & 7;
;         if (AT && ks1 < 8) {
;           const int kr = cid >> 5, tc = cid & 31;
;           *(u32x4*)(Rs + kr * 264 + tc * 8) = rr[i];
;         } else {
;           *(u32x4*)(Rs + row * 72 + kc * 8) = rr[i];
;         }
;         *(u32x4*)(Cs + row * 72 + kc * 8) = cr[i];
;       }
;     }
;     if (kt + 2 < nk) {
;       const int kn = kt + 2;
; #pragma unroll
;       for (int i = 0; i < 4; ++i) {
;         const int cid = tid + NT * i;
;         const int row = cid >> 3, kc = cid & 7;
;         if (AT && kn < 8) {
;           const int kr = cid >> 5, tc = cid & 31;
;           rr[i] = *(const u32x4*)(RT + (size_t)(kn * 64 + kr) * ldrt + tc * 8);
;         } else {
;           rr[i] = *(const u32x4*)(R + (size_t)row * ldr + kn * 64 + kc * 8);
;         }
;         cr[i] = *(const u32x4*)(Cm + (size_t)row * ldc + kn * 64 + kc * 8);
;       }
;     }
;     __builtin_amdgcn_sched_barrier(0x38F);
;     if (kt >= 0) {
;       const u16* Rs = S0 + (kt & 1) * STG;
;       const u16* Cs = Rs + 256 * 72;
;       const u16* RTs = Rs;
; #pragma unroll
;       for (int ks = 0; ks < 4; ++ks) {
;         bf16x8 rf[2];
; #pragma unroll
;         for (int rb = 0; rb < 2; ++rb) {
;           if (AT && kt < 8) {
;             const u16* src = RTs + (16 * ks + 8 * g) * 264 + 64 * wr + 32 * rb + li;
;             bf16x8 t;
; #pragma unroll
;             for (int j = 0; j < 8; ++j) t[j] = (short)src[j * 264];
;             rf[rb] = t;
;           } else {
;             rf[rb] = *(const bf16x8*)(Rs + (64 * wr + 32 * rb + li) * 72 + 16 * ks + 8 * g);
;           }
;         }
; #pragma unroll
;         for (int cb = 0; cb < 4; ++cb) {
;           const bf16x8 cfv = *(const bf16x8*)(Cs + (128 * wc + 32 * cb + li) * 72 + 16 * ks + 8 * g);
; #pragma unroll
;           for (int rb = 0; rb < 2; ++rb) acc[rb][cb] = MFMA(rf[rb], cfv, acc[rb][cb]);
;         }
;       }
;     }
;     __syncthreads();
	ds_read_b128 v[192:195], v187 offset:0
	ds_read_b128 v[220:223], v187 offset:4608
	ds_read_b128 v[232:235], v190 offset:36864
	ds_read_b128 v[236:239], v190 offset:41472
	ds_read_b128 v[240:243], v190 offset:46080
	ds_read_b128 v[244:247], v190 offset:50688
	ds_read_b128 v[224:227], v187 offset:32
	ds_read_b128 v[228:231], v187 offset:4640
	s_waitcnt lgkmcnt(5)
	v_mfma_f32_32x32x16_bf16 v[112:127], v[192:195], v[232:235], v[112:127]
	v_mfma_f32_32x32x16_bf16 v[48:63], v[220:223], v[232:235], v[48:63]
	ds_read_b128 v[232:235], v190 offset:36896
	s_waitcnt vmcnt(0)
	ds_write_b128 v191, v[144:147]
	s_waitcnt lgkmcnt(6)
	v_mfma_f32_32x32x16_bf16 v[96:111], v[192:195], v[236:239], v[96:111]
	v_mfma_f32_32x32x16_bf16 v[32:47], v[220:223], v[236:239], v[32:47]
	ds_read_b128 v[236:239], v190 offset:41504
	ds_write_b128 v191, v[152:155] offset:36864
	s_waitcnt lgkmcnt(7)
	v_mfma_f32_32x32x16_bf16 v[80:95], v[192:195], v[240:243], v[80:95]
	v_mfma_f32_32x32x16_bf16 v[16:31], v[220:223], v[240:243], v[16:31]
	ds_read_b128 v[240:243], v190 offset:46112
	ds_write_b128 v196, v[136:139]
	s_waitcnt lgkmcnt(8)
	v_mfma_f32_32x32x16_bf16 v[64:79], v[192:195], v[244:247], v[64:79]
	v_mfma_f32_32x32x16_bf16 v[0:15], v[220:223], v[244:247], v[0:15]
	ds_read_b128 v[244:247], v190 offset:50720
	ds_write_b128 v196, v[148:151] offset:36864
	ds_read_b128 v[192:195], v187 offset:64
	ds_read_b128 v[220:223], v187 offset:4672
	s_waitcnt lgkmcnt(9)
	v_mfma_f32_32x32x16_bf16 v[112:127], v[224:227], v[232:235], v[112:127]
	v_mfma_f32_32x32x16_bf16 v[48:63], v[228:231], v[232:235], v[48:63]
	ds_read_b128 v[232:235], v190 offset:36928
	ds_write_b128 v197, v[132:135]
	s_waitcnt lgkmcnt(9)
	v_mfma_f32_32x32x16_bf16 v[96:111], v[224:227], v[236:239], v[96:111]
	v_mfma_f32_32x32x16_bf16 v[32:47], v[228:231], v[236:239], v[32:47]
	ds_read_b128 v[236:239], v190 offset:41536
	ds_write_b128 v197, v[140:143] offset:36864
	s_waitcnt lgkmcnt(9)
	v_mfma_f32_32x32x16_bf16 v[80:95], v[224:227], v[240:243], v[80:95]
	v_mfma_f32_32x32x16_bf16 v[16:31], v[228:231], v[240:243], v[16:31]
	ds_read_b128 v[240:243], v190 offset:46144
	ds_write_b128 v249, v[128:131]
	s_waitcnt lgkmcnt(9)
	v_mfma_f32_32x32x16_bf16 v[64:79], v[224:227], v[244:247], v[64:79]
	v_mfma_f32_32x32x16_bf16 v[0:15], v[228:231], v[244:247], v[0:15]
	ds_read_b128 v[244:247], v190 offset:50752
	ds_write_b128 v249, v[156:159] offset:36864
	ds_read_b128 v[224:227], v187 offset:96
	ds_read_b128 v[228:231], v187 offset:4704
	s_waitcnt lgkmcnt(9)
	v_mfma_f32_32x32x16_bf16 v[112:127], v[192:195], v[232:235], v[112:127]
	v_mfma_f32_32x32x16_bf16 v[48:63], v[220:223], v[232:235], v[48:63]
	ds_read_b128 v[232:235], v190 offset:36960
	v_subrev_u32_e32 v191, 0x12000, v191
	s_waitcnt lgkmcnt(8)
	v_mfma_f32_32x32x16_bf16 v[96:111], v[192:195], v[236:239], v[96:111]
	v_mfma_f32_32x32x16_bf16 v[32:47], v[220:223], v[236:239], v[32:47]
	ds_read_b128 v[236:239], v190 offset:41568
	v_subrev_u32_e32 v196, 0x12000, v196
	s_waitcnt lgkmcnt(7)
	v_mfma_f32_32x32x16_bf16 v[80:95], v[192:195], v[240:243], v[80:95]
	v_mfma_f32_32x32x16_bf16 v[16:31], v[220:223], v[240:243], v[16:31]
	ds_read_b128 v[240:243], v190 offset:46176
	v_subrev_u32_e32 v197, 0x12000, v197
	s_waitcnt lgkmcnt(6)
	v_mfma_f32_32x32x16_bf16 v[64:79], v[192:195], v[244:247], v[64:79]
	v_mfma_f32_32x32x16_bf16 v[0:15], v[220:223], v[244:247], v[0:15]
	ds_read_b128 v[244:247], v190 offset:50784
	v_subrev_u32_e32 v249, 0x12000, v249
	v_add_u32_e32 v187, 0x12000, v187
	v_add_u32_e32 v190, 0x12000, v190
	s_waitcnt lgkmcnt(3)
	v_mfma_f32_32x32x16_bf16 v[112:127], v[224:227], v[232:235], v[112:127]
	v_mfma_f32_32x32x16_bf16 v[48:63], v[228:231], v[232:235], v[48:63]
	s_waitcnt lgkmcnt(2)
	v_mfma_f32_32x32x16_bf16 v[96:111], v[224:227], v[236:239], v[96:111]
	v_mfma_f32_32x32x16_bf16 v[32:47], v[228:231], v[236:239], v[32:47]
	s_waitcnt lgkmcnt(1)
	v_mfma_f32_32x32x16_bf16 v[80:95], v[224:227], v[240:243], v[80:95]
	v_mfma_f32_32x32x16_bf16 v[16:31], v[228:231], v[240:243], v[16:31]
	s_waitcnt lgkmcnt(0)
	v_mfma_f32_32x32x16_bf16 v[64:79], v[224:227], v[244:247], v[64:79]
	v_mfma_f32_32x32x16_bf16 v[0:15], v[228:231], v[244:247], v[0:15]
	s_waitcnt lgkmcnt(0)
	s_barrier
	ds_read_b128 v[192:195], v187 offset:0
	ds_read_b128 v[220:223], v187 offset:4608
	ds_read_b128 v[232:235], v190 offset:36864
	ds_read_b128 v[236:239], v190 offset:41472
	ds_read_b128 v[240:243], v190 offset:46080
	ds_read_b128 v[244:247], v190 offset:50688
	ds_read_b128 v[224:227], v187 offset:32
	ds_read_b128 v[228:231], v187 offset:4640
	s_waitcnt lgkmcnt(5)
	v_mfma_f32_32x32x16_bf16 v[112:127], v[192:195], v[232:235], v[112:127]
	v_mfma_f32_32x32x16_bf16 v[48:63], v[220:223], v[232:235], v[48:63]
	ds_read_b128 v[232:235], v190 offset:36896
	s_waitcnt lgkmcnt(5)
	v_mfma_f32_32x32x16_bf16 v[96:111], v[192:195], v[236:239], v[96:111]
	v_mfma_f32_32x32x16_bf16 v[32:47], v[220:223], v[236:239], v[32:47]
	ds_read_b128 v[236:239], v190 offset:41504
	s_waitcnt lgkmcnt(5)
	v_mfma_f32_32x32x16_bf16 v[80:95], v[192:195], v[240:243], v[80:95]
	v_mfma_f32_32x32x16_bf16 v[16:31], v[220:223], v[240:243], v[16:31]
	ds_read_b128 v[240:243], v190 offset:46112
	s_waitcnt lgkmcnt(5)
	v_mfma_f32_32x32x16_bf16 v[64:79], v[192:195], v[244:247], v[64:79]
	v_mfma_f32_32x32x16_bf16 v[0:15], v[220:223], v[244:247], v[0:15]
	ds_read_b128 v[244:247], v190 offset:50720
	ds_read_b128 v[192:195], v187 offset:64
	ds_read_b128 v[220:223], v187 offset:4672
	s_waitcnt lgkmcnt(5)
	v_mfma_f32_32x32x16_bf16 v[112:127], v[224:227], v[232:235], v[112:127]
	v_mfma_f32_32x32x16_bf16 v[48:63], v[228:231], v[232:235], v[48:63]
	ds_read_b128 v[232:235], v190 offset:36928
	s_waitcnt lgkmcnt(5)
; #define MFMA(a, b, c) __builtin_amdgcn_mfma_f32_32x32x16_bf16((a), (b), (c), 0, 0, 0)
; DI u16 f2bf(float a) { return (u16)(pack2(a, 0.f) & 0xffffu); }
; DI int crow(int reg, int g) { return (reg & 3) + 8 * (reg >> 2) + 4 * g; }
; DI float siluf(float x) { return x * __builtin_amdgcn_rcpf(1.f + __expf(-x)); }
; template <bool AT>
; DI void gemm_main(f32x16 (&acc)[2][4], const u16* __restrict__ R, int ldr, const u16* __restrict__ Cm, int ldc,
;                   const u16* __restrict__ RT, int ldrt, int K, char* smem, int tid) {
;     ...
;       for (int ks = 0; ks < 4; ++ks) {
;         bf16x8 rf[2];
; #pragma unroll
;         for (int rb = 0; rb < 2; ++rb) {
;           if (AT && kt < 8) {
;             const u16* src = RTs + (16 * ks + 8 * g) * 264 + 64 * wr + 32 * rb + li;
;             bf16x8 t;
; #pragma unroll
;             for (int j = 0; j < 8; ++j) t[j] = (short)src[j * 264];
;             rf[rb] = t;
;           } else {
;             rf[rb] = *(const bf16x8*)(Rs + (64 * wr + 32 * rb + li) * 72 + 16 * ks + 8 * g);
;           }
;         }
; #pragma unroll
;         for (int cb = 0; cb < 4; ++cb) {
;           const bf16x8 cfv = *(const bf16x8*)(Cs + (128 * wc + 32 * cb + li) * 72 + 16 * ks + 8 * g);
; #pragma unroll
;           for (int rb = 0; rb < 2; ++rb) acc[rb][cb] = MFMA(rf[rb], cfv, acc[rb][cb]);
;         }
;       }
;     }
;     __syncthreads();
; template <bool TR>
; DI void gemm_in_tile(const P& p, int l, int id, char* smem) {
;     ...
;   } else {
; #pragma unroll
;     for (int rb = 0; rb < 2; ++rb) {
; #pragma unroll
;       for (int reg = 0; reg < 16; ++reg) {
;         if ((reg & 7) == 0) asm volatile("" ::: "memory");
;         const int rl = 64 * wr + 32 * rb + crow(reg, g);
;         const int tok = m0 + rl;
;         const float rs = rs_s[rl];
; #pragma unroll
;         for (int cb = 0; cb < 4; ++cb) {
;           const int col = n0 - 3584 + 128 * wc + 32 * cb + li;
;           p.AG[(size_t)tok * 512 + col] = f2bf(siluf(acc[rb][cb][reg] * rs));
;         }
	v_mfma_f32_32x32x16_bf16 v[96:111], v[224:227], v[236:239], v[96:111]
	v_mfma_f32_32x32x16_bf16 v[32:47], v[228:231], v[236:239], v[32:47]
	ds_read_b128 v[236:239], v190 offset:41536
	s_waitcnt lgkmcnt(5)
	v_mfma_f32_32x32x16_bf16 v[80:95], v[224:227], v[240:243], v[80:95]
	v_mfma_f32_32x32x16_bf16 v[16:31], v[228:231], v[240:243], v[16:31]
	ds_read_b128 v[240:243], v190 offset:46144
	s_waitcnt lgkmcnt(5)
	v_mfma_f32_32x32x16_bf16 v[64:79], v[224:227], v[244:247], v[64:79]
	v_mfma_f32_32x32x16_bf16 v[0:15], v[228:231], v[244:247], v[0:15]
	ds_read_b128 v[244:247], v190 offset:50752
	ds_read_b128 v[224:227], v187 offset:96
	ds_read_b128 v[228:231], v187 offset:4704
	s_waitcnt lgkmcnt(5)
	v_mfma_f32_32x32x16_bf16 v[112:127], v[192:195], v[232:235], v[112:127]
	v_mfma_f32_32x32x16_bf16 v[48:63], v[220:223], v[232:235], v[48:63]
	ds_read_b128 v[232:235], v190 offset:36960
	v_add_u32_e32 v191, 0x12000, v191
	s_waitcnt lgkmcnt(5)
	v_mfma_f32_32x32x16_bf16 v[96:111], v[192:195], v[236:239], v[96:111]
	v_mfma_f32_32x32x16_bf16 v[32:47], v[220:223], v[236:239], v[32:47]
	ds_read_b128 v[236:239], v190 offset:41568
	v_add_u32_e32 v196, 0x12000, v196
	s_waitcnt lgkmcnt(5)
	v_mfma_f32_32x32x16_bf16 v[80:95], v[192:195], v[240:243], v[80:95]
	v_mfma_f32_32x32x16_bf16 v[16:31], v[220:223], v[240:243], v[16:31]
	ds_read_b128 v[240:243], v190 offset:46176
	v_add_u32_e32 v197, 0x12000, v197
	s_waitcnt lgkmcnt(5)
	v_mfma_f32_32x32x16_bf16 v[64:79], v[192:195], v[244:247], v[64:79]
	v_mfma_f32_32x32x16_bf16 v[0:15], v[220:223], v[244:247], v[0:15]
	ds_read_b128 v[244:247], v190 offset:50784
	v_add_u32_e32 v249, 0x12000, v249
	v_subrev_u32_e32 v187, 0x12000, v187
	v_subrev_u32_e32 v190, 0x12000, v190
	s_waitcnt lgkmcnt(3)
	v_mfma_f32_32x32x16_bf16 v[112:127], v[224:227], v[232:235], v[112:127]
	v_mfma_f32_32x32x16_bf16 v[48:63], v[228:231], v[232:235], v[48:63]
	s_waitcnt lgkmcnt(2)
	v_mfma_f32_32x32x16_bf16 v[96:111], v[224:227], v[236:239], v[96:111]
	v_mfma_f32_32x32x16_bf16 v[32:47], v[228:231], v[236:239], v[32:47]
	s_waitcnt lgkmcnt(1)
	v_mfma_f32_32x32x16_bf16 v[80:95], v[224:227], v[240:243], v[80:95]
	v_mfma_f32_32x32x16_bf16 v[16:31], v[228:231], v[240:243], v[16:31]
	s_waitcnt lgkmcnt(0)
	v_mfma_f32_32x32x16_bf16 v[64:79], v[224:227], v[244:247], v[64:79]
	v_mfma_f32_32x32x16_bf16 v[0:15], v[228:231], v[244:247], v[0:15]
	s_waitcnt lgkmcnt(0)
	s_barrier
	s_nop 7
	v_bfe_u32 v145, v176, 6, 1
	s_mov_b64 s[8:9], -1
	v_ashrrev_i32_e32 v140, 7, v176
	v_bfe_u32 v141, v176, 5, 1
	v_lshlrev_b32_e32 v128, 6, v140
	v_lshl_or_b32 v144, v141, 2, v128
	s_cmp_lt_u32 s11, 12
	s_cbranch_scc1 .LBB0_332
	s_add_i32 s8, s56, 0xfffff200
	v_lshlrev_b32_e32 v128, 7, v145
	v_or3_b32 v132, v128, s8, v177
	s_add_i32 s8, 0, 0x24000
	v_lshl_add_u32 v128, v144, 2, s8
	ds_read_b128 v[128:131], v128
	v_add_u32_e32 v140, s76, v144
	v_ashrrev_i32_e32 v141, 31, v140
	v_lshlrev_b64 v[134:135], 10, v[140:141]
	v_lshl_add_u64 v[142:143], s[30:31], 0, v[134:135]
	s_waitcnt lgkmcnt(0)
	v_mul_f32_e32 v133, v112, v128
	v_mul_f32_e32 v134, 0xbfb8aa3b, v133
	v_exp_f32_e32 v134, v134
	s_nop 0
	v_add_f32_e32 v134, 1.0, v134
	v_rcp_f32_e32 v134, v134
	s_nop 0
	v_mul_f32_e32 v133, v133, v134
	v_cvt_pk_bf16_f32 v136, v133, s0
	v_ashrrev_i32_e32 v133, 31, v132
	v_lshlrev_b64 v[138:139], 1, v[132:133]
	v_lshl_add_u64 v[134:135], v[142:143], 0, v[138:139]
	v_mul_f32_e32 v133, v96, v128
	global_store_short v[134:135], v136, off
	v_mul_f32_e32 v135, 0xbfb8aa3b, v133
	v_exp_f32_e32 v135, v135
	v_or_b32_e32 v134, 32, v132
	v_add_f32_e32 v135, 1.0, v135
	v_rcp_f32_e32 v135, v135
	s_nop 0
	v_mul_f32_e32 v133, v133, v135
	v_ashrrev_i32_e32 v135, 31, v134
	v_lshlrev_b64 v[136:137], 1, v[134:135]
	v_cvt_pk_bf16_f32 v133, v133, s0
	v_lshl_add_u64 v[134:135], v[142:143], 0, v[136:137]
	global_store_short v[134:135], v133, off
	v_mul_f32_e32 v133, v80, v128
	v_mul_f32_e32 v135, 0xbfb8aa3b, v133
	v_exp_f32_e32 v135, v135
	v_or_b32_e32 v134, 64, v132
	v_mul_f32_e32 v128, v64, v128
	v_or_b32_e32 v132, 0x60, v132
	v_add_f32_e32 v135, 1.0, v135
	v_rcp_f32_e32 v135, v135
	s_nop 0
	v_mul_f32_e32 v133, v133, v135
	v_ashrrev_i32_e32 v135, 31, v134
	v_lshlrev_b64 v[134:135], 1, v[134:135]
	v_cvt_pk_bf16_f32 v133, v133, s0
	v_lshl_add_u64 v[146:147], v[142:143], 0, v[134:135]
	global_store_short v[146:147], v133, off
	v_mul_f32_e32 v133, 0xbfb8aa3b, v128
	v_exp_f32_e32 v133, v133
	s_nop 0
	v_add_f32_e32 v133, 1.0, v133
	v_rcp_f32_e32 v133, v133
	s_nop 0
	v_mul_f32_e32 v128, v128, v133
	v_ashrrev_i32_e32 v133, 31, v132
	v_lshlrev_b64 v[132:133], 1, v[132:133]
	v_cvt_pk_bf16_f32 v128, v128, s0
	v_lshl_add_u64 v[142:143], v[142:143], 0, v[132:133]
	global_store_short v[142:143], v128, off
	v_mul_f32_e32 v128, v113, v129
	v_mul_f32_e32 v141, 0xbfb8aa3b, v128
	v_exp_f32_e32 v141, v141
	v_add_u32_e32 v142, 1, v140
	v_ashrrev_i32_e32 v143, 31, v142
	v_lshlrev_b64 v[142:143], 10, v[142:143]
	v_add_f32_e32 v141, 1.0, v141
	v_rcp_f32_e32 v141, v141
	v_lshl_add_u64 v[142:143], s[30:31], 0, v[142:143]
	v_lshl_add_u64 v[146:147], v[142:143], 0, v[138:139]
	v_mul_f32_e32 v128, v128, v141
	v_cvt_pk_bf16_f32 v128, v128, s0
	global_store_short v[146:147], v128, off
	v_mul_f32_e32 v128, v97, v129
	v_mul_f32_e32 v141, 0xbfb8aa3b, v128
	v_exp_f32_e32 v141, v141
	v_lshl_add_u64 v[146:147], v[142:143], 0, v[136:137]
	v_add_f32_e32 v141, 1.0, v141
	v_rcp_f32_e32 v141, v141
	s_nop 0
	v_mul_f32_e32 v128, v128, v141
	v_cvt_pk_bf16_f32 v128, v128, s0
	global_store_short v[146:147], v128, off
	v_mul_f32_e32 v128, v81, v129
	v_mul_f32_e32 v141, 0xbfb8aa3b, v128
	v_exp_f32_e32 v141, v141
	v_lshl_add_u64 v[146:147], v[142:143], 0, v[134:135]
; DI u16 f2bf(float a) { return (u16)(pack2(a, 0.f) & 0xffffu); }
; DI int crow(int reg, int g) { return (reg & 3) + 8 * (reg >> 2) + 4 * g; }
; DI float siluf(float x) { return x * __builtin_amdgcn_rcpf(1.f + __expf(-x)); }
; template <bool TR>
; DI void gemm_in_tile(const P& p, int l, int id, char* smem) {
;     ...
; #pragma unroll
;     for (int rb = 0; rb < 2; ++rb) {
; #pragma unroll
;       for (int reg = 0; reg < 16; ++reg) {
;         if ((reg & 7) == 0) asm volatile("" ::: "memory");
;         const int rl = 64 * wr + 32 * rb + crow(reg, g);
;         const int tok = m0 + rl;
;         const float rs = rs_s[rl];
; #pragma unroll
;         for (int cb = 0; cb < 4; ++cb) {
;           const int col = n0 - 3584 + 128 * wc + 32 * cb + li;
;           p.AG[(size_t)tok * 512 + col] = f2bf(siluf(acc[rb][cb][reg] * rs));
;         }
;       }
	v_add_f32_e32 v141, 1.0, v141
	v_rcp_f32_e32 v141, v141
	s_nop 0
	v_mul_f32_e32 v128, v128, v141
	v_cvt_pk_bf16_f32 v128, v128, s0
	global_store_short v[146:147], v128, off
	v_mul_f32_e32 v128, v65, v129
	v_mul_f32_e32 v129, 0xbfb8aa3b, v128
	v_exp_f32_e32 v129, v129
	s_nop 0
	v_add_f32_e32 v129, 1.0, v129
	v_rcp_f32_e32 v129, v129
	s_nop 0
	v_mul_f32_e32 v128, v128, v129
	v_cvt_pk_bf16_f32 v141, v128, s0
	v_lshl_add_u64 v[128:129], v[142:143], 0, v[132:133]
	global_store_short v[128:129], v141, off
	v_mul_f32_e32 v141, v114, v130
	v_mul_f32_e32 v142, 0xbfb8aa3b, v141
	v_exp_f32_e32 v142, v142
	v_add_u32_e32 v128, 2, v140
	v_ashrrev_i32_e32 v129, 31, v128
	v_lshlrev_b64 v[128:129], 10, v[128:129]
	v_add_f32_e32 v142, 1.0, v142
	v_rcp_f32_e32 v142, v142
	v_lshl_add_u64 v[128:129], s[30:31], 0, v[128:129]
	v_mul_f32_e32 v141, v141, v142
	v_cvt_pk_bf16_f32 v141, v141, s0
	v_lshl_add_u64 v[142:143], v[128:129], 0, v[138:139]
	global_store_short v[142:143], v141, off
	v_mul_f32_e32 v141, v98, v130
	v_mul_f32_e32 v142, 0xbfb8aa3b, v141
	v_exp_f32_e32 v142, v142
	s_nop 0
	v_add_f32_e32 v142, 1.0, v142
	v_rcp_f32_e32 v142, v142
	s_nop 0
	v_mul_f32_e32 v141, v141, v142
	v_cvt_pk_bf16_f32 v141, v141, s0
	v_lshl_add_u64 v[142:143], v[128:129], 0, v[136:137]
	global_store_short v[142:143], v141, off
	v_mul_f32_e32 v141, v82, v130
	v_mul_f32_e32 v142, 0xbfb8aa3b, v141
	v_exp_f32_e32 v142, v142
	v_mul_f32_e32 v130, v66, v130
	v_add_f32_e32 v142, 1.0, v142
	v_rcp_f32_e32 v142, v142
	s_nop 0
	v_mul_f32_e32 v141, v141, v142
	v_cvt_pk_bf16_f32 v141, v141, s0
	v_lshl_add_u64 v[142:143], v[128:129], 0, v[134:135]
	global_store_short v[142:143], v141, off
	v_mul_f32_e32 v141, 0xbfb8aa3b, v130
	v_exp_f32_e32 v141, v141
	v_lshl_add_u64 v[128:129], v[128:129], 0, v[132:133]
	v_add_f32_e32 v141, 1.0, v141
	v_rcp_f32_e32 v141, v141
	s_nop 0
	v_mul_f32_e32 v130, v130, v141
	v_cvt_pk_bf16_f32 v130, v130, s0
	global_store_short v[128:129], v130, off
	v_mul_f32_e32 v130, v115, v131
	v_mul_f32_e32 v141, 0xbfb8aa3b, v130
	v_exp_f32_e32 v141, v141
	v_add_u32_e32 v128, 3, v140
	v_ashrrev_i32_e32 v129, 31, v128
	v_lshlrev_b64 v[128:129], 10, v[128:129]
	v_add_f32_e32 v141, 1.0, v141
	v_rcp_f32_e32 v141, v141
	v_lshl_add_u64 v[128:129], s[30:31], 0, v[128:129]
	v_lshl_add_u64 v[142:143], v[128:129], 0, v[138:139]
	v_mul_f32_e32 v130, v130, v141
	v_cvt_pk_bf16_f32 v130, v130, s0
	global_store_short v[142:143], v130, off
	v_mul_f32_e32 v130, v99, v131
	v_mul_f32_e32 v141, 0xbfb8aa3b, v130
	v_exp_f32_e32 v141, v141
	v_lshl_add_u64 v[142:143], v[128:129], 0, v[136:137]
	v_add_f32_e32 v141, 1.0, v141
	v_rcp_f32_e32 v141, v141
	s_nop 0
	v_mul_f32_e32 v130, v130, v141
	v_cvt_pk_bf16_f32 v130, v130, s0
	global_store_short v[142:143], v130, off
	v_mul_f32_e32 v130, v83, v131
	v_mul_f32_e32 v141, 0xbfb8aa3b, v130
	v_exp_f32_e32 v141, v141
	v_lshl_add_u64 v[142:143], v[128:129], 0, v[134:135]
	v_lshl_add_u64 v[128:129], v[128:129], 0, v[132:133]
	v_add_f32_e32 v141, 1.0, v141
	v_rcp_f32_e32 v141, v141
	s_nop 0
	v_mul_f32_e32 v130, v130, v141
	v_cvt_pk_bf16_f32 v130, v130, s0
	global_store_short v[142:143], v130, off
	v_mul_f32_e32 v130, v67, v131
	v_mul_f32_e32 v131, 0xbfb8aa3b, v130
	v_exp_f32_e32 v131, v131
	s_nop 0
	v_add_f32_e32 v131, 1.0, v131
	v_rcp_f32_e32 v131, v131
	s_nop 0
	v_mul_f32_e32 v130, v130, v131
	v_cvt_pk_bf16_f32 v130, v130, s0
	global_store_short v[128:129], v130, off
	v_or_b32_e32 v128, 8, v144
	v_add_u32_e32 v142, s76, v128
	v_lshl_add_u32 v128, v128, 2, s8
	ds_read_b128 v[128:131], v128
	v_ashrrev_i32_e32 v143, 31, v142
	v_lshlrev_b64 v[142:143], 10, v[142:143]
	v_lshl_add_u64 v[142:143], s[30:31], 0, v[142:143]
	s_waitcnt lgkmcnt(0)
	v_mul_f32_e32 v141, v116, v128
	v_mul_f32_e32 v146, 0xbfb8aa3b, v141
	v_exp_f32_e32 v146, v146
	s_nop 0
	v_add_f32_e32 v146, 1.0, v146
	v_rcp_f32_e32 v146, v146
	s_nop 0
	v_mul_f32_e32 v141, v141, v146
	v_cvt_pk_bf16_f32 v141, v141, s0
	v_lshl_add_u64 v[146:147], v[142:143], 0, v[138:139]
	global_store_short v[146:147], v141, off
	v_mul_f32_e32 v141, v100, v128
	v_mul_f32_e32 v146, 0xbfb8aa3b, v141
	v_exp_f32_e32 v146, v146
	s_nop 0
	v_add_f32_e32 v146, 1.0, v146
	v_rcp_f32_e32 v146, v146
	s_nop 0
	v_mul_f32_e32 v141, v141, v146
	v_cvt_pk_bf16_f32 v141, v141, s0
	v_lshl_add_u64 v[146:147], v[142:143], 0, v[136:137]
	global_store_short v[146:147], v141, off
	v_mul_f32_e32 v141, v84, v128
	v_mul_f32_e32 v146, 0xbfb8aa3b, v141
	v_exp_f32_e32 v146, v146
	v_mul_f32_e32 v128, v68, v128
	v_add_f32_e32 v146, 1.0, v146
	v_rcp_f32_e32 v146, v146
	s_nop 0
	v_mul_f32_e32 v141, v141, v146
	v_cvt_pk_bf16_f32 v141, v141, s0
	v_lshl_add_u64 v[146:147], v[142:143], 0, v[134:135]
	global_store_short v[146:147], v141, off
	v_mul_f32_e32 v141, 0xbfb8aa3b, v128
	v_exp_f32_e32 v141, v141
	v_lshl_add_u64 v[142:143], v[142:143], 0, v[132:133]
	v_add_f32_e32 v141, 1.0, v141
	v_rcp_f32_e32 v141, v141
	s_nop 0
	v_mul_f32_e32 v128, v128, v141
	v_cvt_pk_bf16_f32 v128, v128, s0
	global_store_short v[142:143], v128, off
	v_mul_f32_e32 v128, v117, v129
	v_mul_f32_e32 v141, 0xbfb8aa3b, v128
	v_exp_f32_e32 v141, v141
	v_add_u32_e32 v142, 9, v140
	v_ashrrev_i32_e32 v143, 31, v142
	v_lshlrev_b64 v[142:143], 10, v[142:143]
	v_add_f32_e32 v141, 1.0, v141
	v_rcp_f32_e32 v141, v141
	v_lshl_add_u64 v[142:143], s[30:31], 0, v[142:143]
	v_lshl_add_u64 v[146:147], v[142:143], 0, v[138:139]
	v_mul_f32_e32 v128, v128, v141
	v_cvt_pk_bf16_f32 v128, v128, s0
	global_store_short v[146:147], v128, off
	v_mul_f32_e32 v128, v101, v129
	v_mul_f32_e32 v141, 0xbfb8aa3b, v128
	v_exp_f32_e32 v141, v141
	v_lshl_add_u64 v[146:147], v[142:143], 0, v[136:137]
	v_add_f32_e32 v141, 1.0, v141
; DI u16 f2bf(float a) { return (u16)(pack2(a, 0.f) & 0xffffu); }
; DI int crow(int reg, int g) { return (reg & 3) + 8 * (reg >> 2) + 4 * g; }
; DI float siluf(float x) { return x * __builtin_amdgcn_rcpf(1.f + __expf(-x)); }
; template <bool TR>
; DI void gemm_in_tile(const P& p, int l, int id, char* smem) {
;     ...
; #pragma unroll
;     for (int rb = 0; rb < 2; ++rb) {
; #pragma unroll
;       for (int reg = 0; reg < 16; ++reg) {
;         if ((reg & 7) == 0) asm volatile("" ::: "memory");
;         const int rl = 64 * wr + 32 * rb + crow(reg, g);
;         const int tok = m0 + rl;
;         const float rs = rs_s[rl];
; #pragma unroll
;         for (int cb = 0; cb < 4; ++cb) {
;           const int col = n0 - 3584 + 128 * wc + 32 * cb + li;
;           p.AG[(size_t)tok * 512 + col] = f2bf(siluf(acc[rb][cb][reg] * rs));
;         }
;       }
	v_rcp_f32_e32 v141, v141
	s_nop 0
	v_mul_f32_e32 v128, v128, v141
	v_cvt_pk_bf16_f32 v128, v128, s0
	global_store_short v[146:147], v128, off
	v_mul_f32_e32 v128, v85, v129
	v_mul_f32_e32 v141, 0xbfb8aa3b, v128
	v_exp_f32_e32 v141, v141
	v_lshl_add_u64 v[146:147], v[142:143], 0, v[134:135]
	v_add_f32_e32 v141, 1.0, v141
	v_rcp_f32_e32 v141, v141
	s_nop 0
	v_mul_f32_e32 v128, v128, v141
	v_cvt_pk_bf16_f32 v128, v128, s0
	global_store_short v[146:147], v128, off
	v_mul_f32_e32 v128, v69, v129
	v_mul_f32_e32 v129, 0xbfb8aa3b, v128
	v_exp_f32_e32 v129, v129
	s_nop 0
	v_add_f32_e32 v129, 1.0, v129
	v_rcp_f32_e32 v129, v129
	s_nop 0
	v_mul_f32_e32 v128, v128, v129
	v_cvt_pk_bf16_f32 v141, v128, s0
	v_lshl_add_u64 v[128:129], v[142:143], 0, v[132:133]
	global_store_short v[128:129], v141, off
	v_mul_f32_e32 v141, v118, v130
	v_mul_f32_e32 v142, 0xbfb8aa3b, v141
	v_exp_f32_e32 v142, v142
	v_add_u32_e32 v128, 10, v140
	v_ashrrev_i32_e32 v129, 31, v128
	v_lshlrev_b64 v[128:129], 10, v[128:129]
	v_add_f32_e32 v142, 1.0, v142
	v_rcp_f32_e32 v142, v142
	v_lshl_add_u64 v[128:129], s[30:31], 0, v[128:129]
	v_mul_f32_e32 v141, v141, v142
	v_cvt_pk_bf16_f32 v141, v141, s0
	v_lshl_add_u64 v[142:143], v[128:129], 0, v[138:139]
	global_store_short v[142:143], v141, off
	v_mul_f32_e32 v141, v102, v130
	v_mul_f32_e32 v142, 0xbfb8aa3b, v141
	v_exp_f32_e32 v142, v142
	s_nop 0
	v_add_f32_e32 v142, 1.0, v142
	v_rcp_f32_e32 v142, v142
	s_nop 0
	v_mul_f32_e32 v141, v141, v142
	v_cvt_pk_bf16_f32 v141, v141, s0
	v_lshl_add_u64 v[142:143], v[128:129], 0, v[136:137]
	global_store_short v[142:143], v141, off
	v_mul_f32_e32 v141, v86, v130
	v_mul_f32_e32 v142, 0xbfb8aa3b, v141
	v_exp_f32_e32 v142, v142
	v_mul_f32_e32 v130, v70, v130
	v_add_f32_e32 v142, 1.0, v142
	v_rcp_f32_e32 v142, v142
	s_nop 0
	v_mul_f32_e32 v141, v141, v142
	v_cvt_pk_bf16_f32 v141, v141, s0
	v_lshl_add_u64 v[142:143], v[128:129], 0, v[134:135]
	global_store_short v[142:143], v141, off
	v_mul_f32_e32 v141, 0xbfb8aa3b, v130
	v_exp_f32_e32 v141, v141
	v_lshl_add_u64 v[128:129], v[128:129], 0, v[132:133]
	v_add_f32_e32 v141, 1.0, v141
	v_rcp_f32_e32 v141, v141
	s_nop 0
	v_mul_f32_e32 v130, v130, v141
	v_cvt_pk_bf16_f32 v130, v130, s0
	global_store_short v[128:129], v130, off
	v_mul_f32_e32 v130, v119, v131
	v_mul_f32_e32 v141, 0xbfb8aa3b, v130
	v_exp_f32_e32 v141, v141
	v_add_u32_e32 v128, 11, v140
	v_ashrrev_i32_e32 v129, 31, v128
	v_lshlrev_b64 v[128:129], 10, v[128:129]
	v_add_f32_e32 v141, 1.0, v141
	v_rcp_f32_e32 v141, v141
	v_lshl_add_u64 v[128:129], s[30:31], 0, v[128:129]
	v_lshl_add_u64 v[142:143], v[128:129], 0, v[138:139]
	v_mul_f32_e32 v130, v130, v141
	v_cvt_pk_bf16_f32 v130, v130, s0
	global_store_short v[142:143], v130, off
	v_mul_f32_e32 v130, v103, v131
	v_mul_f32_e32 v141, 0xbfb8aa3b, v130
	v_exp_f32_e32 v141, v141
	v_lshl_add_u64 v[142:143], v[128:129], 0, v[136:137]
	v_add_f32_e32 v141, 1.0, v141
	v_rcp_f32_e32 v141, v141
	s_nop 0
	v_mul_f32_e32 v130, v130, v141
	v_cvt_pk_bf16_f32 v130, v130, s0
	global_store_short v[142:143], v130, off
	v_mul_f32_e32 v130, v87, v131
	v_mul_f32_e32 v141, 0xbfb8aa3b, v130
	v_exp_f32_e32 v141, v141
	v_lshl_add_u64 v[142:143], v[128:129], 0, v[134:135]
	v_lshl_add_u64 v[128:129], v[128:129], 0, v[132:133]
	v_add_f32_e32 v141, 1.0, v141
	v_rcp_f32_e32 v141, v141
	s_nop 0
	v_mul_f32_e32 v130, v130, v141
	v_cvt_pk_bf16_f32 v130, v130, s0
	global_store_short v[142:143], v130, off
	v_mul_f32_e32 v130, v71, v131
	v_mul_f32_e32 v131, 0xbfb8aa3b, v130
	v_exp_f32_e32 v131, v131
	s_nop 0
	v_add_f32_e32 v131, 1.0, v131
	v_rcp_f32_e32 v131, v131
	s_nop 0
	v_mul_f32_e32 v130, v130, v131
	v_cvt_pk_bf16_f32 v130, v130, s0
	global_store_short v[128:129], v130, off
	v_or_b32_e32 v128, 16, v144
	v_add_u32_e32 v142, s76, v128
	v_lshl_add_u32 v128, v128, 2, s8
	ds_read_b128 v[128:131], v128
	v_ashrrev_i32_e32 v143, 31, v142
	v_lshlrev_b64 v[142:143], 10, v[142:143]
	v_lshl_add_u64 v[142:143], s[30:31], 0, v[142:143]
	s_waitcnt lgkmcnt(0)
	v_mul_f32_e32 v141, v120, v128
	v_mul_f32_e32 v146, 0xbfb8aa3b, v141
	v_exp_f32_e32 v146, v146
	s_nop 0
	v_add_f32_e32 v146, 1.0, v146
	v_rcp_f32_e32 v146, v146
	s_nop 0
	v_mul_f32_e32 v141, v141, v146
	v_cvt_pk_bf16_f32 v141, v141, s0
	v_lshl_add_u64 v[146:147], v[142:143], 0, v[138:139]
	global_store_short v[146:147], v141, off
	v_mul_f32_e32 v141, v104, v128
	v_mul_f32_e32 v146, 0xbfb8aa3b, v141
	v_exp_f32_e32 v146, v146
	s_nop 0
	v_add_f32_e32 v146, 1.0, v146
	v_rcp_f32_e32 v146, v146
	s_nop 0
	v_mul_f32_e32 v141, v141, v146
	v_cvt_pk_bf16_f32 v141, v141, s0
	v_lshl_add_u64 v[146:147], v[142:143], 0, v[136:137]
	global_store_short v[146:147], v141, off
	v_mul_f32_e32 v141, v88, v128
	v_mul_f32_e32 v146, 0xbfb8aa3b, v141
	v_exp_f32_e32 v146, v146
	v_mul_f32_e32 v128, v72, v128
	v_add_f32_e32 v146, 1.0, v146
	v_rcp_f32_e32 v146, v146
	s_nop 0
	v_mul_f32_e32 v141, v141, v146
	v_cvt_pk_bf16_f32 v141, v141, s0
	v_lshl_add_u64 v[146:147], v[142:143], 0, v[134:135]
	global_store_short v[146:147], v141, off
	v_mul_f32_e32 v141, 0xbfb8aa3b, v128
	v_exp_f32_e32 v141, v141
	v_lshl_add_u64 v[142:143], v[142:143], 0, v[132:133]
	v_add_f32_e32 v141, 1.0, v141
	v_rcp_f32_e32 v141, v141
	s_nop 0
	v_mul_f32_e32 v128, v128, v141
	v_cvt_pk_bf16_f32 v128, v128, s0
	global_store_short v[142:143], v128, off
	v_mul_f32_e32 v128, v121, v129
	v_mul_f32_e32 v141, 0xbfb8aa3b, v128
	v_exp_f32_e32 v141, v141
	v_add_u32_e32 v142, 17, v140
	v_ashrrev_i32_e32 v143, 31, v142
	v_lshlrev_b64 v[142:143], 10, v[142:143]
	v_add_f32_e32 v141, 1.0, v141
	v_rcp_f32_e32 v141, v141
	v_lshl_add_u64 v[142:143], s[30:31], 0, v[142:143]
	v_lshl_add_u64 v[146:147], v[142:143], 0, v[138:139]
; DI u16 f2bf(float a) { return (u16)(pack2(a, 0.f) & 0xffffu); }
; DI int crow(int reg, int g) { return (reg & 3) + 8 * (reg >> 2) + 4 * g; }
; DI float siluf(float x) { return x * __builtin_amdgcn_rcpf(1.f + __expf(-x)); }
; template <bool TR>
; DI void gemm_in_tile(const P& p, int l, int id, char* smem) {
;     ...
; #pragma unroll
;     for (int rb = 0; rb < 2; ++rb) {
; #pragma unroll
;       for (int reg = 0; reg < 16; ++reg) {
;         if ((reg & 7) == 0) asm volatile("" ::: "memory");
;         const int rl = 64 * wr + 32 * rb + crow(reg, g);
;         const int tok = m0 + rl;
;         const float rs = rs_s[rl];
; #pragma unroll
;         for (int cb = 0; cb < 4; ++cb) {
;           const int col = n0 - 3584 + 128 * wc + 32 * cb + li;
;           p.AG[(size_t)tok * 512 + col] = f2bf(siluf(acc[rb][cb][reg] * rs));
;         }
;       }
	v_mul_f32_e32 v128, v128, v141
	v_cvt_pk_bf16_f32 v128, v128, s0
	global_store_short v[146:147], v128, off
	v_mul_f32_e32 v128, v105, v129
	v_mul_f32_e32 v141, 0xbfb8aa3b, v128
	v_exp_f32_e32 v141, v141
	v_lshl_add_u64 v[146:147], v[142:143], 0, v[136:137]
	v_add_f32_e32 v141, 1.0, v141
	v_rcp_f32_e32 v141, v141
	s_nop 0
	v_mul_f32_e32 v128, v128, v141
	v_cvt_pk_bf16_f32 v128, v128, s0
	global_store_short v[146:147], v128, off
	v_mul_f32_e32 v128, v89, v129
	v_mul_f32_e32 v141, 0xbfb8aa3b, v128
	v_exp_f32_e32 v141, v141
	v_lshl_add_u64 v[146:147], v[142:143], 0, v[134:135]
	v_add_f32_e32 v141, 1.0, v141
	v_rcp_f32_e32 v141, v141
	s_nop 0
	v_mul_f32_e32 v128, v128, v141
	v_cvt_pk_bf16_f32 v128, v128, s0
	global_store_short v[146:147], v128, off
	v_mul_f32_e32 v128, v73, v129
	v_mul_f32_e32 v129, 0xbfb8aa3b, v128
	v_exp_f32_e32 v129, v129
	s_nop 0
	v_add_f32_e32 v129, 1.0, v129
	v_rcp_f32_e32 v129, v129
	s_nop 0
	v_mul_f32_e32 v128, v128, v129
	v_cvt_pk_bf16_f32 v141, v128, s0
	v_lshl_add_u64 v[128:129], v[142:143], 0, v[132:133]
	global_store_short v[128:129], v141, off
	v_mul_f32_e32 v141, v122, v130
	v_mul_f32_e32 v142, 0xbfb8aa3b, v141
	v_exp_f32_e32 v142, v142
	v_add_u32_e32 v128, 18, v140
	v_ashrrev_i32_e32 v129, 31, v128
	v_lshlrev_b64 v[128:129], 10, v[128:129]
	v_add_f32_e32 v142, 1.0, v142
	v_rcp_f32_e32 v142, v142
	v_lshl_add_u64 v[128:129], s[30:31], 0, v[128:129]
	v_mul_f32_e32 v141, v141, v142
	v_cvt_pk_bf16_f32 v141, v141, s0
	v_lshl_add_u64 v[142:143], v[128:129], 0, v[138:139]
	global_store_short v[142:143], v141, off
	v_mul_f32_e32 v141, v106, v130
	v_mul_f32_e32 v142, 0xbfb8aa3b, v141
	v_exp_f32_e32 v142, v142
	s_nop 0
	v_add_f32_e32 v142, 1.0, v142
	v_rcp_f32_e32 v142, v142
	s_nop 0
	v_mul_f32_e32 v141, v141, v142
	v_cvt_pk_bf16_f32 v141, v141, s0
	v_lshl_add_u64 v[142:143], v[128:129], 0, v[136:137]
	global_store_short v[142:143], v141, off
	v_mul_f32_e32 v141, v90, v130
	v_mul_f32_e32 v142, 0xbfb8aa3b, v141
	v_exp_f32_e32 v142, v142
	v_mul_f32_e32 v130, v74, v130
	v_add_f32_e32 v142, 1.0, v142
	v_rcp_f32_e32 v142, v142
	s_nop 0
	v_mul_f32_e32 v141, v141, v142
	v_cvt_pk_bf16_f32 v141, v141, s0
	v_lshl_add_u64 v[142:143], v[128:129], 0, v[134:135]
	global_store_short v[142:143], v141, off
	v_mul_f32_e32 v141, 0xbfb8aa3b, v130
	v_exp_f32_e32 v141, v141
	v_lshl_add_u64 v[128:129], v[128:129], 0, v[132:133]
	v_add_f32_e32 v141, 1.0, v141
	v_rcp_f32_e32 v141, v141
	s_nop 0
	v_mul_f32_e32 v130, v130, v141
	v_cvt_pk_bf16_f32 v130, v130, s0
	global_store_short v[128:129], v130, off
	v_mul_f32_e32 v130, v123, v131
	v_mul_f32_e32 v141, 0xbfb8aa3b, v130
	v_exp_f32_e32 v141, v141
	v_add_u32_e32 v128, 19, v140
	v_ashrrev_i32_e32 v129, 31, v128
	v_lshlrev_b64 v[128:129], 10, v[128:129]
	v_add_f32_e32 v141, 1.0, v141
	v_rcp_f32_e32 v141, v141
	v_lshl_add_u64 v[128:129], s[30:31], 0, v[128:129]
	v_lshl_add_u64 v[142:143], v[128:129], 0, v[138:139]
	v_mul_f32_e32 v130, v130, v141
	v_cvt_pk_bf16_f32 v130, v130, s0
	global_store_short v[142:143], v130, off
	v_mul_f32_e32 v130, v107, v131
	v_mul_f32_e32 v141, 0xbfb8aa3b, v130
	v_exp_f32_e32 v141, v141
	v_lshl_add_u64 v[142:143], v[128:129], 0, v[136:137]
	v_add_f32_e32 v141, 1.0, v141
	v_rcp_f32_e32 v141, v141
	s_nop 0
	v_mul_f32_e32 v130, v130, v141
	v_cvt_pk_bf16_f32 v130, v130, s0
	global_store_short v[142:143], v130, off
	v_mul_f32_e32 v130, v91, v131
	v_mul_f32_e32 v141, 0xbfb8aa3b, v130
	v_exp_f32_e32 v141, v141
	v_lshl_add_u64 v[142:143], v[128:129], 0, v[134:135]
	v_lshl_add_u64 v[128:129], v[128:129], 0, v[132:133]
	v_add_f32_e32 v141, 1.0, v141
	v_rcp_f32_e32 v141, v141
	s_nop 0
	v_mul_f32_e32 v130, v130, v141
	v_cvt_pk_bf16_f32 v130, v130, s0
	global_store_short v[142:143], v130, off
	v_mul_f32_e32 v130, v75, v131
	v_mul_f32_e32 v131, 0xbfb8aa3b, v130
	v_exp_f32_e32 v131, v131
	s_nop 0
	v_add_f32_e32 v131, 1.0, v131
	v_rcp_f32_e32 v131, v131
	s_nop 0
	v_mul_f32_e32 v130, v130, v131
	v_cvt_pk_bf16_f32 v130, v130, s0
	global_store_short v[128:129], v130, off
	v_or_b32_e32 v128, 24, v144
	v_add_u32_e32 v142, s76, v128
	v_lshl_add_u32 v128, v128, 2, s8
	ds_read_b128 v[128:131], v128
	v_ashrrev_i32_e32 v143, 31, v142
	v_lshlrev_b64 v[142:143], 10, v[142:143]
	v_lshl_add_u64 v[142:143], s[30:31], 0, v[142:143]
	s_waitcnt lgkmcnt(0)
; DI u16 f2bf(float a) { return (u16)(pack2(a, 0.f) & 0xffffu); }
; DI int crow(int reg, int g) { return (reg & 3) + 8 * (reg >> 2) + 4 * g; }
; DI float siluf(float x) { return x * __builtin_amdgcn_rcpf(1.f + __expf(-x)); }
; template <bool TR>
; DI void gemm_in_tile(const P& p, int l, int id, char* smem) {
;     ...
; #pragma unroll
;     for (int rb = 0; rb < 2; ++rb) {
; #pragma unroll
;       for (int reg = 0; reg < 16; ++reg) {
;         if ((reg & 7) == 0) asm volatile("" ::: "memory");
;         const int rl = 64 * wr + 32 * rb + crow(reg, g);
;         const int tok = m0 + rl;
;         const float rs = rs_s[rl];
; #pragma unroll
;         for (int cb = 0; cb < 4; ++cb) {
;           const int col = n0 - 3584 + 128 * wc + 32 * cb + li;
;           p.AG[(size_t)tok * 512 + col] = f2bf(siluf(acc[rb][cb][reg] * rs));
;         }
;       }
	v_mul_f32_e32 v141, v124, v128
	v_mul_f32_e32 v146, 0xbfb8aa3b, v141
	v_exp_f32_e32 v146, v146
	s_nop 0
	v_add_f32_e32 v146, 1.0, v146
	v_rcp_f32_e32 v146, v146
	s_nop 0
	v_mul_f32_e32 v141, v141, v146
	v_cvt_pk_bf16_f32 v141, v141, s0
	v_lshl_add_u64 v[146:147], v[142:143], 0, v[138:139]
	global_store_short v[146:147], v141, off
	v_mul_f32_e32 v141, v108, v128
	v_mul_f32_e32 v146, 0xbfb8aa3b, v141
	v_exp_f32_e32 v146, v146
	s_nop 0
	v_add_f32_e32 v146, 1.0, v146
	v_rcp_f32_e32 v146, v146
	s_nop 0
	v_mul_f32_e32 v141, v141, v146
	v_cvt_pk_bf16_f32 v141, v141, s0
	v_lshl_add_u64 v[146:147], v[142:143], 0, v[136:137]
	global_store_short v[146:147], v141, off
	v_mul_f32_e32 v141, v92, v128
	v_mul_f32_e32 v146, 0xbfb8aa3b, v141
	v_exp_f32_e32 v146, v146
	v_mul_f32_e32 v128, v76, v128
	v_add_f32_e32 v146, 1.0, v146
	v_rcp_f32_e32 v146, v146
	s_nop 0
	v_mul_f32_e32 v141, v141, v146
	v_cvt_pk_bf16_f32 v141, v141, s0
	v_lshl_add_u64 v[146:147], v[142:143], 0, v[134:135]
	global_store_short v[146:147], v141, off
	v_mul_f32_e32 v141, 0xbfb8aa3b, v128
	v_exp_f32_e32 v141, v141
	v_lshl_add_u64 v[142:143], v[142:143], 0, v[132:133]
	v_add_f32_e32 v141, 1.0, v141
	v_rcp_f32_e32 v141, v141
	s_nop 0
	v_mul_f32_e32 v128, v128, v141
	v_cvt_pk_bf16_f32 v128, v128, s0
	global_store_short v[142:143], v128, off
	v_mul_f32_e32 v128, v125, v129
	v_mul_f32_e32 v141, 0xbfb8aa3b, v128
	v_exp_f32_e32 v141, v141
	v_add_u32_e32 v142, 25, v140
	v_ashrrev_i32_e32 v143, 31, v142
	v_lshlrev_b64 v[142:143], 10, v[142:143]
	v_add_f32_e32 v141, 1.0, v141
	v_rcp_f32_e32 v141, v141
	v_lshl_add_u64 v[142:143], s[30:31], 0, v[142:143]
	v_lshl_add_u64 v[146:147], v[142:143], 0, v[138:139]
	v_mul_f32_e32 v128, v128, v141
	v_cvt_pk_bf16_f32 v128, v128, s0
	global_store_short v[146:147], v128, off
	v_mul_f32_e32 v128, v109, v129
	v_mul_f32_e32 v141, 0xbfb8aa3b, v128
	v_exp_f32_e32 v141, v141
	v_lshl_add_u64 v[146:147], v[142:143], 0, v[136:137]
	v_add_f32_e32 v141, 1.0, v141
	v_rcp_f32_e32 v141, v141
	s_nop 0
	v_mul_f32_e32 v128, v128, v141
	v_cvt_pk_bf16_f32 v128, v128, s0
	global_store_short v[146:147], v128, off
	v_mul_f32_e32 v128, v93, v129
	v_mul_f32_e32 v141, 0xbfb8aa3b, v128
	v_exp_f32_e32 v141, v141
	v_lshl_add_u64 v[146:147], v[142:143], 0, v[134:135]
	v_add_f32_e32 v141, 1.0, v141
	v_rcp_f32_e32 v141, v141
	s_nop 0
	v_mul_f32_e32 v128, v128, v141
	v_cvt_pk_bf16_f32 v128, v128, s0
	global_store_short v[146:147], v128, off
	v_mul_f32_e32 v128, v77, v129
	v_mul_f32_e32 v129, 0xbfb8aa3b, v128
	v_exp_f32_e32 v129, v129
	s_nop 0
	v_add_f32_e32 v129, 1.0, v129
	v_rcp_f32_e32 v129, v129
	s_nop 0
	v_mul_f32_e32 v128, v128, v129
	v_cvt_pk_bf16_f32 v141, v128, s0
	v_lshl_add_u64 v[128:129], v[142:143], 0, v[132:133]
	global_store_short v[128:129], v141, off
	v_mul_f32_e32 v141, v126, v130
	v_mul_f32_e32 v142, 0xbfb8aa3b, v141
	v_exp_f32_e32 v142, v142
	v_add_u32_e32 v128, 26, v140
	v_ashrrev_i32_e32 v129, 31, v128
	v_lshlrev_b64 v[128:129], 10, v[128:129]
	v_add_f32_e32 v142, 1.0, v142
	v_rcp_f32_e32 v142, v142
	v_lshl_add_u64 v[128:129], s[30:31], 0, v[128:129]
	v_mul_f32_e32 v141, v141, v142
	v_cvt_pk_bf16_f32 v141, v141, s0
	v_lshl_add_u64 v[142:143], v[128:129], 0, v[138:139]
	global_store_short v[142:143], v141, off
	v_mul_f32_e32 v141, v110, v130
	v_mul_f32_e32 v142, 0xbfb8aa3b, v141
	v_exp_f32_e32 v142, v142
	s_nop 0
	v_add_f32_e32 v142, 1.0, v142
	v_rcp_f32_e32 v142, v142
	s_nop 0
	v_mul_f32_e32 v141, v141, v142
	v_cvt_pk_bf16_f32 v141, v141, s0
	v_lshl_add_u64 v[142:143], v[128:129], 0, v[136:137]
	global_store_short v[142:143], v141, off
	v_mul_f32_e32 v141, v94, v130
	v_mul_f32_e32 v142, 0xbfb8aa3b, v141
	v_exp_f32_e32 v142, v142
	v_mul_f32_e32 v130, v78, v130
	v_add_f32_e32 v142, 1.0, v142
	v_rcp_f32_e32 v142, v142
	s_nop 0
	v_mul_f32_e32 v141, v141, v142
	v_cvt_pk_bf16_f32 v141, v141, s0
	v_lshl_add_u64 v[142:143], v[128:129], 0, v[134:135]
	global_store_short v[142:143], v141, off
	v_mul_f32_e32 v141, 0xbfb8aa3b, v130
	v_exp_f32_e32 v141, v141
	v_lshl_add_u64 v[128:129], v[128:129], 0, v[132:133]
	v_add_f32_e32 v141, 1.0, v141
	v_rcp_f32_e32 v141, v141
	s_nop 0
	v_mul_f32_e32 v130, v130, v141
	v_cvt_pk_bf16_f32 v130, v130, s0
	global_store_short v[128:129], v130, off
	v_mul_f32_e32 v130, v127, v131
	v_mul_f32_e32 v141, 0xbfb8aa3b, v130
	v_exp_f32_e32 v141, v141
	v_add_u32_e32 v128, 27, v140
	v_ashrrev_i32_e32 v129, 31, v128
	v_lshlrev_b64 v[128:129], 10, v[128:129]
	v_add_f32_e32 v141, 1.0, v141
	v_rcp_f32_e32 v141, v141
	v_lshl_add_u64 v[128:129], s[30:31], 0, v[128:129]
	v_lshl_add_u64 v[142:143], v[128:129], 0, v[138:139]
	v_mul_f32_e32 v130, v130, v141
	v_cvt_pk_bf16_f32 v130, v130, s0
	global_store_short v[142:143], v130, off
	v_mul_f32_e32 v130, v111, v131
	v_mul_f32_e32 v141, 0xbfb8aa3b, v130
	v_exp_f32_e32 v141, v141
	v_lshl_add_u64 v[142:143], v[128:129], 0, v[136:137]
	v_add_f32_e32 v141, 1.0, v141
	v_rcp_f32_e32 v141, v141
	s_nop 0
	v_mul_f32_e32 v130, v130, v141
	v_cvt_pk_bf16_f32 v130, v130, s0
	global_store_short v[142:143], v130, off
	v_mul_f32_e32 v130, v95, v131
	v_mul_f32_e32 v141, 0xbfb8aa3b, v130
	v_exp_f32_e32 v141, v141
	v_lshl_add_u64 v[142:143], v[128:129], 0, v[134:135]
	v_lshl_add_u64 v[128:129], v[128:129], 0, v[132:133]
	v_add_f32_e32 v141, 1.0, v141
	v_rcp_f32_e32 v141, v141
	s_nop 0
	v_mul_f32_e32 v130, v130, v141
	v_cvt_pk_bf16_f32 v130, v130, s0
	global_store_short v[142:143], v130, off
	v_mul_f32_e32 v130, v79, v131
	v_mul_f32_e32 v131, 0xbfb8aa3b, v130
	v_exp_f32_e32 v131, v131
	s_nop 0
	v_add_f32_e32 v131, 1.0, v131
	v_rcp_f32_e32 v131, v131
	s_nop 0
	v_mul_f32_e32 v130, v130, v131
	v_cvt_pk_bf16_f32 v130, v130, s0
	global_store_short v[128:129], v130, off
	v_or_b32_e32 v128, 32, v144
	v_add_u32_e32 v142, s76, v128
	v_lshl_add_u32 v128, v128, 2, s8
	ds_read_b128 v[128:131], v128
	v_ashrrev_i32_e32 v143, 31, v142
	v_lshlrev_b64 v[142:143], 10, v[142:143]
	v_lshl_add_u64 v[142:143], s[30:31], 0, v[142:143]
	s_waitcnt lgkmcnt(0)
; DI u16 f2bf(float a) { return (u16)(pack2(a, 0.f) & 0xffffu); }
; DI int crow(int reg, int g) { return (reg & 3) + 8 * (reg >> 2) + 4 * g; }
; DI float siluf(float x) { return x * __builtin_amdgcn_rcpf(1.f + __expf(-x)); }
; template <bool TR>
; DI void gemm_in_tile(const P& p, int l, int id, char* smem) {
;     ...
; #pragma unroll
;     for (int rb = 0; rb < 2; ++rb) {
; #pragma unroll
;       for (int reg = 0; reg < 16; ++reg) {
;         if ((reg & 7) == 0) asm volatile("" ::: "memory");
;         const int rl = 64 * wr + 32 * rb + crow(reg, g);
;         const int tok = m0 + rl;
;         const float rs = rs_s[rl];
; #pragma unroll
;         for (int cb = 0; cb < 4; ++cb) {
;           const int col = n0 - 3584 + 128 * wc + 32 * cb + li;
;           p.AG[(size_t)tok * 512 + col] = f2bf(siluf(acc[rb][cb][reg] * rs));
;         }
;       }
	v_mul_f32_e32 v141, v48, v128
	v_mul_f32_e32 v146, 0xbfb8aa3b, v141
	v_exp_f32_e32 v146, v146
	s_nop 0
	v_add_f32_e32 v146, 1.0, v146
	v_rcp_f32_e32 v146, v146
	s_nop 0
	v_mul_f32_e32 v141, v141, v146
	v_cvt_pk_bf16_f32 v141, v141, s0
	v_lshl_add_u64 v[146:147], v[142:143], 0, v[138:139]
	global_store_short v[146:147], v141, off
	v_mul_f32_e32 v141, v32, v128
	v_mul_f32_e32 v146, 0xbfb8aa3b, v141
	v_exp_f32_e32 v146, v146
	s_nop 0
	v_add_f32_e32 v146, 1.0, v146
	v_rcp_f32_e32 v146, v146
	s_nop 0
	v_mul_f32_e32 v141, v141, v146
	v_cvt_pk_bf16_f32 v141, v141, s0
	v_lshl_add_u64 v[146:147], v[142:143], 0, v[136:137]
	global_store_short v[146:147], v141, off
	v_mul_f32_e32 v141, v16, v128
	v_mul_f32_e32 v146, 0xbfb8aa3b, v141
	v_exp_f32_e32 v146, v146
	v_mul_f32_e32 v128, v0, v128
	v_add_f32_e32 v146, 1.0, v146
	v_rcp_f32_e32 v146, v146
	s_nop 0
	v_mul_f32_e32 v141, v141, v146
	v_cvt_pk_bf16_f32 v141, v141, s0
	v_lshl_add_u64 v[146:147], v[142:143], 0, v[134:135]
	global_store_short v[146:147], v141, off
	v_mul_f32_e32 v141, 0xbfb8aa3b, v128
	v_exp_f32_e32 v141, v141
	v_lshl_add_u64 v[142:143], v[142:143], 0, v[132:133]
	v_add_f32_e32 v141, 1.0, v141
	v_rcp_f32_e32 v141, v141
	s_nop 0
	v_mul_f32_e32 v128, v128, v141
	v_cvt_pk_bf16_f32 v128, v128, s0
	global_store_short v[142:143], v128, off
	v_mul_f32_e32 v128, v49, v129
	v_mul_f32_e32 v141, 0xbfb8aa3b, v128
	v_exp_f32_e32 v141, v141
	v_add_u32_e32 v142, 33, v140
	v_ashrrev_i32_e32 v143, 31, v142
	v_lshlrev_b64 v[142:143], 10, v[142:143]
	v_add_f32_e32 v141, 1.0, v141
	v_rcp_f32_e32 v141, v141
	v_lshl_add_u64 v[142:143], s[30:31], 0, v[142:143]
	v_lshl_add_u64 v[146:147], v[142:143], 0, v[138:139]
	v_mul_f32_e32 v128, v128, v141
	v_cvt_pk_bf16_f32 v128, v128, s0
	global_store_short v[146:147], v128, off
	v_mul_f32_e32 v128, v33, v129
	v_mul_f32_e32 v141, 0xbfb8aa3b, v128
	v_exp_f32_e32 v141, v141
	v_lshl_add_u64 v[146:147], v[142:143], 0, v[136:137]
	v_add_f32_e32 v141, 1.0, v141
	v_rcp_f32_e32 v141, v141
	s_nop 0
	v_mul_f32_e32 v128, v128, v141
	v_cvt_pk_bf16_f32 v128, v128, s0
	global_store_short v[146:147], v128, off
	v_mul_f32_e32 v128, v17, v129
	v_mul_f32_e32 v141, 0xbfb8aa3b, v128
	v_exp_f32_e32 v141, v141
	v_lshl_add_u64 v[146:147], v[142:143], 0, v[134:135]
	v_add_f32_e32 v141, 1.0, v141
	v_rcp_f32_e32 v141, v141
	s_nop 0
	v_mul_f32_e32 v128, v128, v141
	v_cvt_pk_bf16_f32 v128, v128, s0
	global_store_short v[146:147], v128, off
	v_mul_f32_e32 v128, v1, v129
	v_mul_f32_e32 v129, 0xbfb8aa3b, v128
	v_exp_f32_e32 v129, v129
	s_nop 0
	v_add_f32_e32 v129, 1.0, v129
	v_rcp_f32_e32 v129, v129
	s_nop 0
	v_mul_f32_e32 v128, v128, v129
	v_cvt_pk_bf16_f32 v141, v128, s0
	v_lshl_add_u64 v[128:129], v[142:143], 0, v[132:133]
	global_store_short v[128:129], v141, off
	v_mul_f32_e32 v141, v50, v130
	v_mul_f32_e32 v142, 0xbfb8aa3b, v141
	v_exp_f32_e32 v142, v142
	v_add_u32_e32 v128, 34, v140
	v_ashrrev_i32_e32 v129, 31, v128
	v_lshlrev_b64 v[128:129], 10, v[128:129]
	v_add_f32_e32 v142, 1.0, v142
	v_rcp_f32_e32 v142, v142
	v_lshl_add_u64 v[128:129], s[30:31], 0, v[128:129]
	v_mul_f32_e32 v141, v141, v142
	v_cvt_pk_bf16_f32 v141, v141, s0
	v_lshl_add_u64 v[142:143], v[128:129], 0, v[138:139]
	global_store_short v[142:143], v141, off
	v_mul_f32_e32 v141, v34, v130
	v_mul_f32_e32 v142, 0xbfb8aa3b, v141
	v_exp_f32_e32 v142, v142
	s_nop 0
	v_add_f32_e32 v142, 1.0, v142
	v_rcp_f32_e32 v142, v142
	s_nop 0
	v_mul_f32_e32 v141, v141, v142
	v_cvt_pk_bf16_f32 v141, v141, s0
	v_lshl_add_u64 v[142:143], v[128:129], 0, v[136:137]
	global_store_short v[142:143], v141, off
	v_mul_f32_e32 v141, v18, v130
	v_mul_f32_e32 v142, 0xbfb8aa3b, v141
	v_exp_f32_e32 v142, v142
	v_mul_f32_e32 v130, v2, v130
	v_add_f32_e32 v142, 1.0, v142
	v_rcp_f32_e32 v142, v142
	s_nop 0
	v_mul_f32_e32 v141, v141, v142
	v_cvt_pk_bf16_f32 v141, v141, s0
	v_lshl_add_u64 v[142:143], v[128:129], 0, v[134:135]
	global_store_short v[142:143], v141, off
	v_mul_f32_e32 v141, 0xbfb8aa3b, v130
	v_exp_f32_e32 v141, v141
	v_lshl_add_u64 v[128:129], v[128:129], 0, v[132:133]
	v_add_f32_e32 v141, 1.0, v141
	v_rcp_f32_e32 v141, v141
	s_nop 0
	v_mul_f32_e32 v130, v130, v141
	v_cvt_pk_bf16_f32 v130, v130, s0
	global_store_short v[128:129], v130, off
	v_mul_f32_e32 v130, v51, v131
	v_mul_f32_e32 v141, 0xbfb8aa3b, v130
	v_exp_f32_e32 v141, v141
	v_add_u32_e32 v128, 35, v140
	v_ashrrev_i32_e32 v129, 31, v128
	v_lshlrev_b64 v[128:129], 10, v[128:129]
	v_add_f32_e32 v141, 1.0, v141
	v_rcp_f32_e32 v141, v141
	v_lshl_add_u64 v[128:129], s[30:31], 0, v[128:129]
	v_lshl_add_u64 v[142:143], v[128:129], 0, v[138:139]
	v_mul_f32_e32 v130, v130, v141
	v_cvt_pk_bf16_f32 v130, v130, s0
	global_store_short v[142:143], v130, off
	v_mul_f32_e32 v130, v35, v131
	v_mul_f32_e32 v141, 0xbfb8aa3b, v130
	v_exp_f32_e32 v141, v141
	v_lshl_add_u64 v[142:143], v[128:129], 0, v[136:137]
	v_add_f32_e32 v141, 1.0, v141
	v_rcp_f32_e32 v141, v141
	s_nop 0
	v_mul_f32_e32 v130, v130, v141
	v_cvt_pk_bf16_f32 v130, v130, s0
	global_store_short v[142:143], v130, off
	v_mul_f32_e32 v130, v19, v131
	v_mul_f32_e32 v141, 0xbfb8aa3b, v130
	v_exp_f32_e32 v141, v141
	v_lshl_add_u64 v[142:143], v[128:129], 0, v[134:135]
	v_lshl_add_u64 v[128:129], v[128:129], 0, v[132:133]
	v_add_f32_e32 v141, 1.0, v141
	v_rcp_f32_e32 v141, v141
	s_nop 0
	v_mul_f32_e32 v130, v130, v141
	v_cvt_pk_bf16_f32 v130, v130, s0
	global_store_short v[142:143], v130, off
	v_mul_f32_e32 v130, v3, v131
	v_mul_f32_e32 v131, 0xbfb8aa3b, v130
	v_exp_f32_e32 v131, v131
	s_nop 0
	v_add_f32_e32 v131, 1.0, v131
	v_rcp_f32_e32 v131, v131
	s_nop 0
	v_mul_f32_e32 v130, v130, v131
	v_cvt_pk_bf16_f32 v130, v130, s0
	global_store_short v[128:129], v130, off
	v_or_b32_e32 v128, 40, v144
	v_add_u32_e32 v142, s76, v128
	v_lshl_add_u32 v128, v128, 2, s8
	ds_read_b128 v[128:131], v128
	v_ashrrev_i32_e32 v143, 31, v142
	v_lshlrev_b64 v[142:143], 10, v[142:143]
	v_lshl_add_u64 v[142:143], s[30:31], 0, v[142:143]
	s_waitcnt lgkmcnt(0)
; DI u16 f2bf(float a) { return (u16)(pack2(a, 0.f) & 0xffffu); }
; DI int crow(int reg, int g) { return (reg & 3) + 8 * (reg >> 2) + 4 * g; }
; DI float siluf(float x) { return x * __builtin_amdgcn_rcpf(1.f + __expf(-x)); }
; template <bool TR>
; DI void gemm_in_tile(const P& p, int l, int id, char* smem) {
;     ...
; #pragma unroll
;     for (int rb = 0; rb < 2; ++rb) {
; #pragma unroll
;       for (int reg = 0; reg < 16; ++reg) {
;         if ((reg & 7) == 0) asm volatile("" ::: "memory");
;         const int rl = 64 * wr + 32 * rb + crow(reg, g);
;         const int tok = m0 + rl;
;         const float rs = rs_s[rl];
; #pragma unroll
;         for (int cb = 0; cb < 4; ++cb) {
;           const int col = n0 - 3584 + 128 * wc + 32 * cb + li;
;           p.AG[(size_t)tok * 512 + col] = f2bf(siluf(acc[rb][cb][reg] * rs));
;         }
;       }
	v_mul_f32_e32 v141, v52, v128
	v_mul_f32_e32 v146, 0xbfb8aa3b, v141
	v_exp_f32_e32 v146, v146
	s_nop 0
	v_add_f32_e32 v146, 1.0, v146
	v_rcp_f32_e32 v146, v146
	s_nop 0
	v_mul_f32_e32 v141, v141, v146
	v_cvt_pk_bf16_f32 v141, v141, s0
	v_lshl_add_u64 v[146:147], v[142:143], 0, v[138:139]
	global_store_short v[146:147], v141, off
	v_mul_f32_e32 v141, v36, v128
	v_mul_f32_e32 v146, 0xbfb8aa3b, v141
	v_exp_f32_e32 v146, v146
	s_nop 0
	v_add_f32_e32 v146, 1.0, v146
	v_rcp_f32_e32 v146, v146
	s_nop 0
	v_mul_f32_e32 v141, v141, v146
	v_cvt_pk_bf16_f32 v141, v141, s0
	v_lshl_add_u64 v[146:147], v[142:143], 0, v[136:137]
	global_store_short v[146:147], v141, off
	v_mul_f32_e32 v141, v20, v128
	v_mul_f32_e32 v146, 0xbfb8aa3b, v141
	v_exp_f32_e32 v146, v146
	v_mul_f32_e32 v128, v4, v128
	v_add_f32_e32 v146, 1.0, v146
	v_rcp_f32_e32 v146, v146
	s_nop 0
	v_mul_f32_e32 v141, v141, v146
	v_cvt_pk_bf16_f32 v141, v141, s0
	v_lshl_add_u64 v[146:147], v[142:143], 0, v[134:135]
	global_store_short v[146:147], v141, off
	v_mul_f32_e32 v141, 0xbfb8aa3b, v128
	v_exp_f32_e32 v141, v141
	v_lshl_add_u64 v[142:143], v[142:143], 0, v[132:133]
	v_add_f32_e32 v141, 1.0, v141
	v_rcp_f32_e32 v141, v141
	s_nop 0
	v_mul_f32_e32 v128, v128, v141
	v_cvt_pk_bf16_f32 v128, v128, s0
	global_store_short v[142:143], v128, off
	v_mul_f32_e32 v128, v53, v129
	v_mul_f32_e32 v141, 0xbfb8aa3b, v128
	v_exp_f32_e32 v141, v141
	v_add_u32_e32 v142, 41, v140
	v_ashrrev_i32_e32 v143, 31, v142
	v_lshlrev_b64 v[142:143], 10, v[142:143]
	v_add_f32_e32 v141, 1.0, v141
	v_rcp_f32_e32 v141, v141
	v_lshl_add_u64 v[142:143], s[30:31], 0, v[142:143]
	v_lshl_add_u64 v[146:147], v[142:143], 0, v[138:139]
	v_mul_f32_e32 v128, v128, v141
	v_cvt_pk_bf16_f32 v128, v128, s0
	global_store_short v[146:147], v128, off
	v_mul_f32_e32 v128, v37, v129
	v_mul_f32_e32 v141, 0xbfb8aa3b, v128
	v_exp_f32_e32 v141, v141
	v_lshl_add_u64 v[146:147], v[142:143], 0, v[136:137]
	v_add_f32_e32 v141, 1.0, v141
	v_rcp_f32_e32 v141, v141
	s_nop 0
	v_mul_f32_e32 v128, v128, v141
	v_cvt_pk_bf16_f32 v128, v128, s0
	global_store_short v[146:147], v128, off
	v_mul_f32_e32 v128, v21, v129
	v_mul_f32_e32 v141, 0xbfb8aa3b, v128
	v_exp_f32_e32 v141, v141
	v_lshl_add_u64 v[146:147], v[142:143], 0, v[134:135]
	v_add_f32_e32 v141, 1.0, v141
	v_rcp_f32_e32 v141, v141
	s_nop 0
	v_mul_f32_e32 v128, v128, v141
	v_cvt_pk_bf16_f32 v128, v128, s0
	global_store_short v[146:147], v128, off
	v_mul_f32_e32 v128, v5, v129
	v_mul_f32_e32 v129, 0xbfb8aa3b, v128
	v_exp_f32_e32 v129, v129
	s_nop 0
	v_add_f32_e32 v129, 1.0, v129
	v_rcp_f32_e32 v129, v129
	s_nop 0
	v_mul_f32_e32 v128, v128, v129
	v_cvt_pk_bf16_f32 v141, v128, s0
	v_lshl_add_u64 v[128:129], v[142:143], 0, v[132:133]
	global_store_short v[128:129], v141, off
	v_mul_f32_e32 v141, v54, v130
	v_mul_f32_e32 v142, 0xbfb8aa3b, v141
	v_exp_f32_e32 v142, v142
	v_add_u32_e32 v128, 42, v140
	v_ashrrev_i32_e32 v129, 31, v128
	v_lshlrev_b64 v[128:129], 10, v[128:129]
	v_add_f32_e32 v142, 1.0, v142
	v_rcp_f32_e32 v142, v142
	v_lshl_add_u64 v[128:129], s[30:31], 0, v[128:129]
	v_mul_f32_e32 v141, v141, v142
	v_cvt_pk_bf16_f32 v141, v141, s0
	v_lshl_add_u64 v[142:143], v[128:129], 0, v[138:139]
	global_store_short v[142:143], v141, off
	v_mul_f32_e32 v141, v38, v130
	v_mul_f32_e32 v142, 0xbfb8aa3b, v141
	v_exp_f32_e32 v142, v142
	s_nop 0
	v_add_f32_e32 v142, 1.0, v142
	v_rcp_f32_e32 v142, v142
	s_nop 0
	v_mul_f32_e32 v141, v141, v142
	v_cvt_pk_bf16_f32 v141, v141, s0
	v_lshl_add_u64 v[142:143], v[128:129], 0, v[136:137]
	global_store_short v[142:143], v141, off
	v_mul_f32_e32 v141, v22, v130
	v_mul_f32_e32 v142, 0xbfb8aa3b, v141
	v_exp_f32_e32 v142, v142
	v_mul_f32_e32 v130, v6, v130
	v_add_f32_e32 v142, 1.0, v142
	v_rcp_f32_e32 v142, v142
	s_nop 0
	v_mul_f32_e32 v141, v141, v142
	v_cvt_pk_bf16_f32 v141, v141, s0
	v_lshl_add_u64 v[142:143], v[128:129], 0, v[134:135]
	global_store_short v[142:143], v141, off
	v_mul_f32_e32 v141, 0xbfb8aa3b, v130
	v_exp_f32_e32 v141, v141
	v_lshl_add_u64 v[128:129], v[128:129], 0, v[132:133]
	v_add_f32_e32 v141, 1.0, v141
	v_rcp_f32_e32 v141, v141
	s_nop 0
	v_mul_f32_e32 v130, v130, v141
	v_cvt_pk_bf16_f32 v130, v130, s0
	global_store_short v[128:129], v130, off
	v_mul_f32_e32 v130, v55, v131
	v_mul_f32_e32 v141, 0xbfb8aa3b, v130
	v_exp_f32_e32 v141, v141
	v_add_u32_e32 v128, 43, v140
	v_ashrrev_i32_e32 v129, 31, v128
	v_lshlrev_b64 v[128:129], 10, v[128:129]
	v_add_f32_e32 v141, 1.0, v141
	v_rcp_f32_e32 v141, v141
	v_lshl_add_u64 v[128:129], s[30:31], 0, v[128:129]
	v_lshl_add_u64 v[142:143], v[128:129], 0, v[138:139]
	v_mul_f32_e32 v130, v130, v141
	v_cvt_pk_bf16_f32 v130, v130, s0
	global_store_short v[142:143], v130, off
	v_mul_f32_e32 v130, v39, v131
	v_mul_f32_e32 v141, 0xbfb8aa3b, v130
	v_exp_f32_e32 v141, v141
	v_lshl_add_u64 v[142:143], v[128:129], 0, v[136:137]
	v_add_f32_e32 v141, 1.0, v141
	v_rcp_f32_e32 v141, v141
	s_nop 0
	v_mul_f32_e32 v130, v130, v141
	v_cvt_pk_bf16_f32 v130, v130, s0
	global_store_short v[142:143], v130, off
	v_mul_f32_e32 v130, v23, v131
	v_mul_f32_e32 v141, 0xbfb8aa3b, v130
	v_exp_f32_e32 v141, v141
	v_lshl_add_u64 v[142:143], v[128:129], 0, v[134:135]
	v_lshl_add_u64 v[128:129], v[128:129], 0, v[132:133]
	v_add_f32_e32 v141, 1.0, v141
	v_rcp_f32_e32 v141, v141
	s_nop 0
	v_mul_f32_e32 v130, v130, v141
	v_cvt_pk_bf16_f32 v130, v130, s0
	global_store_short v[142:143], v130, off
	v_mul_f32_e32 v130, v7, v131
	v_mul_f32_e32 v131, 0xbfb8aa3b, v130
	v_exp_f32_e32 v131, v131
	s_nop 0
	v_add_f32_e32 v131, 1.0, v131
	v_rcp_f32_e32 v131, v131
	s_nop 0
	v_mul_f32_e32 v130, v130, v131
	v_cvt_pk_bf16_f32 v130, v130, s0
	global_store_short v[128:129], v130, off
	v_or_b32_e32 v128, 48, v144
	v_add_u32_e32 v142, s76, v128
	v_lshl_add_u32 v128, v128, 2, s8
	ds_read_b128 v[128:131], v128
	v_ashrrev_i32_e32 v143, 31, v142
	v_lshlrev_b64 v[142:143], 10, v[142:143]
	v_lshl_add_u64 v[142:143], s[30:31], 0, v[142:143]
	s_waitcnt lgkmcnt(0)
; DI u16 f2bf(float a) { return (u16)(pack2(a, 0.f) & 0xffffu); }
; DI int crow(int reg, int g) { return (reg & 3) + 8 * (reg >> 2) + 4 * g; }
; DI float siluf(float x) { return x * __builtin_amdgcn_rcpf(1.f + __expf(-x)); }
; template <bool TR>
; DI void gemm_in_tile(const P& p, int l, int id, char* smem) {
;     ...
; #pragma unroll
;     for (int rb = 0; rb < 2; ++rb) {
; #pragma unroll
;       for (int reg = 0; reg < 16; ++reg) {
;         if ((reg & 7) == 0) asm volatile("" ::: "memory");
;         const int rl = 64 * wr + 32 * rb + crow(reg, g);
;         const int tok = m0 + rl;
;         const float rs = rs_s[rl];
; #pragma unroll
;         for (int cb = 0; cb < 4; ++cb) {
;           const int col = n0 - 3584 + 128 * wc + 32 * cb + li;
;           p.AG[(size_t)tok * 512 + col] = f2bf(siluf(acc[rb][cb][reg] * rs));
;         }
;       }
	v_mul_f32_e32 v141, v56, v128
	v_mul_f32_e32 v146, 0xbfb8aa3b, v141
	v_exp_f32_e32 v146, v146
	s_nop 0
	v_add_f32_e32 v146, 1.0, v146
	v_rcp_f32_e32 v146, v146
	s_nop 0
	v_mul_f32_e32 v141, v141, v146
	v_cvt_pk_bf16_f32 v141, v141, s0
	v_lshl_add_u64 v[146:147], v[142:143], 0, v[138:139]
	global_store_short v[146:147], v141, off
	v_mul_f32_e32 v141, v40, v128
	v_mul_f32_e32 v146, 0xbfb8aa3b, v141
	v_exp_f32_e32 v146, v146
	s_nop 0
	v_add_f32_e32 v146, 1.0, v146
	v_rcp_f32_e32 v146, v146
	s_nop 0
	v_mul_f32_e32 v141, v141, v146
	v_cvt_pk_bf16_f32 v141, v141, s0
	v_lshl_add_u64 v[146:147], v[142:143], 0, v[136:137]
	global_store_short v[146:147], v141, off
	v_mul_f32_e32 v141, v24, v128
	v_mul_f32_e32 v146, 0xbfb8aa3b, v141
	v_exp_f32_e32 v146, v146
	v_mul_f32_e32 v128, v8, v128
	v_add_f32_e32 v146, 1.0, v146
	v_rcp_f32_e32 v146, v146
	s_nop 0
	v_mul_f32_e32 v141, v141, v146
	v_cvt_pk_bf16_f32 v141, v141, s0
	v_lshl_add_u64 v[146:147], v[142:143], 0, v[134:135]
	global_store_short v[146:147], v141, off
	v_mul_f32_e32 v141, 0xbfb8aa3b, v128
	v_exp_f32_e32 v141, v141
	v_lshl_add_u64 v[142:143], v[142:143], 0, v[132:133]
	v_add_f32_e32 v141, 1.0, v141
	v_rcp_f32_e32 v141, v141
	s_nop 0
	v_mul_f32_e32 v128, v128, v141
	v_cvt_pk_bf16_f32 v128, v128, s0
	global_store_short v[142:143], v128, off
	v_mul_f32_e32 v128, v57, v129
	v_mul_f32_e32 v141, 0xbfb8aa3b, v128
	v_exp_f32_e32 v141, v141
	v_add_u32_e32 v142, 49, v140
	v_ashrrev_i32_e32 v143, 31, v142
	v_lshlrev_b64 v[142:143], 10, v[142:143]
	v_add_f32_e32 v141, 1.0, v141
	v_rcp_f32_e32 v141, v141
	v_lshl_add_u64 v[142:143], s[30:31], 0, v[142:143]
	v_lshl_add_u64 v[146:147], v[142:143], 0, v[138:139]
	v_mul_f32_e32 v128, v128, v141
	v_cvt_pk_bf16_f32 v128, v128, s0
	global_store_short v[146:147], v128, off
	v_mul_f32_e32 v128, v41, v129
	v_mul_f32_e32 v141, 0xbfb8aa3b, v128
	v_exp_f32_e32 v141, v141
	v_lshl_add_u64 v[146:147], v[142:143], 0, v[136:137]
	v_add_f32_e32 v141, 1.0, v141
	v_rcp_f32_e32 v141, v141
	s_nop 0
	v_mul_f32_e32 v128, v128, v141
	v_cvt_pk_bf16_f32 v128, v128, s0
	global_store_short v[146:147], v128, off
	v_mul_f32_e32 v128, v25, v129
	v_mul_f32_e32 v141, 0xbfb8aa3b, v128
	v_exp_f32_e32 v141, v141
	v_lshl_add_u64 v[146:147], v[142:143], 0, v[134:135]
	v_add_f32_e32 v141, 1.0, v141
	v_rcp_f32_e32 v141, v141
	s_nop 0
	v_mul_f32_e32 v128, v128, v141
	v_cvt_pk_bf16_f32 v128, v128, s0
	global_store_short v[146:147], v128, off
	v_mul_f32_e32 v128, v9, v129
	v_mul_f32_e32 v129, 0xbfb8aa3b, v128
	v_exp_f32_e32 v129, v129
	s_nop 0
	v_add_f32_e32 v129, 1.0, v129
	v_rcp_f32_e32 v129, v129
	s_nop 0
	v_mul_f32_e32 v128, v128, v129
	v_cvt_pk_bf16_f32 v141, v128, s0
	v_lshl_add_u64 v[128:129], v[142:143], 0, v[132:133]
	global_store_short v[128:129], v141, off
	v_mul_f32_e32 v141, v58, v130
	v_mul_f32_e32 v142, 0xbfb8aa3b, v141
	v_exp_f32_e32 v142, v142
	v_add_u32_e32 v128, 50, v140
	v_ashrrev_i32_e32 v129, 31, v128
	v_lshlrev_b64 v[128:129], 10, v[128:129]
	v_add_f32_e32 v142, 1.0, v142
	v_rcp_f32_e32 v142, v142
	v_lshl_add_u64 v[128:129], s[30:31], 0, v[128:129]
	v_mul_f32_e32 v141, v141, v142
	v_cvt_pk_bf16_f32 v141, v141, s0
	v_lshl_add_u64 v[142:143], v[128:129], 0, v[138:139]
	global_store_short v[142:143], v141, off
	v_mul_f32_e32 v141, v42, v130
	v_mul_f32_e32 v142, 0xbfb8aa3b, v141
	v_exp_f32_e32 v142, v142
	s_nop 0
	v_add_f32_e32 v142, 1.0, v142
	v_rcp_f32_e32 v142, v142
	s_nop 0
	v_mul_f32_e32 v141, v141, v142
	v_cvt_pk_bf16_f32 v141, v141, s0
	v_lshl_add_u64 v[142:143], v[128:129], 0, v[136:137]
	global_store_short v[142:143], v141, off
	v_mul_f32_e32 v141, v26, v130
	v_mul_f32_e32 v142, 0xbfb8aa3b, v141
	v_exp_f32_e32 v142, v142
	v_mul_f32_e32 v130, v10, v130
	v_add_f32_e32 v142, 1.0, v142
	v_rcp_f32_e32 v142, v142
	s_nop 0
	v_mul_f32_e32 v141, v141, v142
	v_cvt_pk_bf16_f32 v141, v141, s0
	v_lshl_add_u64 v[142:143], v[128:129], 0, v[134:135]
	global_store_short v[142:143], v141, off
	v_mul_f32_e32 v141, 0xbfb8aa3b, v130
	v_exp_f32_e32 v141, v141
	v_lshl_add_u64 v[128:129], v[128:129], 0, v[132:133]
	v_add_f32_e32 v141, 1.0, v141
	v_rcp_f32_e32 v141, v141
	s_nop 0
	v_mul_f32_e32 v130, v130, v141
	v_cvt_pk_bf16_f32 v130, v130, s0
	global_store_short v[128:129], v130, off
	v_mul_f32_e32 v130, v59, v131
	v_mul_f32_e32 v141, 0xbfb8aa3b, v130
	v_exp_f32_e32 v141, v141
	v_add_u32_e32 v128, 51, v140
	v_ashrrev_i32_e32 v129, 31, v128
	v_lshlrev_b64 v[128:129], 10, v[128:129]
	v_add_f32_e32 v141, 1.0, v141
	v_rcp_f32_e32 v141, v141
	v_lshl_add_u64 v[128:129], s[30:31], 0, v[128:129]
	v_lshl_add_u64 v[142:143], v[128:129], 0, v[138:139]
	v_mul_f32_e32 v130, v130, v141
	v_cvt_pk_bf16_f32 v130, v130, s0
	global_store_short v[142:143], v130, off
	v_mul_f32_e32 v130, v43, v131
	v_mul_f32_e32 v141, 0xbfb8aa3b, v130
	v_exp_f32_e32 v141, v141
	v_lshl_add_u64 v[142:143], v[128:129], 0, v[136:137]
	v_add_f32_e32 v141, 1.0, v141
	v_rcp_f32_e32 v141, v141
	s_nop 0
	v_mul_f32_e32 v130, v130, v141
	v_cvt_pk_bf16_f32 v130, v130, s0
	global_store_short v[142:143], v130, off
	v_mul_f32_e32 v130, v27, v131
	v_mul_f32_e32 v141, 0xbfb8aa3b, v130
	v_exp_f32_e32 v141, v141
	v_lshl_add_u64 v[142:143], v[128:129], 0, v[134:135]
	v_lshl_add_u64 v[128:129], v[128:129], 0, v[132:133]
	v_add_f32_e32 v141, 1.0, v141
	v_rcp_f32_e32 v141, v141
	s_nop 0
	v_mul_f32_e32 v130, v130, v141
	v_cvt_pk_bf16_f32 v130, v130, s0
	global_store_short v[142:143], v130, off
	v_mul_f32_e32 v130, v11, v131
	v_mul_f32_e32 v131, 0xbfb8aa3b, v130
	v_exp_f32_e32 v131, v131
	s_nop 0
	v_add_f32_e32 v131, 1.0, v131
	v_rcp_f32_e32 v131, v131
	s_nop 0
	v_mul_f32_e32 v130, v130, v131
	v_cvt_pk_bf16_f32 v130, v130, s0
	global_store_short v[128:129], v130, off
	v_or_b32_e32 v128, 56, v144
	v_add_u32_e32 v142, s76, v128
	v_lshl_add_u32 v128, v128, 2, s8
	ds_read_b128 v[128:131], v128
	v_ashrrev_i32_e32 v143, 31, v142
	v_lshlrev_b64 v[142:143], 10, v[142:143]
	v_lshl_add_u64 v[142:143], s[30:31], 0, v[142:143]
	s_mov_b64 s[8:9], 0
	s_waitcnt lgkmcnt(0)
; DI u16 f2bf(float a) { return (u16)(pack2(a, 0.f) & 0xffffu); }
; DI int crow(int reg, int g) { return (reg & 3) + 8 * (reg >> 2) + 4 * g; }
; DI float siluf(float x) { return x * __builtin_amdgcn_rcpf(1.f + __expf(-x)); }
; template <bool TR>
; DI void gemm_in_tile(const P& p, int l, int id, char* smem) {
;     ...
; #pragma unroll
;     for (int rb = 0; rb < 2; ++rb) {
; #pragma unroll
;       for (int reg = 0; reg < 16; ++reg) {
;         if ((reg & 7) == 0) asm volatile("" ::: "memory");
;         const int rl = 64 * wr + 32 * rb + crow(reg, g);
;         const int tok = m0 + rl;
;         const float rs = rs_s[rl];
; #pragma unroll
;         for (int cb = 0; cb < 4; ++cb) {
;           const int col = n0 - 3584 + 128 * wc + 32 * cb + li;
;           p.AG[(size_t)tok * 512 + col] = f2bf(siluf(acc[rb][cb][reg] * rs));
;         }
;       }
	v_mul_f32_e32 v141, v60, v128
	v_mul_f32_e32 v146, 0xbfb8aa3b, v141
	v_exp_f32_e32 v146, v146
	s_nop 0
	v_add_f32_e32 v146, 1.0, v146
	v_rcp_f32_e32 v146, v146
	s_nop 0
	v_mul_f32_e32 v141, v141, v146
	v_cvt_pk_bf16_f32 v141, v141, s0
	v_lshl_add_u64 v[146:147], v[142:143], 0, v[138:139]
	global_store_short v[146:147], v141, off
	v_mul_f32_e32 v141, v44, v128
	v_mul_f32_e32 v146, 0xbfb8aa3b, v141
	v_exp_f32_e32 v146, v146
	s_nop 0
	v_add_f32_e32 v146, 1.0, v146
	v_rcp_f32_e32 v146, v146
	s_nop 0
	v_mul_f32_e32 v141, v141, v146
	v_cvt_pk_bf16_f32 v141, v141, s0
	v_lshl_add_u64 v[146:147], v[142:143], 0, v[136:137]
	global_store_short v[146:147], v141, off
	v_mul_f32_e32 v141, v28, v128
	v_mul_f32_e32 v146, 0xbfb8aa3b, v141
	v_exp_f32_e32 v146, v146
	v_mul_f32_e32 v128, v12, v128
	v_add_f32_e32 v146, 1.0, v146
	v_rcp_f32_e32 v146, v146
	s_nop 0
	v_mul_f32_e32 v141, v141, v146
	v_cvt_pk_bf16_f32 v141, v141, s0
	v_lshl_add_u64 v[146:147], v[142:143], 0, v[134:135]
	global_store_short v[146:147], v141, off
	v_mul_f32_e32 v141, 0xbfb8aa3b, v128
	v_exp_f32_e32 v141, v141
	v_lshl_add_u64 v[142:143], v[142:143], 0, v[132:133]
	v_add_f32_e32 v141, 1.0, v141
	v_rcp_f32_e32 v141, v141
	s_nop 0
	v_mul_f32_e32 v128, v128, v141
	v_cvt_pk_bf16_f32 v128, v128, s0
	global_store_short v[142:143], v128, off
	v_mul_f32_e32 v128, v61, v129
	v_mul_f32_e32 v141, 0xbfb8aa3b, v128
	v_exp_f32_e32 v141, v141
	v_add_u32_e32 v142, 57, v140
	v_ashrrev_i32_e32 v143, 31, v142
	v_lshlrev_b64 v[142:143], 10, v[142:143]
	v_add_f32_e32 v141, 1.0, v141
	v_rcp_f32_e32 v141, v141
	v_lshl_add_u64 v[142:143], s[30:31], 0, v[142:143]
	v_lshl_add_u64 v[146:147], v[142:143], 0, v[138:139]
	v_mul_f32_e32 v128, v128, v141
	v_cvt_pk_bf16_f32 v128, v128, s0
	global_store_short v[146:147], v128, off
	v_mul_f32_e32 v128, v45, v129
	v_mul_f32_e32 v141, 0xbfb8aa3b, v128
	v_exp_f32_e32 v141, v141
	v_lshl_add_u64 v[146:147], v[142:143], 0, v[136:137]
	v_add_f32_e32 v141, 1.0, v141
	v_rcp_f32_e32 v141, v141
	s_nop 0
	v_mul_f32_e32 v128, v128, v141
	v_cvt_pk_bf16_f32 v128, v128, s0
	global_store_short v[146:147], v128, off
	v_mul_f32_e32 v128, v29, v129
	v_mul_f32_e32 v141, 0xbfb8aa3b, v128
	v_exp_f32_e32 v141, v141
	v_lshl_add_u64 v[146:147], v[142:143], 0, v[134:135]
	v_add_f32_e32 v141, 1.0, v141
	v_rcp_f32_e32 v141, v141
	s_nop 0
	v_mul_f32_e32 v128, v128, v141
	v_cvt_pk_bf16_f32 v128, v128, s0
	global_store_short v[146:147], v128, off
	v_mul_f32_e32 v128, v13, v129
	v_mul_f32_e32 v129, 0xbfb8aa3b, v128
	v_exp_f32_e32 v129, v129
	s_nop 0
	v_add_f32_e32 v129, 1.0, v129
	v_rcp_f32_e32 v129, v129
	s_nop 0
	v_mul_f32_e32 v128, v128, v129
	v_cvt_pk_bf16_f32 v141, v128, s0
	v_lshl_add_u64 v[128:129], v[142:143], 0, v[132:133]
	global_store_short v[128:129], v141, off
	v_mul_f32_e32 v141, v62, v130
	v_mul_f32_e32 v142, 0xbfb8aa3b, v141
	v_exp_f32_e32 v142, v142
	v_add_u32_e32 v128, 58, v140
	v_ashrrev_i32_e32 v129, 31, v128
	v_lshlrev_b64 v[128:129], 10, v[128:129]
	v_add_f32_e32 v142, 1.0, v142
	v_rcp_f32_e32 v142, v142
	v_lshl_add_u64 v[128:129], s[30:31], 0, v[128:129]
	v_mul_f32_e32 v141, v141, v142
	v_cvt_pk_bf16_f32 v141, v141, s0
	v_lshl_add_u64 v[142:143], v[128:129], 0, v[138:139]
	global_store_short v[142:143], v141, off
	v_mul_f32_e32 v141, v46, v130
	v_mul_f32_e32 v142, 0xbfb8aa3b, v141
	v_exp_f32_e32 v142, v142
	s_nop 0
	v_add_f32_e32 v142, 1.0, v142
	v_rcp_f32_e32 v142, v142
	s_nop 0
	v_mul_f32_e32 v141, v141, v142
	v_cvt_pk_bf16_f32 v141, v141, s0
	v_lshl_add_u64 v[142:143], v[128:129], 0, v[136:137]
	global_store_short v[142:143], v141, off
	v_mul_f32_e32 v141, v30, v130
	v_mul_f32_e32 v142, 0xbfb8aa3b, v141
	v_exp_f32_e32 v142, v142
	v_mul_f32_e32 v130, v14, v130
	v_add_f32_e32 v142, 1.0, v142
	v_rcp_f32_e32 v142, v142
	s_nop 0
	v_mul_f32_e32 v141, v141, v142
	v_cvt_pk_bf16_f32 v141, v141, s0
	v_lshl_add_u64 v[142:143], v[128:129], 0, v[134:135]
	global_store_short v[142:143], v141, off
	v_mul_f32_e32 v141, 0xbfb8aa3b, v130
	v_exp_f32_e32 v141, v141
	v_lshl_add_u64 v[128:129], v[128:129], 0, v[132:133]
	v_add_f32_e32 v141, 1.0, v141
	v_rcp_f32_e32 v141, v141
	s_nop 0
	v_mul_f32_e32 v130, v130, v141
	v_cvt_pk_bf16_f32 v130, v130, s0
	global_store_short v[128:129], v130, off
	v_mul_f32_e32 v130, v63, v131
	v_add_u32_e32 v128, 59, v140
	v_mul_f32_e32 v140, 0xbfb8aa3b, v130
	v_exp_f32_e32 v140, v140
	v_ashrrev_i32_e32 v129, 31, v128
	v_lshlrev_b64 v[128:129], 10, v[128:129]
	v_lshl_add_u64 v[128:129], s[30:31], 0, v[128:129]
	v_add_f32_e32 v140, 1.0, v140
	v_rcp_f32_e32 v140, v140
	v_lshl_add_u64 v[138:139], v[128:129], 0, v[138:139]
	v_lshl_add_u64 v[136:137], v[128:129], 0, v[136:137]
	v_lshl_add_u64 v[134:135], v[128:129], 0, v[134:135]
	v_mul_f32_e32 v130, v130, v140
	v_cvt_pk_bf16_f32 v130, v130, s0
	global_store_short v[138:139], v130, off
	v_mul_f32_e32 v130, v47, v131
	v_mul_f32_e32 v138, 0xbfb8aa3b, v130
	v_exp_f32_e32 v138, v138
	v_lshl_add_u64 v[128:129], v[128:129], 0, v[132:133]
	v_add_f32_e32 v138, 1.0, v138
	v_rcp_f32_e32 v138, v138
	s_nop 0
	v_mul_f32_e32 v130, v130, v138
	v_cvt_pk_bf16_f32 v130, v130, s0
	global_store_short v[136:137], v130, off
	v_mul_f32_e32 v130, v31, v131
	v_mul_f32_e32 v136, 0xbfb8aa3b, v130
	v_exp_f32_e32 v136, v136
	s_nop 0
	v_add_f32_e32 v136, 1.0, v136
	v_rcp_f32_e32 v136, v136
	s_nop 0
	v_mul_f32_e32 v130, v130, v136
	v_cvt_pk_bf16_f32 v130, v130, s0
	global_store_short v[134:135], v130, off
	v_mul_f32_e32 v130, v15, v131
	v_mul_f32_e32 v131, 0xbfb8aa3b, v130
	v_exp_f32_e32 v131, v131
	s_nop 0
	v_add_f32_e32 v131, 1.0, v131
	v_rcp_f32_e32 v131, v131
	s_nop 0
	v_mul_f32_e32 v130, v130, v131
	v_cvt_pk_bf16_f32 v130, v130, s0
	global_store_short v[128:129], v130, off

; template <bool AT>
; DI void gemm_main(f32x16 (&acc)[2][4], const u16* __restrict__ R, int ldr, const u16* __restrict__ Cm, int ldc,
;                   const u16* __restrict__ RT, int ldrt, int K, char* smem, int tid) {
;     ...
;     if (kt + 1 < nk) {
;       const int ks1 = kt + 1;
;       u16* Rs = S0 + (ks1 & 1) * STG;
;       u16* Cs = Rs + 256 * 72;
; #pragma unroll
;       for (int i = 0; i < 4; ++i) {
;         const int cid = tid + NT * i;
;         const int row = cid >> 3, kc = cid & 7;
;         if (AT && ks1 < 8) {
;           const int kr = cid >> 5, tc = cid & 31;
;           *(u32x4*)(Rs + kr * 264 + tc * 8) = rr[i];
;         } else {
;           *(u32x4*)(Rs + row * 72 + kc * 8) = rr[i];
;         }
;         *(u32x4*)(Cs + row * 72 + kc * 8) = cr[i];
;       }
;     }
;     if (kt + 2 < nk) {
;       const int kn = kt + 2;
; #pragma unroll
;       for (int i = 0; i < 4; ++i) {
;         const int cid = tid + NT * i;
;         const int row = cid >> 3, kc = cid & 7;
;         if (AT && kn < 8) {
;           const int kr = cid >> 5, tc = cid & 31;
;           rr[i] = *(const u32x4*)(RT + (size_t)(kn * 64 + kr) * ldrt + tc * 8);
;         } else {
;           rr[i] = *(const u32x4*)(R + (size_t)row * ldr + kn * 64 + kc * 8);
;         }
;         cr[i] = *(const u32x4*)(Cm + (size_t)row * ldc + kn * 64 + kc * 8);
;       }
;     }
;     __builtin_amdgcn_sched_barrier(0x38F);
;     if (kt >= 0) {
;       const u16* Rs = S0 + (kt & 1) * STG;
;       const u16* Cs = Rs + 256 * 72;
;       const u16* RTs = Rs;
; #pragma unroll
;       for (int ks = 0; ks < 4; ++ks) {
;         bf16x8 rf[2];
; #pragma unroll
;         for (int rb = 0; rb < 2; ++rb) {
;           if (AT && kt < 8) {
;             const u16* src = RTs + (16 * ks + 8 * g) * 264 + 64 * wr + 32 * rb + li;
;             bf16x8 t;
; #pragma unroll
;             for (int j = 0; j < 8; ++j) t[j] = (short)src[j * 264];
;             rf[rb] = t;
;           } else {
;             rf[rb] = *(const bf16x8*)(Rs + (64 * wr + 32 * rb + li) * 72 + 16 * ks + 8 * g);
;           }
;         }
; #pragma unroll
;         for (int cb = 0; cb < 4; ++cb) {
;           const bf16x8 cfv = *(const bf16x8*)(Cs + (128 * wc + 32 * cb + li) * 72 + 16 * ks + 8 * g);
; #pragma unroll
;           for (int rb = 0; rb < 2; ++rb) acc[rb][cb] = MFMA(rf[rb], cfv, acc[rb][cb]);
;         }
;       }
;     }
.Lgn_loop:
	ds_read_b128 v[192:195], v190 offset:0
	ds_read_b128 v[220:223], v190 offset:4608
	ds_read_b128 v[232:235], v191 offset:36864
	ds_read_b128 v[236:239], v191 offset:41472
	ds_read_b128 v[240:243], v191 offset:46080
	ds_read_b128 v[244:247], v191 offset:50688
	ds_read_b128 v[224:227], v190 offset:32
	ds_read_b128 v[228:231], v190 offset:4640
	s_waitcnt lgkmcnt(5)
	v_mfma_f32_32x32x16_bf16 v[112:127], v[192:195], v[232:235], v[112:127]
	v_mfma_f32_32x32x16_bf16 v[96:111], v[220:223], v[232:235], v[96:111]
	ds_read_b128 v[232:235], v191 offset:36896
	s_waitcnt vmcnt(0)
	ds_write_b128 v196, v[152:155]
	s_waitcnt lgkmcnt(6)
	v_mfma_f32_32x32x16_bf16 v[80:95], v[192:195], v[236:239], v[80:95]
	v_mfma_f32_32x32x16_bf16 v[64:79], v[220:223], v[236:239], v[64:79]
	ds_read_b128 v[236:239], v191 offset:41504
	ds_write_b128 v196, v[136:139] offset:36864
	s_waitcnt lgkmcnt(7)
	v_mfma_f32_32x32x16_bf16 v[48:63], v[192:195], v[240:243], v[48:63]
	v_mfma_f32_32x32x16_bf16 v[32:47], v[220:223], v[240:243], v[32:47]
	ds_read_b128 v[240:243], v191 offset:46112
	ds_write_b128 v197, v[148:151]
	s_waitcnt lgkmcnt(8)
	v_mfma_f32_32x32x16_bf16 v[16:31], v[192:195], v[244:247], v[16:31]
	v_mfma_f32_32x32x16_bf16 v[0:15], v[220:223], v[244:247], v[0:15]
	ds_read_b128 v[244:247], v191 offset:50720
	ds_write_b128 v197, v[132:135] offset:36864
	ds_read_b128 v[192:195], v190 offset:64
	ds_read_b128 v[220:223], v190 offset:4672
	s_waitcnt lgkmcnt(9)
	v_mfma_f32_32x32x16_bf16 v[112:127], v[224:227], v[232:235], v[112:127]
	v_mfma_f32_32x32x16_bf16 v[96:111], v[228:231], v[232:235], v[96:111]
	ds_read_b128 v[232:235], v191 offset:36928
	ds_write_b128 v249, v[144:147]
	s_waitcnt lgkmcnt(9)
	v_mfma_f32_32x32x16_bf16 v[80:95], v[224:227], v[236:239], v[80:95]
	v_mfma_f32_32x32x16_bf16 v[64:79], v[228:231], v[236:239], v[64:79]
	ds_read_b128 v[236:239], v191 offset:41536
	ds_write_b128 v249, v[128:131] offset:36864
	s_waitcnt lgkmcnt(9)
	v_mfma_f32_32x32x16_bf16 v[48:63], v[224:227], v[240:243], v[48:63]
	v_mfma_f32_32x32x16_bf16 v[32:47], v[228:231], v[240:243], v[32:47]
	ds_read_b128 v[240:243], v191 offset:46144
	ds_write_b128 v250, v[140:143]
	s_waitcnt lgkmcnt(9)
	v_mfma_f32_32x32x16_bf16 v[16:31], v[224:227], v[244:247], v[16:31]
	v_mfma_f32_32x32x16_bf16 v[0:15], v[228:231], v[244:247], v[0:15]
	ds_read_b128 v[244:247], v191 offset:50752
	ds_write_b128 v250, v[156:159] offset:36864
	ds_read_b128 v[224:227], v190 offset:96
	ds_read_b128 v[228:231], v190 offset:4704
	s_waitcnt lgkmcnt(9)
	v_mfma_f32_32x32x16_bf16 v[112:127], v[192:195], v[232:235], v[112:127]
	v_mfma_f32_32x32x16_bf16 v[96:111], v[220:223], v[232:235], v[96:111]
	ds_read_b128 v[232:235], v191 offset:36960
	v_subrev_u32_e32 v196, 0x12000, v196
	global_load_dwordx4 v[152:155], v[174:175], off
	v_lshl_add_u64 v[174:175], v[174:175], 0, s[58:59]
	s_waitcnt lgkmcnt(8)
	v_mfma_f32_32x32x16_bf16 v[80:95], v[192:195], v[236:239], v[80:95]
	v_mfma_f32_32x32x16_bf16 v[64:79], v[220:223], v[236:239], v[64:79]
	ds_read_b128 v[236:239], v191 offset:41568
	v_subrev_u32_e32 v197, 0x12000, v197
	global_load_dwordx4 v[136:139], v[166:167], off
	v_lshl_add_u64 v[166:167], v[166:167], 0, s[58:59]
	s_waitcnt lgkmcnt(7)
	v_mfma_f32_32x32x16_bf16 v[48:63], v[192:195], v[240:243], v[48:63]
	v_mfma_f32_32x32x16_bf16 v[32:47], v[220:223], v[240:243], v[32:47]
	ds_read_b128 v[240:243], v191 offset:46176
	v_subrev_u32_e32 v249, 0x12000, v249
	global_load_dwordx4 v[148:151], v[172:173], off
	v_lshl_add_u64 v[172:173], v[172:173], 0, s[58:59]
	s_waitcnt lgkmcnt(6)
	v_mfma_f32_32x32x16_bf16 v[16:31], v[192:195], v[244:247], v[16:31]
	v_mfma_f32_32x32x16_bf16 v[0:15], v[220:223], v[244:247], v[0:15]
	ds_read_b128 v[244:247], v191 offset:50784
	v_subrev_u32_e32 v250, 0x12000, v250
	global_load_dwordx4 v[132:135], v[164:165], off
	v_lshl_add_u64 v[164:165], v[164:165], 0, s[58:59]
	v_add_u32_e32 v190, 0x12000, v190
	v_add_u32_e32 v191, 0x12000, v191
	s_waitcnt lgkmcnt(3)
	v_mfma_f32_32x32x16_bf16 v[112:127], v[224:227], v[232:235], v[112:127]
	v_mfma_f32_32x32x16_bf16 v[96:111], v[228:231], v[232:235], v[96:111]
	global_load_dwordx4 v[144:147], v[170:171], off
	v_lshl_add_u64 v[170:171], v[170:171], 0, s[58:59]
	s_waitcnt lgkmcnt(2)
	v_mfma_f32_32x32x16_bf16 v[80:95], v[224:227], v[236:239], v[80:95]
	v_mfma_f32_32x32x16_bf16 v[64:79], v[228:231], v[236:239], v[64:79]
	global_load_dwordx4 v[128:131], v[162:163], off
	v_lshl_add_u64 v[162:163], v[162:163], 0, s[58:59]
	s_waitcnt lgkmcnt(1)
	v_mfma_f32_32x32x16_bf16 v[48:63], v[224:227], v[240:243], v[48:63]
	v_mfma_f32_32x32x16_bf16 v[32:47], v[228:231], v[240:243], v[32:47]
	global_load_dwordx4 v[140:143], v[168:169], off
	v_lshl_add_u64 v[168:169], v[168:169], 0, s[58:59]
	s_waitcnt lgkmcnt(0)
	v_mfma_f32_32x32x16_bf16 v[16:31], v[224:227], v[244:247], v[16:31]
	v_mfma_f32_32x32x16_bf16 v[0:15], v[228:231], v[244:247], v[0:15]
	global_load_dwordx4 v[156:159], v[160:161], off
	v_lshl_add_u64 v[160:161], v[160:161], 0, s[58:59]
	s_waitcnt lgkmcnt(0)
	s_barrier
; template <bool AT>
; DI void gemm_main(f32x16 (&acc)[2][4], const u16* __restrict__ R, int ldr, const u16* __restrict__ Cm, int ldc,
;                   const u16* __restrict__ RT, int ldrt, int K, char* smem, int tid) {
;     ...
;     if (kt + 1 < nk) {
;       const int ks1 = kt + 1;
;       u16* Rs = S0 + (ks1 & 1) * STG;
;       u16* Cs = Rs + 256 * 72;
; #pragma unroll
;       for (int i = 0; i < 4; ++i) {
;         const int cid = tid + NT * i;
;         const int row = cid >> 3, kc = cid & 7;
;         if (AT && ks1 < 8) {
;           const int kr = cid >> 5, tc = cid & 31;
;           *(u32x4*)(Rs + kr * 264 + tc * 8) = rr[i];
;         } else {
;           *(u32x4*)(Rs + row * 72 + kc * 8) = rr[i];
;         }
;         *(u32x4*)(Cs + row * 72 + kc * 8) = cr[i];
;       }
;     }
;     if (kt + 2 < nk) {
;       const int kn = kt + 2;
; #pragma unroll
;       for (int i = 0; i < 4; ++i) {
;         const int cid = tid + NT * i;
;         const int row = cid >> 3, kc = cid & 7;
;         if (AT && kn < 8) {
;           const int kr = cid >> 5, tc = cid & 31;
;           rr[i] = *(const u32x4*)(RT + (size_t)(kn * 64 + kr) * ldrt + tc * 8);
;         } else {
;           rr[i] = *(const u32x4*)(R + (size_t)row * ldr + kn * 64 + kc * 8);
;         }
;         cr[i] = *(const u32x4*)(Cm + (size_t)row * ldc + kn * 64 + kc * 8);
;       }
;     }
;     __builtin_amdgcn_sched_barrier(0x38F);
;     if (kt >= 0) {
;       const u16* Rs = S0 + (kt & 1) * STG;
;       const u16* Cs = Rs + 256 * 72;
;       const u16* RTs = Rs;
; #pragma unroll
;       for (int ks = 0; ks < 4; ++ks) {
;         bf16x8 rf[2];
; #pragma unroll
;         for (int rb = 0; rb < 2; ++rb) {
;           if (AT && kt < 8) {
;             const u16* src = RTs + (16 * ks + 8 * g) * 264 + 64 * wr + 32 * rb + li;
;             bf16x8 t;
; #pragma unroll
;             for (int j = 0; j < 8; ++j) t[j] = (short)src[j * 264];
;             rf[rb] = t;
;           } else {
;             rf[rb] = *(const bf16x8*)(Rs + (64 * wr + 32 * rb + li) * 72 + 16 * ks + 8 * g);
;           }
;         }
; #pragma unroll
;         for (int cb = 0; cb < 4; ++cb) {
;           const bf16x8 cfv = *(const bf16x8*)(Cs + (128 * wc + 32 * cb + li) * 72 + 16 * ks + 8 * g);
; #pragma unroll
;           for (int rb = 0; rb < 2; ++rb) acc[rb][cb] = MFMA(rf[rb], cfv, acc[rb][cb]);
;         }
;       }
;     }
	ds_read_b128 v[192:195], v190 offset:0
	ds_read_b128 v[220:223], v190 offset:4608
	ds_read_b128 v[232:235], v191 offset:36864
	ds_read_b128 v[236:239], v191 offset:41472
	ds_read_b128 v[240:243], v191 offset:46080
	ds_read_b128 v[244:247], v191 offset:50688
	ds_read_b128 v[224:227], v190 offset:32
	ds_read_b128 v[228:231], v190 offset:4640
	s_waitcnt lgkmcnt(5)
	v_mfma_f32_32x32x16_bf16 v[112:127], v[192:195], v[232:235], v[112:127]
	v_mfma_f32_32x32x16_bf16 v[96:111], v[220:223], v[232:235], v[96:111]
	ds_read_b128 v[232:235], v191 offset:36896
	s_waitcnt vmcnt(0)
	ds_write_b128 v196, v[152:155]
	s_waitcnt lgkmcnt(6)
	v_mfma_f32_32x32x16_bf16 v[80:95], v[192:195], v[236:239], v[80:95]
	v_mfma_f32_32x32x16_bf16 v[64:79], v[220:223], v[236:239], v[64:79]
	ds_read_b128 v[236:239], v191 offset:41504
	ds_write_b128 v196, v[136:139] offset:36864
	s_waitcnt lgkmcnt(7)
	v_mfma_f32_32x32x16_bf16 v[48:63], v[192:195], v[240:243], v[48:63]
	v_mfma_f32_32x32x16_bf16 v[32:47], v[220:223], v[240:243], v[32:47]
	ds_read_b128 v[240:243], v191 offset:46112
	ds_write_b128 v197, v[148:151]
	s_waitcnt lgkmcnt(8)
	v_mfma_f32_32x32x16_bf16 v[16:31], v[192:195], v[244:247], v[16:31]
	v_mfma_f32_32x32x16_bf16 v[0:15], v[220:223], v[244:247], v[0:15]
	ds_read_b128 v[244:247], v191 offset:50720
	ds_write_b128 v197, v[132:135] offset:36864
	ds_read_b128 v[192:195], v190 offset:64
	ds_read_b128 v[220:223], v190 offset:4672
	s_waitcnt lgkmcnt(9)
	v_mfma_f32_32x32x16_bf16 v[112:127], v[224:227], v[232:235], v[112:127]
	v_mfma_f32_32x32x16_bf16 v[96:111], v[228:231], v[232:235], v[96:111]
	ds_read_b128 v[232:235], v191 offset:36928
	ds_write_b128 v249, v[144:147]
	s_waitcnt lgkmcnt(9)
	v_mfma_f32_32x32x16_bf16 v[80:95], v[224:227], v[236:239], v[80:95]
	v_mfma_f32_32x32x16_bf16 v[64:79], v[228:231], v[236:239], v[64:79]
	ds_read_b128 v[236:239], v191 offset:41536
	ds_write_b128 v249, v[128:131] offset:36864
	s_waitcnt lgkmcnt(9)
	v_mfma_f32_32x32x16_bf16 v[48:63], v[224:227], v[240:243], v[48:63]
	v_mfma_f32_32x32x16_bf16 v[32:47], v[228:231], v[240:243], v[32:47]
	ds_read_b128 v[240:243], v191 offset:46144
	ds_write_b128 v250, v[140:143]
	s_waitcnt lgkmcnt(9)
	v_mfma_f32_32x32x16_bf16 v[16:31], v[224:227], v[244:247], v[16:31]
	v_mfma_f32_32x32x16_bf16 v[0:15], v[228:231], v[244:247], v[0:15]
	ds_read_b128 v[244:247], v191 offset:50752
	ds_write_b128 v250, v[156:159] offset:36864
	ds_read_b128 v[224:227], v190 offset:96
	ds_read_b128 v[228:231], v190 offset:4704
	s_waitcnt lgkmcnt(9)
	v_mfma_f32_32x32x16_bf16 v[112:127], v[192:195], v[232:235], v[112:127]
	v_mfma_f32_32x32x16_bf16 v[96:111], v[220:223], v[232:235], v[96:111]
	ds_read_b128 v[232:235], v191 offset:36960
	v_add_u32_e32 v196, 0x12000, v196
	global_load_dwordx4 v[152:155], v[174:175], off
	v_lshl_add_u64 v[174:175], v[174:175], 0, s[58:59]
	s_waitcnt lgkmcnt(8)
	v_mfma_f32_32x32x16_bf16 v[80:95], v[192:195], v[236:239], v[80:95]
	v_mfma_f32_32x32x16_bf16 v[64:79], v[220:223], v[236:239], v[64:79]
	ds_read_b128 v[236:239], v191 offset:41568
	v_add_u32_e32 v197, 0x12000, v197
	global_load_dwordx4 v[136:139], v[166:167], off
	v_lshl_add_u64 v[166:167], v[166:167], 0, s[58:59]
	s_waitcnt lgkmcnt(7)
	v_mfma_f32_32x32x16_bf16 v[48:63], v[192:195], v[240:243], v[48:63]
	v_mfma_f32_32x32x16_bf16 v[32:47], v[220:223], v[240:243], v[32:47]
	ds_read_b128 v[240:243], v191 offset:46176
	v_add_u32_e32 v249, 0x12000, v249
	global_load_dwordx4 v[148:151], v[172:173], off
	v_lshl_add_u64 v[172:173], v[172:173], 0, s[58:59]
	s_waitcnt lgkmcnt(6)
	v_mfma_f32_32x32x16_bf16 v[16:31], v[192:195], v[244:247], v[16:31]
	v_mfma_f32_32x32x16_bf16 v[0:15], v[220:223], v[244:247], v[0:15]
	ds_read_b128 v[244:247], v191 offset:50784
	v_add_u32_e32 v250, 0x12000, v250
	global_load_dwordx4 v[132:135], v[164:165], off
	v_lshl_add_u64 v[164:165], v[164:165], 0, s[58:59]
	v_subrev_u32_e32 v190, 0x12000, v190
	v_subrev_u32_e32 v191, 0x12000, v191
	s_waitcnt lgkmcnt(3)
	v_mfma_f32_32x32x16_bf16 v[112:127], v[224:227], v[232:235], v[112:127]
	v_mfma_f32_32x32x16_bf16 v[96:111], v[228:231], v[232:235], v[96:111]
	global_load_dwordx4 v[144:147], v[170:171], off
	v_lshl_add_u64 v[170:171], v[170:171], 0, s[58:59]
	s_waitcnt lgkmcnt(2)
	v_mfma_f32_32x32x16_bf16 v[80:95], v[224:227], v[236:239], v[80:95]
	v_mfma_f32_32x32x16_bf16 v[64:79], v[228:231], v[236:239], v[64:79]
	global_load_dwordx4 v[128:131], v[162:163], off
	v_lshl_add_u64 v[162:163], v[162:163], 0, s[58:59]
	s_waitcnt lgkmcnt(1)
	v_mfma_f32_32x32x16_bf16 v[48:63], v[224:227], v[240:243], v[48:63]
	v_mfma_f32_32x32x16_bf16 v[32:47], v[228:231], v[240:243], v[32:47]
	global_load_dwordx4 v[140:143], v[168:169], off
	v_lshl_add_u64 v[168:169], v[168:169], 0, s[58:59]
	s_waitcnt lgkmcnt(0)
	v_mfma_f32_32x32x16_bf16 v[16:31], v[224:227], v[244:247], v[16:31]
	v_mfma_f32_32x32x16_bf16 v[0:15], v[228:231], v[244:247], v[0:15]
	global_load_dwordx4 v[156:159], v[160:161], off
	v_lshl_add_u64 v[160:161], v[160:161], 0, s[58:59]
	s_waitcnt lgkmcnt(0)
	s_barrier
	s_add_i32 s64, s64, -1
	s_cmp_lg_u32 s64, 0
	s_cbranch_scc1 .Lgn_loop
; template <bool AT>
; DI void gemm_main(f32x16 (&acc)[2][4], const u16* __restrict__ R, int ldr, const u16* __restrict__ Cm, int ldc,
;                   const u16* __restrict__ RT, int ldrt, int K, char* smem, int tid) {
;     ...
;   for (int kt = -1; kt < nk; ++kt) {
;     if (kt + 1 < nk) {
;       const int ks1 = kt + 1;
;       u16* Rs = S0 + (ks1 & 1) * STG;
;       u16* Cs = Rs + 256 * 72;
; #pragma unroll
;       for (int i = 0; i < 4; ++i) {
;         const int cid = tid + NT * i;
;         const int row = cid >> 3, kc = cid & 7;
;         if (AT && ks1 < 8) {
;           const int kr = cid >> 5, tc = cid & 31;
;           *(u32x4*)(Rs + kr * 264 + tc * 8) = rr[i];
;         } else {
;           *(u32x4*)(Rs + row * 72 + kc * 8) = rr[i];
;         }
;         *(u32x4*)(Cs + row * 72 + kc * 8) = cr[i];
;       }
;     }
;     if (kt + 2 < nk) {
;       const int kn = kt + 2;
; #pragma unroll
;       for (int i = 0; i < 4; ++i) {
;         const int cid = tid + NT * i;
;         const int row = cid >> 3, kc = cid & 7;
;         if (AT && kn < 8) {
;           const int kr = cid >> 5, tc = cid & 31;
;           rr[i] = *(const u32x4*)(RT + (size_t)(kn * 64 + kr) * ldrt + tc * 8);
;         } else {
;           rr[i] = *(const u32x4*)(R + (size_t)row * ldr + kn * 64 + kc * 8);
;         }
;         cr[i] = *(const u32x4*)(Cm + (size_t)row * ldc + kn * 64 + kc * 8);
;       }
;     }
;     __builtin_amdgcn_sched_barrier(0x38F);
;     if (kt >= 0) {
;       const u16* Rs = S0 + (kt & 1) * STG;
;       const u16* Cs = Rs + 256 * 72;
;       const u16* RTs = Rs;
; #pragma unroll
;       for (int ks = 0; ks < 4; ++ks) {
;         bf16x8 rf[2];
; #pragma unroll
;         for (int rb = 0; rb < 2; ++rb) {
;           if (AT && kt < 8) {
;             const u16* src = RTs + (16 * ks + 8 * g) * 264 + 64 * wr + 32 * rb + li;
;             bf16x8 t;
; #pragma unroll
;             for (int j = 0; j < 8; ++j) t[j] = (short)src[j * 264];
;             rf[rb] = t;
;           } else {
;             rf[rb] = *(const bf16x8*)(Rs + (64 * wr + 32 * rb + li) * 72 + 16 * ks + 8 * g);
;           }
;         }
; #pragma unroll
;         for (int cb = 0; cb < 4; ++cb) {
;           const bf16x8 cfv = *(const bf16x8*)(Cs + (128 * wc + 32 * cb + li) * 72 + 16 * ks + 8 * g);
; #pragma unroll
;           for (int rb = 0; rb < 2; ++rb) acc[rb][cb] = MFMA(rf[rb], cfv, acc[rb][cb]);
	ds_read_b128 v[192:195], v190 offset:0
	ds_read_b128 v[220:223], v190 offset:4608
	ds_read_b128 v[232:235], v191 offset:36864
	ds_read_b128 v[236:239], v191 offset:41472
	ds_read_b128 v[240:243], v191 offset:46080
	ds_read_b128 v[244:247], v191 offset:50688
	ds_read_b128 v[224:227], v190 offset:32
	ds_read_b128 v[228:231], v190 offset:4640
	s_waitcnt lgkmcnt(5)
	v_mfma_f32_32x32x16_bf16 v[112:127], v[192:195], v[232:235], v[112:127]
	v_mfma_f32_32x32x16_bf16 v[96:111], v[220:223], v[232:235], v[96:111]
	ds_read_b128 v[232:235], v191 offset:36896
	s_waitcnt vmcnt(0)
	ds_write_b128 v196, v[152:155]
	s_waitcnt lgkmcnt(6)
	v_mfma_f32_32x32x16_bf16 v[80:95], v[192:195], v[236:239], v[80:95]
	v_mfma_f32_32x32x16_bf16 v[64:79], v[220:223], v[236:239], v[64:79]
	ds_read_b128 v[236:239], v191 offset:41504
	ds_write_b128 v196, v[136:139] offset:36864
	s_waitcnt lgkmcnt(7)
	v_mfma_f32_32x32x16_bf16 v[48:63], v[192:195], v[240:243], v[48:63]
	v_mfma_f32_32x32x16_bf16 v[32:47], v[220:223], v[240:243], v[32:47]
	ds_read_b128 v[240:243], v191 offset:46112
	ds_write_b128 v197, v[148:151]
	s_waitcnt lgkmcnt(8)
	v_mfma_f32_32x32x16_bf16 v[16:31], v[192:195], v[244:247], v[16:31]
	v_mfma_f32_32x32x16_bf16 v[0:15], v[220:223], v[244:247], v[0:15]
	ds_read_b128 v[244:247], v191 offset:50720
	ds_write_b128 v197, v[132:135] offset:36864
	ds_read_b128 v[192:195], v190 offset:64
	ds_read_b128 v[220:223], v190 offset:4672
	s_waitcnt lgkmcnt(9)
	v_mfma_f32_32x32x16_bf16 v[112:127], v[224:227], v[232:235], v[112:127]
	v_mfma_f32_32x32x16_bf16 v[96:111], v[228:231], v[232:235], v[96:111]
	ds_read_b128 v[232:235], v191 offset:36928
	ds_write_b128 v249, v[144:147]
	s_waitcnt lgkmcnt(9)
	v_mfma_f32_32x32x16_bf16 v[80:95], v[224:227], v[236:239], v[80:95]
	v_mfma_f32_32x32x16_bf16 v[64:79], v[228:231], v[236:239], v[64:79]
	ds_read_b128 v[236:239], v191 offset:41536
	ds_write_b128 v249, v[128:131] offset:36864
	s_waitcnt lgkmcnt(9)
	v_mfma_f32_32x32x16_bf16 v[48:63], v[224:227], v[240:243], v[48:63]
	v_mfma_f32_32x32x16_bf16 v[32:47], v[228:231], v[240:243], v[32:47]
	ds_read_b128 v[240:243], v191 offset:46144
	ds_write_b128 v250, v[140:143]
	s_waitcnt lgkmcnt(9)
	v_mfma_f32_32x32x16_bf16 v[16:31], v[224:227], v[244:247], v[16:31]
	v_mfma_f32_32x32x16_bf16 v[0:15], v[228:231], v[244:247], v[0:15]
	ds_read_b128 v[244:247], v191 offset:50752
	ds_write_b128 v250, v[156:159] offset:36864
	ds_read_b128 v[224:227], v190 offset:96
	ds_read_b128 v[228:231], v190 offset:4704
	s_waitcnt lgkmcnt(9)
	v_mfma_f32_32x32x16_bf16 v[112:127], v[192:195], v[232:235], v[112:127]
	v_mfma_f32_32x32x16_bf16 v[96:111], v[220:223], v[232:235], v[96:111]
	ds_read_b128 v[232:235], v191 offset:36960
	v_subrev_u32_e32 v196, 0x12000, v196
	s_waitcnt lgkmcnt(8)
	v_mfma_f32_32x32x16_bf16 v[80:95], v[192:195], v[236:239], v[80:95]
	v_mfma_f32_32x32x16_bf16 v[64:79], v[220:223], v[236:239], v[64:79]
	ds_read_b128 v[236:239], v191 offset:41568
	v_subrev_u32_e32 v197, 0x12000, v197
	s_waitcnt lgkmcnt(7)
	v_mfma_f32_32x32x16_bf16 v[48:63], v[192:195], v[240:243], v[48:63]
	v_mfma_f32_32x32x16_bf16 v[32:47], v[220:223], v[240:243], v[32:47]
	ds_read_b128 v[240:243], v191 offset:46176
	v_subrev_u32_e32 v249, 0x12000, v249
	s_waitcnt lgkmcnt(6)
	v_mfma_f32_32x32x16_bf16 v[16:31], v[192:195], v[244:247], v[16:31]
	v_mfma_f32_32x32x16_bf16 v[0:15], v[220:223], v[244:247], v[0:15]
	ds_read_b128 v[244:247], v191 offset:50784
	v_subrev_u32_e32 v250, 0x12000, v250
	v_add_u32_e32 v190, 0x12000, v190
	v_add_u32_e32 v191, 0x12000, v191
	s_waitcnt lgkmcnt(3)
	v_mfma_f32_32x32x16_bf16 v[112:127], v[224:227], v[232:235], v[112:127]
	v_mfma_f32_32x32x16_bf16 v[96:111], v[228:231], v[232:235], v[96:111]
	s_waitcnt lgkmcnt(2)
	v_mfma_f32_32x32x16_bf16 v[80:95], v[224:227], v[236:239], v[80:95]
	v_mfma_f32_32x32x16_bf16 v[64:79], v[228:231], v[236:239], v[64:79]
	s_waitcnt lgkmcnt(1)
	v_mfma_f32_32x32x16_bf16 v[48:63], v[224:227], v[240:243], v[48:63]
	v_mfma_f32_32x32x16_bf16 v[32:47], v[228:231], v[240:243], v[32:47]
	s_waitcnt lgkmcnt(0)
	v_mfma_f32_32x32x16_bf16 v[16:31], v[224:227], v[244:247], v[16:31]
	v_mfma_f32_32x32x16_bf16 v[0:15], v[228:231], v[244:247], v[0:15]
	s_waitcnt lgkmcnt(0)
	s_barrier
	ds_read_b128 v[192:195], v190 offset:0
	ds_read_b128 v[220:223], v190 offset:4608
	ds_read_b128 v[232:235], v191 offset:36864
	ds_read_b128 v[236:239], v191 offset:41472
	ds_read_b128 v[240:243], v191 offset:46080
	ds_read_b128 v[244:247], v191 offset:50688
	ds_read_b128 v[224:227], v190 offset:32
	ds_read_b128 v[228:231], v190 offset:4640
	s_waitcnt lgkmcnt(5)
	v_mfma_f32_32x32x16_bf16 v[112:127], v[192:195], v[232:235], v[112:127]
	v_mfma_f32_32x32x16_bf16 v[96:111], v[220:223], v[232:235], v[96:111]
	ds_read_b128 v[232:235], v191 offset:36896
	s_waitcnt lgkmcnt(5)
	v_mfma_f32_32x32x16_bf16 v[80:95], v[192:195], v[236:239], v[80:95]
	v_mfma_f32_32x32x16_bf16 v[64:79], v[220:223], v[236:239], v[64:79]
	ds_read_b128 v[236:239], v191 offset:41504
	s_waitcnt lgkmcnt(5)
	v_mfma_f32_32x32x16_bf16 v[48:63], v[192:195], v[240:243], v[48:63]
	v_mfma_f32_32x32x16_bf16 v[32:47], v[220:223], v[240:243], v[32:47]
	ds_read_b128 v[240:243], v191 offset:46112
	s_waitcnt lgkmcnt(5)
	v_mfma_f32_32x32x16_bf16 v[16:31], v[192:195], v[244:247], v[16:31]
	v_mfma_f32_32x32x16_bf16 v[0:15], v[220:223], v[244:247], v[0:15]
	ds_read_b128 v[244:247], v191 offset:50720
	ds_read_b128 v[192:195], v190 offset:64
	ds_read_b128 v[220:223], v190 offset:4672
	s_waitcnt lgkmcnt(5)
	v_mfma_f32_32x32x16_bf16 v[112:127], v[224:227], v[232:235], v[112:127]
	v_mfma_f32_32x32x16_bf16 v[96:111], v[228:231], v[232:235], v[96:111]
	ds_read_b128 v[232:235], v191 offset:36928
	s_waitcnt lgkmcnt(5)
; template <bool AT>
; DI void gemm_main(f32x16 (&acc)[2][4], const u16* __restrict__ R, int ldr, const u16* __restrict__ Cm, int ldc,
;                   const u16* __restrict__ RT, int ldrt, int K, char* smem, int tid) {
;     ...
;   for (int kt = -1; kt < nk; ++kt) {
;     if (kt + 1 < nk) {
;       const int ks1 = kt + 1;
;       u16* Rs = S0 + (ks1 & 1) * STG;
;       u16* Cs = Rs + 256 * 72;
; #pragma unroll
;       for (int i = 0; i < 4; ++i) {
;         const int cid = tid + NT * i;
;         const int row = cid >> 3, kc = cid & 7;
;         if (AT && ks1 < 8) {
;           const int kr = cid >> 5, tc = cid & 31;
;           *(u32x4*)(Rs + kr * 264 + tc * 8) = rr[i];
;         } else {
;           *(u32x4*)(Rs + row * 72 + kc * 8) = rr[i];
;         }
;         *(u32x4*)(Cs + row * 72 + kc * 8) = cr[i];
;       }
;     }
;     if (kt + 2 < nk) {
;       const int kn = kt + 2;
; #pragma unroll
;       for (int i = 0; i < 4; ++i) {
;         const int cid = tid + NT * i;
;         const int row = cid >> 3, kc = cid & 7;
;         if (AT && kn < 8) {
;           const int kr = cid >> 5, tc = cid & 31;
;           rr[i] = *(const u32x4*)(RT + (size_t)(kn * 64 + kr) * ldrt + tc * 8);
;         } else {
;           rr[i] = *(const u32x4*)(R + (size_t)row * ldr + kn * 64 + kc * 8);
;         }
;         cr[i] = *(const u32x4*)(Cm + (size_t)row * ldc + kn * 64 + kc * 8);
;       }
;     }
;     __builtin_amdgcn_sched_barrier(0x38F);
;     if (kt >= 0) {
;       const u16* Rs = S0 + (kt & 1) * STG;
;       const u16* Cs = Rs + 256 * 72;
;       const u16* RTs = Rs;
; #pragma unroll
;       for (int ks = 0; ks < 4; ++ks) {
;         bf16x8 rf[2];
; #pragma unroll
;         for (int rb = 0; rb < 2; ++rb) {
;           if (AT && kt < 8) {
;             const u16* src = RTs + (16 * ks + 8 * g) * 264 + 64 * wr + 32 * rb + li;
;             bf16x8 t;
; #pragma unroll
;             for (int j = 0; j < 8; ++j) t[j] = (short)src[j * 264];
;             rf[rb] = t;
;           } else {
;             rf[rb] = *(const bf16x8*)(Rs + (64 * wr + 32 * rb + li) * 72 + 16 * ks + 8 * g);
;           }
;         }
; #pragma unroll
;         for (int cb = 0; cb < 4; ++cb) {
;           const bf16x8 cfv = *(const bf16x8*)(Cs + (128 * wc + 32 * cb + li) * 72 + 16 * ks + 8 * g);
; #pragma unroll
;           for (int rb = 0; rb < 2; ++rb) acc[rb][cb] = MFMA(rf[rb], cfv, acc[rb][cb]);
	v_mfma_f32_32x32x16_bf16 v[80:95], v[224:227], v[236:239], v[80:95]
	v_mfma_f32_32x32x16_bf16 v[64:79], v[228:231], v[236:239], v[64:79]
	ds_read_b128 v[236:239], v191 offset:41536
	s_waitcnt lgkmcnt(5)
	v_mfma_f32_32x32x16_bf16 v[48:63], v[224:227], v[240:243], v[48:63]
	v_mfma_f32_32x32x16_bf16 v[32:47], v[228:231], v[240:243], v[32:47]
	ds_read_b128 v[240:243], v191 offset:46144
	s_waitcnt lgkmcnt(5)
	v_mfma_f32_32x32x16_bf16 v[16:31], v[224:227], v[244:247], v[16:31]
	v_mfma_f32_32x32x16_bf16 v[0:15], v[228:231], v[244:247], v[0:15]
	ds_read_b128 v[244:247], v191 offset:50752
	ds_read_b128 v[224:227], v190 offset:96
	ds_read_b128 v[228:231], v190 offset:4704
	s_waitcnt lgkmcnt(5)
	v_mfma_f32_32x32x16_bf16 v[112:127], v[192:195], v[232:235], v[112:127]
	v_mfma_f32_32x32x16_bf16 v[96:111], v[220:223], v[232:235], v[96:111]
	ds_read_b128 v[232:235], v191 offset:36960
	v_add_u32_e32 v196, 0x12000, v196
	s_waitcnt lgkmcnt(5)
	v_mfma_f32_32x32x16_bf16 v[80:95], v[192:195], v[236:239], v[80:95]
	v_mfma_f32_32x32x16_bf16 v[64:79], v[220:223], v[236:239], v[64:79]
	ds_read_b128 v[236:239], v191 offset:41568
	v_add_u32_e32 v197, 0x12000, v197
	s_waitcnt lgkmcnt(5)
	v_mfma_f32_32x32x16_bf16 v[48:63], v[192:195], v[240:243], v[48:63]
	v_mfma_f32_32x32x16_bf16 v[32:47], v[220:223], v[240:243], v[32:47]
	ds_read_b128 v[240:243], v191 offset:46176
	v_add_u32_e32 v249, 0x12000, v249
	s_waitcnt lgkmcnt(5)
	v_mfma_f32_32x32x16_bf16 v[16:31], v[192:195], v[244:247], v[16:31]
	v_mfma_f32_32x32x16_bf16 v[0:15], v[220:223], v[244:247], v[0:15]
	ds_read_b128 v[244:247], v191 offset:50784
	v_add_u32_e32 v250, 0x12000, v250
	v_subrev_u32_e32 v190, 0x12000, v190
	v_subrev_u32_e32 v191, 0x12000, v191
	s_waitcnt lgkmcnt(3)
	v_mfma_f32_32x32x16_bf16 v[112:127], v[224:227], v[232:235], v[112:127]
	v_mfma_f32_32x32x16_bf16 v[96:111], v[228:231], v[232:235], v[96:111]
	s_waitcnt lgkmcnt(2)
	v_mfma_f32_32x32x16_bf16 v[80:95], v[224:227], v[236:239], v[80:95]
	v_mfma_f32_32x32x16_bf16 v[64:79], v[228:231], v[236:239], v[64:79]
	s_waitcnt lgkmcnt(1)
	v_mfma_f32_32x32x16_bf16 v[48:63], v[224:227], v[240:243], v[48:63]
	v_mfma_f32_32x32x16_bf16 v[32:47], v[228:231], v[240:243], v[32:47]
	s_waitcnt lgkmcnt(0)
	v_mfma_f32_32x32x16_bf16 v[16:31], v[224:227], v[244:247], v[16:31]
	v_mfma_f32_32x32x16_bf16 v[0:15], v[228:231], v[244:247], v[0:15]
	s_waitcnt lgkmcnt(0)
	s_barrier
	s_nop 7
	v_mov_b32_e32 v162, s56
	s_lshl_b32 s9, s75, 4
	s_and_b32 s9, s9, 0x200
	s_add_i32 s9, s8, s9
	s_addk_i32 s9, 0xf400
	v_lshrrev_b32_e32 v128, 3, v177
	v_and_b32_e32 v163, 4, v128
	v_add_u32_e32 v130, s9, v178
	s_movk_i32 s9, 0x4080
	v_add_u32_e32 v132, s8, v178
	s_add_i32 s8, 0, 0x24000
	v_lshl_add_u32 v128, v176, 2, s8
	ds_read_b32 v164, v128
	v_mov_b64_e32 v[128:129], s[28:29]
	v_mad_i64_i32 v[128:129], s[10:11], v130, s9, v[128:129]
	s_movk_i32 s9, 0x1f9f
	v_or_b32_e32 v133, s56, v176
	v_bitop3_b32 v134, v176, s9, v162 bitop3:0xc8
	v_mov_b64_e32 v[130:131], s[38:39]
	s_and_b64 s[10:11], s[6:7], exec
	s_movk_i32 s9, 0x4040
	v_mad_i64_i32 v[130:131], s[10:11], v132, s67, v[130:131]
	v_cndmask_b32_e64 v132, v134, v133, s[6:7]
	s_cselect_b32 s9, s9, 0x2040
	v_cndmask_b32_e64 v129, v129, v131, s[6:7]
	v_cndmask_b32_e64 v128, v128, v130, s[6:7]
	v_lshlrev_b32_e32 v188, 1, v132
	v_mul_u32_u24_e32 v130, s9, v163
	v_lshl_add_u64 v[138:139], v[128:129], 0, v[188:189]
	s_waitcnt lgkmcnt(0)
	v_mul_f32_e32 v112, v112, v164
	v_lshlrev_b32_e32 v188, 1, v130
	v_cvt_pk_bf16_f32 v112, v112, s0
	v_lshl_add_u64 v[130:131], v[138:139], 0, v[188:189]
	global_store_short v[130:131], v112, off
	v_or_b32_e32 v112, 1, v163
	v_mul_f32_e32 v113, v113, v164
	v_mul_u32_u24_e32 v112, s9, v112
	v_cvt_pk_bf16_f32 v132, v113, s0
	v_lshlrev_b32_e32 v112, 1, v112
	v_mov_b32_e32 v113, v189
	v_lshl_add_u64 v[130:131], v[138:139], 0, v[112:113]
	global_store_short v[130:131], v132, off
	v_or_b32_e32 v130, 2, v163
	v_mul_u32_u24_e32 v130, s9, v130
	v_mul_f32_e32 v114, v114, v164
	v_lshlrev_b32_e32 v130, 1, v130
	v_mov_b32_e32 v131, v189
	v_cvt_pk_bf16_f32 v114, v114, s0
	v_lshl_add_u64 v[132:133], v[138:139], 0, v[130:131]
	global_store_short v[132:133], v114, off
	v_or_b32_e32 v114, 3, v163
	v_mul_f32_e32 v115, v115, v164
	v_mul_u32_u24_e32 v114, s9, v114
	v_cvt_pk_bf16_f32 v134, v115, s0
	v_lshlrev_b32_e32 v114, 1, v114
	v_mov_b32_e32 v115, v189
	v_lshl_add_u64 v[132:133], v[138:139], 0, v[114:115]
	global_store_short v[132:133], v134, off
	v_or_b32_e32 v132, 8, v163
	v_mul_u32_u24_e32 v132, s9, v132
	v_mul_f32_e32 v116, v116, v164
	v_lshlrev_b32_e32 v132, 1, v132
	v_mov_b32_e32 v133, v189
	v_cvt_pk_bf16_f32 v116, v116, s0
	v_lshl_add_u64 v[134:135], v[138:139], 0, v[132:133]
	global_store_short v[134:135], v116, off
	v_or_b32_e32 v116, 9, v163
	v_mul_f32_e32 v117, v117, v164
	v_mul_u32_u24_e32 v116, s9, v116
	v_cvt_pk_bf16_f32 v136, v117, s0
	v_lshlrev_b32_e32 v116, 1, v116
	v_mov_b32_e32 v117, v189
	v_lshl_add_u64 v[134:135], v[138:139], 0, v[116:117]
	global_store_short v[134:135], v136, off
	v_or_b32_e32 v134, 10, v163
	v_mul_u32_u24_e32 v134, s9, v134
	v_mul_f32_e32 v118, v118, v164
	v_lshlrev_b32_e32 v134, 1, v134
	v_mov_b32_e32 v135, v189
	v_cvt_pk_bf16_f32 v118, v118, s0
	v_lshl_add_u64 v[136:137], v[138:139], 0, v[134:135]
	global_store_short v[136:137], v118, off
	v_or_b32_e32 v118, 11, v163
	v_mul_f32_e32 v119, v119, v164
	v_mul_u32_u24_e32 v118, s9, v118
	v_cvt_pk_bf16_f32 v140, v119, s0
	v_lshlrev_b32_e32 v118, 1, v118
	v_mov_b32_e32 v119, v189
	v_lshl_add_u64 v[136:137], v[138:139], 0, v[118:119]
	global_store_short v[136:137], v140, off
	v_or_b32_e32 v136, 16, v163
	v_mul_u32_u24_e32 v136, s9, v136
; DI u16 f2bf(float a) { return (u16)(pack2(a, 0.f) & 0xffffu); }
; DI int crow(int reg, int g) { return (reg & 3) + 8 * (reg >> 2) + 4 * g; }
; template <bool TR>
; DI void gemm_in_tile(const P& p, int l, int id, char* smem) {
;     ...
; #pragma unroll
;       for (int rb = 0; rb < 2; ++rb) {
; #pragma unroll
;         for (int reg = 0; reg < 16; ++reg) {
;           const int cl = 32 * rb + crow(reg, g);
;           dst[(size_t)cl * cstride] = f2bf(acc[rb][cb][reg] * rs);
;         }
;       }
	v_mul_f32_e32 v120, v120, v164
	v_lshlrev_b32_e32 v136, 1, v136
	v_mov_b32_e32 v137, v189
	v_cvt_pk_bf16_f32 v120, v120, s0
	v_lshl_add_u64 v[140:141], v[138:139], 0, v[136:137]
	global_store_short v[140:141], v120, off
	v_or_b32_e32 v120, 17, v163
	v_mul_f32_e32 v121, v121, v164
	v_mul_u32_u24_e32 v120, s9, v120
	v_cvt_pk_bf16_f32 v142, v121, s0
	v_lshlrev_b32_e32 v120, 1, v120
	v_mov_b32_e32 v121, v189
	v_lshl_add_u64 v[140:141], v[138:139], 0, v[120:121]
	global_store_short v[140:141], v142, off
	v_or_b32_e32 v140, 18, v163
	v_mul_u32_u24_e32 v140, s9, v140
	v_mul_f32_e32 v122, v122, v164
	v_lshlrev_b32_e32 v140, 1, v140
	v_mov_b32_e32 v141, v189
	v_cvt_pk_bf16_f32 v122, v122, s0
	v_lshl_add_u64 v[142:143], v[138:139], 0, v[140:141]
	global_store_short v[142:143], v122, off
	v_or_b32_e32 v122, 19, v163
	v_mul_f32_e32 v123, v123, v164
	v_mul_u32_u24_e32 v122, s9, v122
	v_cvt_pk_bf16_f32 v144, v123, s0
	v_lshlrev_b32_e32 v122, 1, v122
	v_mov_b32_e32 v123, v189
	v_lshl_add_u64 v[142:143], v[138:139], 0, v[122:123]
	global_store_short v[142:143], v144, off
	v_or_b32_e32 v142, 24, v163
	v_mul_u32_u24_e32 v142, s9, v142
	v_mul_f32_e32 v124, v124, v164
	v_lshlrev_b32_e32 v142, 1, v142
	v_mov_b32_e32 v143, v189
	v_cvt_pk_bf16_f32 v124, v124, s0
	v_lshl_add_u64 v[144:145], v[138:139], 0, v[142:143]
	global_store_short v[144:145], v124, off
	v_or_b32_e32 v124, 25, v163
	v_mul_f32_e32 v125, v125, v164
	v_mul_u32_u24_e32 v124, s9, v124
	v_cvt_pk_bf16_f32 v146, v125, s0
	v_lshlrev_b32_e32 v124, 1, v124
	v_mov_b32_e32 v125, v189
	v_lshl_add_u64 v[144:145], v[138:139], 0, v[124:125]
	global_store_short v[144:145], v146, off
	v_or_b32_e32 v144, 26, v163
	v_mul_u32_u24_e32 v144, s9, v144
	v_mul_f32_e32 v126, v126, v164
	v_lshlrev_b32_e32 v144, 1, v144
	v_mov_b32_e32 v145, v189
	v_cvt_pk_bf16_f32 v126, v126, s0
	v_lshl_add_u64 v[146:147], v[138:139], 0, v[144:145]
	global_store_short v[146:147], v126, off
	v_or_b32_e32 v126, 27, v163
	v_mul_f32_e32 v127, v127, v164
	v_mul_u32_u24_e32 v126, s9, v126
	v_cvt_pk_bf16_f32 v148, v127, s0
	v_lshlrev_b32_e32 v126, 1, v126
	v_mov_b32_e32 v127, v189
	v_lshl_add_u64 v[146:147], v[138:139], 0, v[126:127]
	global_store_short v[146:147], v148, off
	v_or_b32_e32 v146, 32, v163
	v_mul_u32_u24_e32 v146, s9, v146
	v_mul_f32_e32 v96, v96, v164
	v_lshlrev_b32_e32 v146, 1, v146
	v_mov_b32_e32 v147, v189
	v_cvt_pk_bf16_f32 v96, v96, s0
	v_lshl_add_u64 v[148:149], v[138:139], 0, v[146:147]
	global_store_short v[148:149], v96, off
	v_or_b32_e32 v96, 33, v163
	v_mul_f32_e32 v97, v97, v164
	v_mul_u32_u24_e32 v96, s9, v96
	v_cvt_pk_bf16_f32 v150, v97, s0
	v_lshlrev_b32_e32 v96, 1, v96
	v_mov_b32_e32 v97, v189
	v_lshl_add_u64 v[148:149], v[138:139], 0, v[96:97]
	global_store_short v[148:149], v150, off
	v_or_b32_e32 v148, 34, v163
	v_mul_u32_u24_e32 v148, s9, v148
	v_mul_f32_e32 v98, v98, v164
	v_lshlrev_b32_e32 v148, 1, v148
	v_mov_b32_e32 v149, v189
	v_cvt_pk_bf16_f32 v98, v98, s0
	v_lshl_add_u64 v[150:151], v[138:139], 0, v[148:149]
	global_store_short v[150:151], v98, off
	v_or_b32_e32 v98, 35, v163
	v_mul_f32_e32 v99, v99, v164
	v_mul_u32_u24_e32 v98, s9, v98
	v_cvt_pk_bf16_f32 v152, v99, s0
	v_lshlrev_b32_e32 v98, 1, v98
	v_mov_b32_e32 v99, v189
	v_lshl_add_u64 v[150:151], v[138:139], 0, v[98:99]
	global_store_short v[150:151], v152, off
	v_or_b32_e32 v150, 40, v163
	v_mul_u32_u24_e32 v150, s9, v150
	v_mul_f32_e32 v100, v100, v164
	v_lshlrev_b32_e32 v150, 1, v150
	v_mov_b32_e32 v151, v189
	v_cvt_pk_bf16_f32 v100, v100, s0
	v_lshl_add_u64 v[152:153], v[138:139], 0, v[150:151]
	global_store_short v[152:153], v100, off
	v_or_b32_e32 v100, 41, v163
	v_mul_f32_e32 v101, v101, v164
	v_mul_u32_u24_e32 v100, s9, v100
	v_cvt_pk_bf16_f32 v154, v101, s0
	v_lshlrev_b32_e32 v100, 1, v100
	v_mov_b32_e32 v101, v189
	v_lshl_add_u64 v[152:153], v[138:139], 0, v[100:101]
	global_store_short v[152:153], v154, off
	v_or_b32_e32 v152, 42, v163
	v_mul_u32_u24_e32 v152, s9, v152
	v_mul_f32_e32 v102, v102, v164
	v_lshlrev_b32_e32 v152, 1, v152
	v_mov_b32_e32 v153, v189
	v_cvt_pk_bf16_f32 v102, v102, s0
	v_lshl_add_u64 v[154:155], v[138:139], 0, v[152:153]
	global_store_short v[154:155], v102, off
	v_or_b32_e32 v102, 43, v163
	v_mul_f32_e32 v103, v103, v164
	v_mul_u32_u24_e32 v102, s9, v102
	v_cvt_pk_bf16_f32 v156, v103, s0
	v_lshlrev_b32_e32 v102, 1, v102
	v_mov_b32_e32 v103, v189
	v_lshl_add_u64 v[154:155], v[138:139], 0, v[102:103]
	global_store_short v[154:155], v156, off
	v_or_b32_e32 v154, 48, v163
	v_mul_u32_u24_e32 v154, s9, v154
	v_mul_f32_e32 v104, v104, v164
	v_lshlrev_b32_e32 v154, 1, v154
	v_mov_b32_e32 v155, v189
	v_cvt_pk_bf16_f32 v104, v104, s0
	v_lshl_add_u64 v[156:157], v[138:139], 0, v[154:155]
	global_store_short v[156:157], v104, off
	v_or_b32_e32 v104, 49, v163
	v_mul_f32_e32 v105, v105, v164
	v_mul_u32_u24_e32 v104, s9, v104
	v_cvt_pk_bf16_f32 v158, v105, s0
	v_lshlrev_b32_e32 v104, 1, v104
	v_mov_b32_e32 v105, v189
	v_lshl_add_u64 v[156:157], v[138:139], 0, v[104:105]
	global_store_short v[156:157], v158, off
	v_or_b32_e32 v156, 50, v163
	v_mul_u32_u24_e32 v156, s9, v156
	v_mul_f32_e32 v106, v106, v164
	v_lshlrev_b32_e32 v156, 1, v156
	v_mov_b32_e32 v157, v189
	v_cvt_pk_bf16_f32 v106, v106, s0
	v_lshl_add_u64 v[158:159], v[138:139], 0, v[156:157]
	global_store_short v[158:159], v106, off
	v_or_b32_e32 v106, 51, v163
	v_mul_f32_e32 v107, v107, v164
	v_mul_u32_u24_e32 v106, s9, v106
	v_cvt_pk_bf16_f32 v160, v107, s0
	v_lshlrev_b32_e32 v106, 1, v106
	v_mov_b32_e32 v107, v189
	v_lshl_add_u64 v[158:159], v[138:139], 0, v[106:107]
	global_store_short v[158:159], v160, off
	v_or_b32_e32 v158, 56, v163
	v_mul_u32_u24_e32 v158, s9, v158
; DI u16 f2bf(float a) { return (u16)(pack2(a, 0.f) & 0xffffu); }
; DI int crow(int reg, int g) { return (reg & 3) + 8 * (reg >> 2) + 4 * g; }
; template <bool TR>
; DI void gemm_in_tile(const P& p, int l, int id, char* smem) {
;     ...
;     for (int cb = 0; cb < 4; ++cb) {
;       asm volatile("" ::: "memory");
;       const int tl = 128 * wc + 32 * cb + li;
;       const int tok = m0 + tl;
;       const float rs = rs_s[tl];
;       u16* dst = hy ? (p.hyT + (size_t)(n0 + 64 * wr) * HYP + tok)
;                     : (p.VT + (size_t)((tok >> 13) * 512 + (n0 - 3072) + 64 * wr) * VTP + (tok & 8191));
;       const size_t cstride = hy ? (size_t)HYP : (size_t)VTP;
; #pragma unroll
;       for (int rb = 0; rb < 2; ++rb) {
; #pragma unroll
;         for (int reg = 0; reg < 16; ++reg) {
;           const int cl = 32 * rb + crow(reg, g);
;           dst[(size_t)cl * cstride] = f2bf(acc[rb][cb][reg] * rs);
;         }
;       }
	v_mul_f32_e32 v108, v108, v164
	v_lshlrev_b32_e32 v158, 1, v158
	v_mov_b32_e32 v159, v189
	v_cvt_pk_bf16_f32 v108, v108, s0
	v_lshl_add_u64 v[160:161], v[138:139], 0, v[158:159]
	global_store_short v[160:161], v108, off
	v_or_b32_e32 v108, 57, v163
	v_mul_f32_e32 v109, v109, v164
	v_mul_u32_u24_e32 v108, s9, v108
	v_cvt_pk_bf16_f32 v165, v109, s0
	v_lshlrev_b32_e32 v108, 1, v108
	v_mov_b32_e32 v109, v189
	v_lshl_add_u64 v[160:161], v[138:139], 0, v[108:109]
	global_store_short v[160:161], v165, off
	v_or_b32_e32 v160, 58, v163
	v_mul_u32_u24_e32 v160, s9, v160
	v_mul_f32_e32 v110, v110, v164
	v_lshlrev_b32_e32 v160, 1, v160
	v_mov_b32_e32 v161, v189
	v_cvt_pk_bf16_f32 v110, v110, s0
	v_lshl_add_u64 v[166:167], v[138:139], 0, v[160:161]
	global_store_short v[166:167], v110, off
	v_or_b32_e32 v110, 59, v163
	v_mul_f32_e32 v111, v111, v164
	v_mul_u32_u24_e32 v110, s9, v110
	v_cvt_pk_bf16_f32 v163, v111, s0
	v_lshlrev_b32_e32 v110, 1, v110
	v_mov_b32_e32 v111, v189
	v_lshl_add_u64 v[138:139], v[138:139], 0, v[110:111]
	global_store_short v[138:139], v163, off
	v_or_b32_e32 v138, 32, v176
	v_lshl_add_u32 v163, v138, 2, s8
	ds_read_b32 v163, v163
	s_movk_i32 s9, 0x1fbf
	v_or_b32_e32 v139, s56, v138
	v_bitop3_b32 v138, v138, s9, v162 bitop3:0xc8
	v_cndmask_b32_e64 v138, v138, v139, s[6:7]
	v_lshlrev_b32_e32 v138, 1, v138
	v_mov_b32_e32 v139, v189
	v_lshl_add_u64 v[138:139], v[128:129], 0, v[138:139]
	s_waitcnt lgkmcnt(0)
	v_mul_f32_e32 v80, v80, v163
	v_cvt_pk_bf16_f32 v80, v80, s0
	v_lshl_add_u64 v[164:165], v[138:139], 0, v[188:189]
	global_store_short v[164:165], v80, off
	v_mul_f32_e32 v80, v81, v163
	v_cvt_pk_bf16_f32 v164, v80, s0
	v_lshl_add_u64 v[80:81], v[138:139], 0, v[112:113]
	global_store_short v[80:81], v164, off
	v_mul_f32_e32 v80, v82, v163
	v_cvt_pk_bf16_f32 v82, v80, s0
	v_lshl_add_u64 v[80:81], v[138:139], 0, v[130:131]
	global_store_short v[80:81], v82, off
	v_mul_f32_e32 v80, v83, v163
	v_cvt_pk_bf16_f32 v82, v80, s0
	v_lshl_add_u64 v[80:81], v[138:139], 0, v[114:115]
	global_store_short v[80:81], v82, off
	v_mul_f32_e32 v80, v84, v163
	v_cvt_pk_bf16_f32 v82, v80, s0
	v_lshl_add_u64 v[80:81], v[138:139], 0, v[132:133]
	global_store_short v[80:81], v82, off
	v_mul_f32_e32 v80, v85, v163
	v_cvt_pk_bf16_f32 v82, v80, s0
	v_lshl_add_u64 v[80:81], v[138:139], 0, v[116:117]
	global_store_short v[80:81], v82, off
	v_mul_f32_e32 v80, v86, v163
	v_cvt_pk_bf16_f32 v82, v80, s0
	v_lshl_add_u64 v[80:81], v[138:139], 0, v[134:135]
	global_store_short v[80:81], v82, off
	v_mul_f32_e32 v80, v87, v163
	v_cvt_pk_bf16_f32 v82, v80, s0
	v_lshl_add_u64 v[80:81], v[138:139], 0, v[118:119]
	global_store_short v[80:81], v82, off
	v_mul_f32_e32 v80, v88, v163
	v_cvt_pk_bf16_f32 v82, v80, s0
	v_lshl_add_u64 v[80:81], v[138:139], 0, v[136:137]
	global_store_short v[80:81], v82, off
	v_mul_f32_e32 v80, v89, v163
	v_cvt_pk_bf16_f32 v82, v80, s0
	v_lshl_add_u64 v[80:81], v[138:139], 0, v[120:121]
	global_store_short v[80:81], v82, off
	v_mul_f32_e32 v80, v90, v163
	v_cvt_pk_bf16_f32 v82, v80, s0
	v_lshl_add_u64 v[80:81], v[138:139], 0, v[140:141]
	global_store_short v[80:81], v82, off
	v_mul_f32_e32 v80, v91, v163
	v_cvt_pk_bf16_f32 v82, v80, s0
	v_lshl_add_u64 v[80:81], v[138:139], 0, v[122:123]
	global_store_short v[80:81], v82, off
	v_mul_f32_e32 v80, v92, v163
	v_cvt_pk_bf16_f32 v82, v80, s0
	v_lshl_add_u64 v[80:81], v[138:139], 0, v[142:143]
	global_store_short v[80:81], v82, off
	v_mul_f32_e32 v80, v93, v163
	v_cvt_pk_bf16_f32 v82, v80, s0
	v_lshl_add_u64 v[80:81], v[138:139], 0, v[124:125]
	global_store_short v[80:81], v82, off
	v_mul_f32_e32 v80, v94, v163
	v_cvt_pk_bf16_f32 v82, v80, s0
	v_lshl_add_u64 v[80:81], v[138:139], 0, v[144:145]
	global_store_short v[80:81], v82, off
	v_mul_f32_e32 v80, v95, v163
	v_cvt_pk_bf16_f32 v82, v80, s0
	v_lshl_add_u64 v[80:81], v[138:139], 0, v[126:127]
	v_mul_f32_e32 v64, v64, v163
	global_store_short v[80:81], v82, off
	v_cvt_pk_bf16_f32 v64, v64, s0
	v_lshl_add_u64 v[80:81], v[138:139], 0, v[146:147]
	global_store_short v[80:81], v64, off
	v_mul_f32_e32 v64, v65, v163
	v_cvt_pk_bf16_f32 v80, v64, s0
	v_lshl_add_u64 v[64:65], v[138:139], 0, v[96:97]
	global_store_short v[64:65], v80, off
	v_mul_f32_e32 v64, v66, v163
	v_cvt_pk_bf16_f32 v66, v64, s0
	v_lshl_add_u64 v[64:65], v[138:139], 0, v[148:149]
	global_store_short v[64:65], v66, off
	v_mul_f32_e32 v64, v67, v163
	v_cvt_pk_bf16_f32 v66, v64, s0
	v_lshl_add_u64 v[64:65], v[138:139], 0, v[98:99]
	global_store_short v[64:65], v66, off
	v_mul_f32_e32 v64, v68, v163
	v_cvt_pk_bf16_f32 v66, v64, s0
	v_lshl_add_u64 v[64:65], v[138:139], 0, v[150:151]
	global_store_short v[64:65], v66, off
	v_mul_f32_e32 v64, v69, v163
	v_cvt_pk_bf16_f32 v66, v64, s0
	v_lshl_add_u64 v[64:65], v[138:139], 0, v[100:101]
	global_store_short v[64:65], v66, off
	v_mul_f32_e32 v64, v70, v163
	v_cvt_pk_bf16_f32 v66, v64, s0
	v_lshl_add_u64 v[64:65], v[138:139], 0, v[152:153]
	global_store_short v[64:65], v66, off
	v_mul_f32_e32 v64, v71, v163
	v_cvt_pk_bf16_f32 v66, v64, s0
	v_lshl_add_u64 v[64:65], v[138:139], 0, v[102:103]
	global_store_short v[64:65], v66, off
	v_mul_f32_e32 v64, v72, v163
	v_cvt_pk_bf16_f32 v66, v64, s0
	v_lshl_add_u64 v[64:65], v[138:139], 0, v[154:155]
	global_store_short v[64:65], v66, off
	v_mul_f32_e32 v64, v73, v163
	v_cvt_pk_bf16_f32 v66, v64, s0
	v_lshl_add_u64 v[64:65], v[138:139], 0, v[104:105]
	global_store_short v[64:65], v66, off
	v_mul_f32_e32 v64, v74, v163
	v_cvt_pk_bf16_f32 v66, v64, s0
	v_lshl_add_u64 v[64:65], v[138:139], 0, v[156:157]
	global_store_short v[64:65], v66, off
	v_mul_f32_e32 v64, v75, v163
	v_cvt_pk_bf16_f32 v66, v64, s0
	v_lshl_add_u64 v[64:65], v[138:139], 0, v[106:107]
	global_store_short v[64:65], v66, off
	v_mul_f32_e32 v64, v76, v163
	v_cvt_pk_bf16_f32 v66, v64, s0
	v_lshl_add_u64 v[64:65], v[138:139], 0, v[158:159]
	global_store_short v[64:65], v66, off
	v_mul_f32_e32 v64, v77, v163
	v_cvt_pk_bf16_f32 v66, v64, s0
	v_lshl_add_u64 v[64:65], v[138:139], 0, v[108:109]
	global_store_short v[64:65], v66, off
	v_mul_f32_e32 v64, v78, v163
	v_cvt_pk_bf16_f32 v66, v64, s0
	v_lshl_add_u64 v[64:65], v[138:139], 0, v[160:161]
	global_store_short v[64:65], v66, off
	v_mul_f32_e32 v64, v79, v163
	v_cvt_pk_bf16_f32 v66, v64, s0
	v_lshl_add_u64 v[64:65], v[138:139], 0, v[110:111]
	global_store_short v[64:65], v66, off
	v_or_b32_e32 v64, 64, v176
	v_lshl_add_u32 v66, v64, 2, s8
	ds_read_b32 v68, v66
	s_movk_i32 s9, 0x1fdf
	v_or_b32_e32 v65, s56, v64
	v_bitop3_b32 v64, v64, s9, v162 bitop3:0xc8
	v_cndmask_b32_e64 v64, v64, v65, s[6:7]
	v_lshlrev_b32_e32 v64, 1, v64
	v_mov_b32_e32 v65, v189
	v_lshl_add_u64 v[64:65], v[128:129], 0, v[64:65]
	s_waitcnt lgkmcnt(0)
; DI u16 f2bf(float a) { return (u16)(pack2(a, 0.f) & 0xffffu); }
; DI int crow(int reg, int g) { return (reg & 3) + 8 * (reg >> 2) + 4 * g; }
; template <bool TR>
; DI void gemm_in_tile(const P& p, int l, int id, char* smem) {
;     ...
;     for (int cb = 0; cb < 4; ++cb) {
;       asm volatile("" ::: "memory");
;       const int tl = 128 * wc + 32 * cb + li;
;       const int tok = m0 + tl;
;       const float rs = rs_s[tl];
;       u16* dst = hy ? (p.hyT + (size_t)(n0 + 64 * wr) * HYP + tok)
;                     : (p.VT + (size_t)((tok >> 13) * 512 + (n0 - 3072) + 64 * wr) * VTP + (tok & 8191));
;       const size_t cstride = hy ? (size_t)HYP : (size_t)VTP;
; #pragma unroll
;       for (int rb = 0; rb < 2; ++rb) {
; #pragma unroll
;         for (int reg = 0; reg < 16; ++reg) {
;           const int cl = 32 * rb + crow(reg, g);
;           dst[(size_t)cl * cstride] = f2bf(acc[rb][cb][reg] * rs);
;         }
;       }
	v_mul_f32_e32 v48, v48, v68
	v_cvt_pk_bf16_f32 v48, v48, s0
	v_lshl_add_u64 v[66:67], v[64:65], 0, v[188:189]
	global_store_short v[66:67], v48, off
	v_mul_f32_e32 v48, v49, v68
	v_cvt_pk_bf16_f32 v66, v48, s0
	v_lshl_add_u64 v[48:49], v[64:65], 0, v[112:113]
	global_store_short v[48:49], v66, off
	v_mul_f32_e32 v48, v50, v68
	v_cvt_pk_bf16_f32 v50, v48, s0
	v_lshl_add_u64 v[48:49], v[64:65], 0, v[130:131]
	global_store_short v[48:49], v50, off
	v_mul_f32_e32 v48, v51, v68
	v_cvt_pk_bf16_f32 v50, v48, s0
	v_lshl_add_u64 v[48:49], v[64:65], 0, v[114:115]
	global_store_short v[48:49], v50, off
	v_mul_f32_e32 v48, v52, v68
	v_cvt_pk_bf16_f32 v50, v48, s0
	v_lshl_add_u64 v[48:49], v[64:65], 0, v[132:133]
	global_store_short v[48:49], v50, off
	v_mul_f32_e32 v48, v53, v68
	v_cvt_pk_bf16_f32 v50, v48, s0
	v_lshl_add_u64 v[48:49], v[64:65], 0, v[116:117]
	global_store_short v[48:49], v50, off
	v_mul_f32_e32 v48, v54, v68
	v_cvt_pk_bf16_f32 v50, v48, s0
	v_lshl_add_u64 v[48:49], v[64:65], 0, v[134:135]
	global_store_short v[48:49], v50, off
	v_mul_f32_e32 v48, v55, v68
	v_cvt_pk_bf16_f32 v50, v48, s0
	v_lshl_add_u64 v[48:49], v[64:65], 0, v[118:119]
	global_store_short v[48:49], v50, off
	v_mul_f32_e32 v48, v56, v68
	v_cvt_pk_bf16_f32 v50, v48, s0
	v_lshl_add_u64 v[48:49], v[64:65], 0, v[136:137]
	global_store_short v[48:49], v50, off
	v_mul_f32_e32 v48, v57, v68
	v_cvt_pk_bf16_f32 v50, v48, s0
	v_lshl_add_u64 v[48:49], v[64:65], 0, v[120:121]
	global_store_short v[48:49], v50, off
	v_mul_f32_e32 v48, v58, v68
	v_cvt_pk_bf16_f32 v50, v48, s0
	v_lshl_add_u64 v[48:49], v[64:65], 0, v[140:141]
	global_store_short v[48:49], v50, off
	v_mul_f32_e32 v48, v59, v68
	v_cvt_pk_bf16_f32 v50, v48, s0
	v_lshl_add_u64 v[48:49], v[64:65], 0, v[122:123]
	global_store_short v[48:49], v50, off
	v_mul_f32_e32 v48, v60, v68
	v_cvt_pk_bf16_f32 v50, v48, s0
	v_lshl_add_u64 v[48:49], v[64:65], 0, v[142:143]
	global_store_short v[48:49], v50, off
	v_mul_f32_e32 v48, v61, v68
	v_cvt_pk_bf16_f32 v50, v48, s0
	v_lshl_add_u64 v[48:49], v[64:65], 0, v[124:125]
	global_store_short v[48:49], v50, off
	v_mul_f32_e32 v48, v62, v68
	v_cvt_pk_bf16_f32 v50, v48, s0
	v_lshl_add_u64 v[48:49], v[64:65], 0, v[144:145]
	global_store_short v[48:49], v50, off
	v_mul_f32_e32 v48, v63, v68
	v_cvt_pk_bf16_f32 v50, v48, s0
	v_lshl_add_u64 v[48:49], v[64:65], 0, v[126:127]
	v_mul_f32_e32 v32, v32, v68
	global_store_short v[48:49], v50, off
	v_cvt_pk_bf16_f32 v32, v32, s0
	v_lshl_add_u64 v[48:49], v[64:65], 0, v[146:147]
	global_store_short v[48:49], v32, off
	v_mul_f32_e32 v32, v33, v68
	v_cvt_pk_bf16_f32 v48, v32, s0
	v_lshl_add_u64 v[32:33], v[64:65], 0, v[96:97]
	global_store_short v[32:33], v48, off
	v_mul_f32_e32 v32, v34, v68
	v_cvt_pk_bf16_f32 v34, v32, s0
	v_lshl_add_u64 v[32:33], v[64:65], 0, v[148:149]
	global_store_short v[32:33], v34, off
	v_mul_f32_e32 v32, v35, v68
	v_cvt_pk_bf16_f32 v34, v32, s0
	v_lshl_add_u64 v[32:33], v[64:65], 0, v[98:99]
	global_store_short v[32:33], v34, off
	v_mul_f32_e32 v32, v36, v68
	v_cvt_pk_bf16_f32 v34, v32, s0
	v_lshl_add_u64 v[32:33], v[64:65], 0, v[150:151]
	global_store_short v[32:33], v34, off
	v_mul_f32_e32 v32, v37, v68
	v_cvt_pk_bf16_f32 v34, v32, s0
	v_lshl_add_u64 v[32:33], v[64:65], 0, v[100:101]
	global_store_short v[32:33], v34, off
	v_mul_f32_e32 v32, v38, v68
	v_cvt_pk_bf16_f32 v34, v32, s0
	v_lshl_add_u64 v[32:33], v[64:65], 0, v[152:153]
	global_store_short v[32:33], v34, off
	v_mul_f32_e32 v32, v39, v68
	v_cvt_pk_bf16_f32 v34, v32, s0
	v_lshl_add_u64 v[32:33], v[64:65], 0, v[102:103]
	global_store_short v[32:33], v34, off
	v_mul_f32_e32 v32, v40, v68
	v_cvt_pk_bf16_f32 v34, v32, s0
	v_lshl_add_u64 v[32:33], v[64:65], 0, v[154:155]
	global_store_short v[32:33], v34, off
	v_mul_f32_e32 v32, v41, v68
	v_cvt_pk_bf16_f32 v34, v32, s0
	v_lshl_add_u64 v[32:33], v[64:65], 0, v[104:105]
	global_store_short v[32:33], v34, off
	v_mul_f32_e32 v32, v42, v68
	v_cvt_pk_bf16_f32 v34, v32, s0
	v_lshl_add_u64 v[32:33], v[64:65], 0, v[156:157]
	global_store_short v[32:33], v34, off
	v_mul_f32_e32 v32, v43, v68
	v_cvt_pk_bf16_f32 v34, v32, s0
	v_lshl_add_u64 v[32:33], v[64:65], 0, v[106:107]
	global_store_short v[32:33], v34, off
	v_mul_f32_e32 v32, v44, v68
	v_cvt_pk_bf16_f32 v34, v32, s0
	v_lshl_add_u64 v[32:33], v[64:65], 0, v[158:159]
	global_store_short v[32:33], v34, off
	v_mul_f32_e32 v32, v45, v68
	v_cvt_pk_bf16_f32 v34, v32, s0
	v_lshl_add_u64 v[32:33], v[64:65], 0, v[108:109]
	global_store_short v[32:33], v34, off
	v_mul_f32_e32 v32, v46, v68
	v_cvt_pk_bf16_f32 v34, v32, s0
	v_lshl_add_u64 v[32:33], v[64:65], 0, v[160:161]
	global_store_short v[32:33], v34, off
	v_mul_f32_e32 v32, v47, v68
	v_cvt_pk_bf16_f32 v34, v32, s0
	v_lshl_add_u64 v[32:33], v[64:65], 0, v[110:111]
	global_store_short v[32:33], v34, off
	v_or_b32_e32 v32, 0x60, v176
	v_lshl_add_u32 v34, v32, 2, s8
	ds_read_b32 v36, v34
	s_movk_i32 s8, 0x1fff
	v_or_b32_e32 v33, s56, v32
	v_bitop3_b32 v32, v32, s8, v162 bitop3:0xc8
	v_cndmask_b32_e64 v32, v32, v33, s[6:7]
	v_lshlrev_b32_e32 v32, 1, v32
	v_mov_b32_e32 v33, v189
	v_lshl_add_u64 v[32:33], v[128:129], 0, v[32:33]
	s_waitcnt lgkmcnt(0)
; DI u16 f2bf(float a) { return (u16)(pack2(a, 0.f) & 0xffffu); }
; DI int crow(int reg, int g) { return (reg & 3) + 8 * (reg >> 2) + 4 * g; }
; template <bool TR>
; DI void gemm_in_tile(const P& p, int l, int id, char* smem) {
;     ...
;     for (int cb = 0; cb < 4; ++cb) {
;       asm volatile("" ::: "memory");
;       const int tl = 128 * wc + 32 * cb + li;
;       const int tok = m0 + tl;
;       const float rs = rs_s[tl];
;       u16* dst = hy ? (p.hyT + (size_t)(n0 + 64 * wr) * HYP + tok)
;                     : (p.VT + (size_t)((tok >> 13) * 512 + (n0 - 3072) + 64 * wr) * VTP + (tok & 8191));
;       const size_t cstride = hy ? (size_t)HYP : (size_t)VTP;
; #pragma unroll
;       for (int rb = 0; rb < 2; ++rb) {
; #pragma unroll
;         for (int reg = 0; reg < 16; ++reg) {
;           const int cl = 32 * rb + crow(reg, g);
;           dst[(size_t)cl * cstride] = f2bf(acc[rb][cb][reg] * rs);
;         }
;       }
	v_mul_f32_e32 v16, v16, v36
	v_cvt_pk_bf16_f32 v16, v16, s0
	v_lshl_add_u64 v[34:35], v[32:33], 0, v[188:189]
	global_store_short v[34:35], v16, off
	v_mul_f32_e32 v16, v17, v36
	v_cvt_pk_bf16_f32 v34, v16, s0
	v_lshl_add_u64 v[16:17], v[32:33], 0, v[112:113]
	global_store_short v[16:17], v34, off
	v_mul_f32_e32 v16, v18, v36
	v_cvt_pk_bf16_f32 v18, v16, s0
	v_lshl_add_u64 v[16:17], v[32:33], 0, v[130:131]
	global_store_short v[16:17], v18, off
	v_mul_f32_e32 v16, v19, v36
	v_cvt_pk_bf16_f32 v18, v16, s0
	v_lshl_add_u64 v[16:17], v[32:33], 0, v[114:115]
	global_store_short v[16:17], v18, off
	v_mul_f32_e32 v16, v20, v36
	v_cvt_pk_bf16_f32 v18, v16, s0
	v_lshl_add_u64 v[16:17], v[32:33], 0, v[132:133]
	global_store_short v[16:17], v18, off
	v_mul_f32_e32 v16, v21, v36
	v_cvt_pk_bf16_f32 v18, v16, s0
	v_lshl_add_u64 v[16:17], v[32:33], 0, v[116:117]
	global_store_short v[16:17], v18, off
	v_mul_f32_e32 v16, v22, v36
	v_cvt_pk_bf16_f32 v18, v16, s0
	v_lshl_add_u64 v[16:17], v[32:33], 0, v[134:135]
	global_store_short v[16:17], v18, off
	v_mul_f32_e32 v16, v23, v36
	v_cvt_pk_bf16_f32 v18, v16, s0
	v_lshl_add_u64 v[16:17], v[32:33], 0, v[118:119]
	global_store_short v[16:17], v18, off
	v_mul_f32_e32 v16, v24, v36
	v_cvt_pk_bf16_f32 v18, v16, s0
	v_lshl_add_u64 v[16:17], v[32:33], 0, v[136:137]
	global_store_short v[16:17], v18, off
	v_mul_f32_e32 v16, v25, v36
	v_cvt_pk_bf16_f32 v18, v16, s0
	v_lshl_add_u64 v[16:17], v[32:33], 0, v[120:121]
	global_store_short v[16:17], v18, off
	v_mul_f32_e32 v16, v26, v36
	v_cvt_pk_bf16_f32 v18, v16, s0
	v_lshl_add_u64 v[16:17], v[32:33], 0, v[140:141]
	global_store_short v[16:17], v18, off
	v_mul_f32_e32 v16, v27, v36
	v_cvt_pk_bf16_f32 v18, v16, s0
	v_lshl_add_u64 v[16:17], v[32:33], 0, v[122:123]
	global_store_short v[16:17], v18, off
	v_mul_f32_e32 v16, v28, v36
	v_cvt_pk_bf16_f32 v18, v16, s0
	v_lshl_add_u64 v[16:17], v[32:33], 0, v[142:143]
	global_store_short v[16:17], v18, off
	v_mul_f32_e32 v16, v29, v36
	v_cvt_pk_bf16_f32 v18, v16, s0
	v_lshl_add_u64 v[16:17], v[32:33], 0, v[124:125]
	global_store_short v[16:17], v18, off
	v_mul_f32_e32 v16, v30, v36
	v_cvt_pk_bf16_f32 v18, v16, s0
	v_lshl_add_u64 v[16:17], v[32:33], 0, v[144:145]
	global_store_short v[16:17], v18, off
	v_mul_f32_e32 v16, v31, v36
	v_cvt_pk_bf16_f32 v18, v16, s0
	v_lshl_add_u64 v[16:17], v[32:33], 0, v[126:127]
	v_mul_f32_e32 v0, v0, v36
	global_store_short v[16:17], v18, off
	v_cvt_pk_bf16_f32 v0, v0, s0
	v_lshl_add_u64 v[16:17], v[32:33], 0, v[146:147]
	global_store_short v[16:17], v0, off
	v_mul_f32_e32 v0, v1, v36
	v_cvt_pk_bf16_f32 v16, v0, s0
	v_lshl_add_u64 v[0:1], v[32:33], 0, v[96:97]
	global_store_short v[0:1], v16, off
	v_mul_f32_e32 v0, v2, v36
	v_cvt_pk_bf16_f32 v2, v0, s0
	v_lshl_add_u64 v[0:1], v[32:33], 0, v[148:149]
	global_store_short v[0:1], v2, off
	v_mul_f32_e32 v0, v3, v36
	v_cvt_pk_bf16_f32 v2, v0, s0
	v_lshl_add_u64 v[0:1], v[32:33], 0, v[98:99]
	global_store_short v[0:1], v2, off
	v_mul_f32_e32 v0, v4, v36
	v_cvt_pk_bf16_f32 v2, v0, s0
	v_lshl_add_u64 v[0:1], v[32:33], 0, v[150:151]
	global_store_short v[0:1], v2, off
	v_mul_f32_e32 v0, v5, v36
	v_cvt_pk_bf16_f32 v2, v0, s0
	v_lshl_add_u64 v[0:1], v[32:33], 0, v[100:101]
	global_store_short v[0:1], v2, off
	v_mul_f32_e32 v0, v6, v36
	v_cvt_pk_bf16_f32 v2, v0, s0
	v_lshl_add_u64 v[0:1], v[32:33], 0, v[152:153]
	global_store_short v[0:1], v2, off
	v_mul_f32_e32 v0, v7, v36
	v_cvt_pk_bf16_f32 v2, v0, s0
	v_lshl_add_u64 v[0:1], v[32:33], 0, v[102:103]
	global_store_short v[0:1], v2, off
	v_mul_f32_e32 v0, v8, v36
	v_cvt_pk_bf16_f32 v2, v0, s0
	v_lshl_add_u64 v[0:1], v[32:33], 0, v[154:155]
	global_store_short v[0:1], v2, off
	v_mul_f32_e32 v0, v9, v36
	v_cvt_pk_bf16_f32 v2, v0, s0
	v_lshl_add_u64 v[0:1], v[32:33], 0, v[104:105]
	global_store_short v[0:1], v2, off
	v_mul_f32_e32 v0, v10, v36
	v_cvt_pk_bf16_f32 v2, v0, s0
	v_lshl_add_u64 v[0:1], v[32:33], 0, v[156:157]
	global_store_short v[0:1], v2, off
	v_mul_f32_e32 v0, v11, v36
	v_cvt_pk_bf16_f32 v2, v0, s0
	v_lshl_add_u64 v[0:1], v[32:33], 0, v[106:107]
	global_store_short v[0:1], v2, off
	v_mul_f32_e32 v0, v12, v36
	v_cvt_pk_bf16_f32 v2, v0, s0
	v_lshl_add_u64 v[0:1], v[32:33], 0, v[158:159]
	global_store_short v[0:1], v2, off
	v_mul_f32_e32 v0, v13, v36
	v_cvt_pk_bf16_f32 v2, v0, s0
	v_lshl_add_u64 v[0:1], v[32:33], 0, v[108:109]
	global_store_short v[0:1], v2, off
	v_mul_f32_e32 v0, v14, v36
	v_cvt_pk_bf16_f32 v2, v0, s0
	v_lshl_add_u64 v[0:1], v[32:33], 0, v[160:161]
	global_store_short v[0:1], v2, off
	v_mul_f32_e32 v0, v15, v36
	v_cvt_pk_bf16_f32 v2, v0, s0
	v_lshl_add_u64 v[0:1], v[32:33], 0, v[110:111]
	global_store_short v[0:1], v2, off
	s_branch .LBB0_102
